# GEMM compute blocks on v_mfma_f32_16x16x32_bf16 (same bf16 operands/f32 accumulate, 128x64 per wave), accumulators restored to the 32x32 layout by permlane16/32 swaps before each epilogue; ds_read_b12
# baseline (speedup 1.0000x reference)
.LBB0_20:
	s_waitcnt lgkmcnt(0)
	s_barrier
	s_setprio 2
	v_bfe_u32 v221, v222, 5, 1
	v_bfe_u32 v248, v222, 4, 1
	v_lshl_add_u32 v211, v221, 4, v178
	v_lshl_add_u32 v215, v221, 4, v179
	v_mul_u32_u24_e32 v221, 0x8f0, v248
	v_mul_u32_u24_e32 v248, 0x8f8, v248
	v_sub_u32_e32 v213, v211, v248
	v_sub_u32_e32 v220, v215, v248
	v_sub_u32_e32 v211, v211, v221
	v_sub_u32_e32 v215, v215, v221
	ds_read_b128 v[190:193], v215 offset:36864
	ds_read_b128 v[194:197], v211
	ds_read_b128 v[198:201], v215 offset:39168
	ds_read_b128 v[202:205], v215 offset:41472
	ds_read_b128 v[206:209], v215 offset:43776
	ds_read_b128 v[216:219], v211 offset:2304
	ds_read_b128 v[236:239], v211 offset:4608
	ds_read_b128 v[240:243], v211 offset:6912
	ds_read_b128 v[244:247], v211 offset:9216
	s_waitcnt lgkmcnt(7)
	v_mfma_f32_16x16x32_bf16 v[114:117], v[190:193], v[194:197], v[114:117]
	s_waitcnt lgkmcnt(6)
	v_mfma_f32_16x16x32_bf16 v[122:125], v[198:201], v[194:197], v[122:125]
	s_waitcnt lgkmcnt(5)
	v_mfma_f32_16x16x32_bf16 v[98:101], v[202:205], v[194:197], v[98:101]
	s_waitcnt lgkmcnt(4)
	v_mfma_f32_16x16x32_bf16 v[106:109], v[206:209], v[194:197], v[106:109]
	ds_read_b128 v[194:197], v211 offset:11520
	s_waitcnt lgkmcnt(4)
	v_mfma_f32_16x16x32_bf16 v[118:121], v[190:193], v[216:219], v[118:121]
	v_mfma_f32_16x16x32_bf16 v[126:129], v[198:201], v[216:219], v[126:129]
	v_mfma_f32_16x16x32_bf16 v[102:105], v[202:205], v[216:219], v[102:105]
	v_mfma_f32_16x16x32_bf16 v[110:113], v[206:209], v[216:219], v[110:113]
	ds_read_b128 v[216:219], v211 offset:13824
	s_waitcnt lgkmcnt(4)
	v_mfma_f32_16x16x32_bf16 v[82:85], v[190:193], v[236:239], v[82:85]
	v_mfma_f32_16x16x32_bf16 v[90:93], v[198:201], v[236:239], v[90:93]
	v_mfma_f32_16x16x32_bf16 v[66:69], v[202:205], v[236:239], v[66:69]
	v_mfma_f32_16x16x32_bf16 v[74:77], v[206:209], v[236:239], v[74:77]
	ds_read_b128 v[236:239], v211 offset:16128
	s_waitcnt lgkmcnt(4)
	v_mfma_f32_16x16x32_bf16 v[86:89], v[190:193], v[240:243], v[86:89]
	v_mfma_f32_16x16x32_bf16 v[94:97], v[198:201], v[240:243], v[94:97]
	v_mfma_f32_16x16x32_bf16 v[70:73], v[202:205], v[240:243], v[70:73]
	v_mfma_f32_16x16x32_bf16 v[78:81], v[206:209], v[240:243], v[78:81]
	ds_read_b128 v[240:243], v215 offset:36928
	s_waitcnt lgkmcnt(4)
	v_mfma_f32_16x16x32_bf16 v[50:53], v[190:193], v[244:247], v[50:53]
	v_mfma_f32_16x16x32_bf16 v[58:61], v[198:201], v[244:247], v[58:61]
	v_mfma_f32_16x16x32_bf16 v[34:37], v[202:205], v[244:247], v[34:37]
	v_mfma_f32_16x16x32_bf16 v[42:45], v[206:209], v[244:247], v[42:45]
	ds_read_b128 v[244:247], v211 offset:64
	s_waitcnt lgkmcnt(4)
	v_mfma_f32_16x16x32_bf16 v[54:57], v[190:193], v[194:197], v[54:57]
	v_mfma_f32_16x16x32_bf16 v[62:65], v[198:201], v[194:197], v[62:65]
	v_mfma_f32_16x16x32_bf16 v[38:41], v[202:205], v[194:197], v[38:41]
	v_mfma_f32_16x16x32_bf16 v[46:49], v[206:209], v[194:197], v[46:49]
	ds_read_b128 v[194:197], v211 offset:2368
	s_waitcnt lgkmcnt(4)
	v_mfma_f32_16x16x32_bf16 v[18:21], v[190:193], v[216:219], v[18:21]
	s_waitcnt lgkmcnt(3)
	v_mfma_f32_16x16x32_bf16 v[22:25], v[190:193], v[236:239], v[22:25]
	ds_read_b128 v[190:193], v215 offset:39232
	v_mfma_f32_16x16x32_bf16 v[26:29], v[198:201], v[216:219], v[26:29]
	v_mfma_f32_16x16x32_bf16 v[30:33], v[198:201], v[236:239], v[30:33]
	ds_read_b128 v[198:201], v215 offset:41536
	v_mfma_f32_16x16x32_bf16 v[2:5], v[202:205], v[216:219], v[2:5]
	v_mfma_f32_16x16x32_bf16 v[6:9], v[202:205], v[236:239], v[6:9]
	ds_read_b128 v[202:205], v215 offset:43840
	v_mfma_f32_16x16x32_bf16 v[10:13], v[206:209], v[216:219], v[10:13]
	ds_read_b128 v[216:219], v211 offset:4672
	v_mfma_f32_16x16x32_bf16 v[14:17], v[206:209], v[236:239], v[14:17]
	ds_read_b128 v[206:209], v211 offset:6976
	ds_read_b128 v[236:239], v211 offset:9280
	s_waitcnt lgkmcnt(7)
	v_mfma_f32_16x16x32_bf16 v[114:117], v[240:243], v[244:247], v[114:117]
	s_waitcnt lgkmcnt(6)
	v_mfma_f32_16x16x32_bf16 v[118:121], v[240:243], v[194:197], v[118:121]
	s_waitcnt lgkmcnt(5)
	v_mfma_f32_16x16x32_bf16 v[122:125], v[190:193], v[244:247], v[122:125]
	v_mfma_f32_16x16x32_bf16 v[126:129], v[190:193], v[194:197], v[126:129]
	s_waitcnt lgkmcnt(4)
	v_mfma_f32_16x16x32_bf16 v[98:101], v[198:201], v[244:247], v[98:101]
	v_mfma_f32_16x16x32_bf16 v[102:105], v[198:201], v[194:197], v[102:105]
	s_waitcnt lgkmcnt(3)
	v_mfma_f32_16x16x32_bf16 v[106:109], v[202:205], v[244:247], v[106:109]
	ds_read_b128 v[244:247], v211 offset:11584
	v_mfma_f32_16x16x32_bf16 v[110:113], v[202:205], v[194:197], v[110:113]
	ds_read_b128 v[194:197], v211 offset:13888
	s_waitcnt lgkmcnt(4)
	v_mfma_f32_16x16x32_bf16 v[82:85], v[240:243], v[216:219], v[82:85]
	v_mfma_f32_16x16x32_bf16 v[90:93], v[190:193], v[216:219], v[90:93]
	v_mfma_f32_16x16x32_bf16 v[66:69], v[198:201], v[216:219], v[66:69]
	v_mfma_f32_16x16x32_bf16 v[74:77], v[202:205], v[216:219], v[74:77]
	ds_read_b128 v[216:219], v211 offset:16192
	s_waitcnt lgkmcnt(4)
	v_mfma_f32_16x16x32_bf16 v[86:89], v[240:243], v[206:209], v[86:89]
	v_mfma_f32_16x16x32_bf16 v[94:97], v[190:193], v[206:209], v[94:97]
	v_mfma_f32_16x16x32_bf16 v[70:73], v[198:201], v[206:209], v[70:73]
	v_mfma_f32_16x16x32_bf16 v[78:81], v[202:205], v[206:209], v[78:81]
	s_waitcnt lgkmcnt(3)
	v_mfma_f32_16x16x32_bf16 v[50:53], v[240:243], v[236:239], v[50:53]
	v_mfma_f32_16x16x32_bf16 v[58:61], v[190:193], v[236:239], v[58:61]
	v_mfma_f32_16x16x32_bf16 v[34:37], v[198:201], v[236:239], v[34:37]
	v_mfma_f32_16x16x32_bf16 v[42:45], v[202:205], v[236:239], v[42:45]
	s_waitcnt lgkmcnt(2)
	v_mfma_f32_16x16x32_bf16 v[54:57], v[240:243], v[244:247], v[54:57]
	v_mfma_f32_16x16x32_bf16 v[62:65], v[190:193], v[244:247], v[62:65]
	v_mfma_f32_16x16x32_bf16 v[38:41], v[198:201], v[244:247], v[38:41]
	v_mfma_f32_16x16x32_bf16 v[46:49], v[202:205], v[244:247], v[46:49]
	s_waitcnt lgkmcnt(1)
	v_mfma_f32_16x16x32_bf16 v[18:21], v[240:243], v[194:197], v[18:21]
	v_mfma_f32_16x16x32_bf16 v[26:29], v[190:193], v[194:197], v[26:29]
	v_mfma_f32_16x16x32_bf16 v[2:5], v[198:201], v[194:197], v[2:5]
	v_mfma_f32_16x16x32_bf16 v[10:13], v[202:205], v[194:197], v[10:13]
	s_waitcnt lgkmcnt(0)
	v_mfma_f32_16x16x32_bf16 v[22:25], v[240:243], v[216:219], v[22:25]
	v_mfma_f32_16x16x32_bf16 v[30:33], v[190:193], v[216:219], v[30:33]
	v_mfma_f32_16x16x32_bf16 v[6:9], v[198:201], v[216:219], v[6:9]
	v_mfma_f32_16x16x32_bf16 v[14:17], v[202:205], v[216:219], v[14:17]
	s_setprio 0

.LcL_20:
	s_waitcnt lgkmcnt(0)
	s_barrier
	s_setprio 2
	v_bfe_u32 v221, v222, 5, 1
	v_bfe_u32 v248, v222, 4, 1
	v_lshl_add_u32 v211, v221, 4, v178
	v_lshl_add_u32 v215, v221, 4, v179
	v_mul_u32_u24_e32 v221, 0x8f0, v248
	v_mul_u32_u24_e32 v248, 0x8f8, v248
	v_sub_u32_e32 v213, v211, v248
	v_sub_u32_e32 v220, v215, v248
	v_sub_u32_e32 v211, v211, v221
	v_sub_u32_e32 v215, v215, v221
	ds_read_b128 v[190:193], v215 offset:36864
	ds_read_b128 v[194:197], v211
	ds_read_b128 v[198:201], v215 offset:39168
	ds_read_b128 v[202:205], v215 offset:41472
	ds_read_b128 v[206:209], v215 offset:43776
	ds_read_b128 v[216:219], v211 offset:2304
	ds_read_b128 v[236:239], v211 offset:4608
	ds_read_b128 v[240:243], v211 offset:6912
	ds_read_b128 v[244:247], v211 offset:9216
	s_waitcnt lgkmcnt(7)
	v_mfma_f32_16x16x32_bf16 v[114:117], v[190:193], v[194:197], v[114:117]
	s_ashr_i32 s1, s0, 31
	s_lshl_b64 s[6:7], s[0:1], 7
	s_waitcnt lgkmcnt(6)
	v_mfma_f32_16x16x32_bf16 v[122:125], v[198:201], v[194:197], v[122:125]
	v_lshl_add_u64 v[154:155], v[180:181], 0, s[6:7]
	v_add_co_u32_e32 v130, vcc, 0x2c000, v154
	s_waitcnt lgkmcnt(5)
	v_mfma_f32_16x16x32_bf16 v[98:101], v[202:205], v[194:197], v[98:101]
	v_lshl_add_u64 v[170:171], v[182:183], 0, s[6:7]
	s_nop 0
	s_waitcnt lgkmcnt(4)
	v_mfma_f32_16x16x32_bf16 v[106:109], v[206:209], v[194:197], v[106:109]
	ds_read_b128 v[194:197], v211 offset:11520
	v_addc_co_u32_e32 v131, vcc, 0, v155, vcc
	v_add_co_u32_e32 v134, vcc, 0x58000, v154
	s_waitcnt lgkmcnt(4)
	v_mfma_f32_16x16x32_bf16 v[118:121], v[190:193], v[216:219], v[118:121]
	global_load_dwordx4 v[142:145], v[154:155], off
	s_nop 0
	v_mfma_f32_16x16x32_bf16 v[126:129], v[198:201], v[216:219], v[126:129]
	global_load_dwordx4 v[130:133], v[130:131], off
	v_addc_co_u32_e32 v135, vcc, 0, v155, vcc
	v_mfma_f32_16x16x32_bf16 v[102:105], v[202:205], v[216:219], v[102:105]
	v_add_co_u32_e32 v138, vcc, 0x84000, v154
	s_add_i32 s0, s0, 1
	v_mfma_f32_16x16x32_bf16 v[110:113], v[206:209], v[216:219], v[110:113]
	ds_read_b128 v[216:219], v211 offset:13824
	s_nop 0
	v_addc_co_u32_e32 v139, vcc, 0, v155, vcc
	s_waitcnt lgkmcnt(4)
	v_mfma_f32_16x16x32_bf16 v[82:85], v[190:193], v[236:239], v[82:85]
	v_add_co_u32_e32 v146, vcc, 0xb0000, v154
	global_load_dwordx4 v[134:137], v[134:135], off
	v_mfma_f32_16x16x32_bf16 v[90:93], v[198:201], v[236:239], v[90:93]
	s_nop 0
	global_load_dwordx4 v[138:141], v[138:139], off
	v_mfma_f32_16x16x32_bf16 v[66:69], v[202:205], v[236:239], v[66:69]
	v_addc_co_u32_e32 v147, vcc, 0, v155, vcc
	v_add_co_u32_e32 v150, vcc, 0xdc000, v154
	v_mfma_f32_16x16x32_bf16 v[74:77], v[206:209], v[236:239], v[74:77]
	ds_read_b128 v[236:239], v211 offset:16128
	s_nop 0
	v_addc_co_u32_e32 v151, vcc, 0, v155, vcc
	s_waitcnt lgkmcnt(4)
	v_mfma_f32_16x16x32_bf16 v[86:89], v[190:193], v[240:243], v[86:89]
	v_add_co_u32_e32 v156, vcc, 0x108000, v154
	global_load_dwordx4 v[146:149], v[146:147], off
	v_mfma_f32_16x16x32_bf16 v[94:97], v[198:201], v[240:243], v[94:97]
	s_nop 0
	global_load_dwordx4 v[150:153], v[150:151], off
	v_mfma_f32_16x16x32_bf16 v[70:73], v[202:205], v[240:243], v[70:73]
	v_addc_co_u32_e32 v157, vcc, 0, v155, vcc
	v_add_co_u32_e32 v158, vcc, 0x134000, v154
	v_mfma_f32_16x16x32_bf16 v[78:81], v[206:209], v[240:243], v[78:81]
	ds_read_b128 v[240:243], v215 offset:36928
	s_nop 1
	v_addc_co_u32_e32 v159, vcc, 0, v155, vcc
	s_waitcnt lgkmcnt(4)
	v_mfma_f32_16x16x32_bf16 v[50:53], v[190:193], v[244:247], v[50:53]
	v_add_co_u32_e32 v166, vcc, 0x2c000, v170
	global_load_dwordx4 v[154:157], v[156:157], off
	v_mfma_f32_16x16x32_bf16 v[58:61], v[198:201], v[244:247], v[58:61]
	s_nop 0
	global_load_dwordx4 v[158:161], v[158:159], off
	v_mfma_f32_16x16x32_bf16 v[34:37], v[202:205], v[244:247], v[34:37]
	v_addc_co_u32_e32 v167, vcc, 0, v171, vcc
	v_add_co_u32_e32 v172, vcc, 0x58000, v170
	v_mfma_f32_16x16x32_bf16 v[42:45], v[206:209], v[244:247], v[42:45]
	ds_read_b128 v[244:247], v211 offset:64
	global_load_dwordx4 v[162:165], v[170:171], off
	s_nop 0
	s_waitcnt lgkmcnt(4)
	v_mfma_f32_16x16x32_bf16 v[54:57], v[190:193], v[194:197], v[54:57]
	global_load_dwordx4 v[166:169], v[166:167], off
	v_addc_co_u32_e32 v173, vcc, 0, v171, vcc
	v_mfma_f32_16x16x32_bf16 v[62:65], v[198:201], v[194:197], v[62:65]
	v_add_co_u32_e32 v174, vcc, 0x84000, v170
	s_nop 1
	v_mfma_f32_16x16x32_bf16 v[38:41], v[202:205], v[194:197], v[38:41]
	v_addc_co_u32_e32 v175, vcc, 0, v171, vcc
	global_load_dwordx4 v[170:173], v[172:173], off
	v_mfma_f32_16x16x32_bf16 v[46:49], v[206:209], v[194:197], v[46:49]
	ds_read_b128 v[194:197], v211 offset:2368
	s_nop 0
	global_load_dwordx4 v[174:177], v[174:175], off
	s_waitcnt lgkmcnt(4)
	v_mfma_f32_16x16x32_bf16 v[18:21], v[190:193], v[216:219], v[18:21]
	s_cmp_lg_u32 s0, 44
	s_waitcnt lgkmcnt(3)
	v_mfma_f32_16x16x32_bf16 v[22:25], v[190:193], v[236:239], v[22:25]
	ds_read_b128 v[190:193], v215 offset:39232
	v_mfma_f32_16x16x32_bf16 v[26:29], v[198:201], v[216:219], v[26:29]
	v_mfma_f32_16x16x32_bf16 v[30:33], v[198:201], v[236:239], v[30:33]
	ds_read_b128 v[198:201], v215 offset:41536
	v_mfma_f32_16x16x32_bf16 v[2:5], v[202:205], v[216:219], v[2:5]
	v_mfma_f32_16x16x32_bf16 v[6:9], v[202:205], v[236:239], v[6:9]
	ds_read_b128 v[202:205], v215 offset:43840
	v_mfma_f32_16x16x32_bf16 v[10:13], v[206:209], v[216:219], v[10:13]
	ds_read_b128 v[216:219], v211 offset:4672
	v_mfma_f32_16x16x32_bf16 v[14:17], v[206:209], v[236:239], v[14:17]
	ds_read_b128 v[206:209], v211 offset:6976
	ds_read_b128 v[236:239], v211 offset:9280
	s_waitcnt lgkmcnt(7)
	v_mfma_f32_16x16x32_bf16 v[114:117], v[240:243], v[244:247], v[114:117]
	s_waitcnt lgkmcnt(6)
	v_mfma_f32_16x16x32_bf16 v[118:121], v[240:243], v[194:197], v[118:121]
	s_waitcnt lgkmcnt(5)
	v_mfma_f32_16x16x32_bf16 v[122:125], v[190:193], v[244:247], v[122:125]
	v_mfma_f32_16x16x32_bf16 v[126:129], v[190:193], v[194:197], v[126:129]
	s_waitcnt lgkmcnt(4)
	v_mfma_f32_16x16x32_bf16 v[98:101], v[198:201], v[244:247], v[98:101]
	v_mfma_f32_16x16x32_bf16 v[102:105], v[198:201], v[194:197], v[102:105]
	s_waitcnt lgkmcnt(3)
	v_mfma_f32_16x16x32_bf16 v[106:109], v[202:205], v[244:247], v[106:109]
	ds_read_b128 v[244:247], v211 offset:11584
	v_mfma_f32_16x16x32_bf16 v[110:113], v[202:205], v[194:197], v[110:113]
	ds_read_b128 v[194:197], v211 offset:13888
	s_waitcnt lgkmcnt(4)
	v_mfma_f32_16x16x32_bf16 v[82:85], v[240:243], v[216:219], v[82:85]
	v_mfma_f32_16x16x32_bf16 v[90:93], v[190:193], v[216:219], v[90:93]
	v_mfma_f32_16x16x32_bf16 v[66:69], v[198:201], v[216:219], v[66:69]
	v_mfma_f32_16x16x32_bf16 v[74:77], v[202:205], v[216:219], v[74:77]
	ds_read_b128 v[216:219], v211 offset:16192
	s_waitcnt lgkmcnt(4)
	v_mfma_f32_16x16x32_bf16 v[86:89], v[240:243], v[206:209], v[86:89]
	v_mfma_f32_16x16x32_bf16 v[94:97], v[190:193], v[206:209], v[94:97]
	v_mfma_f32_16x16x32_bf16 v[70:73], v[198:201], v[206:209], v[70:73]
	v_mfma_f32_16x16x32_bf16 v[78:81], v[202:205], v[206:209], v[78:81]
	s_waitcnt lgkmcnt(3)
	v_mfma_f32_16x16x32_bf16 v[50:53], v[240:243], v[236:239], v[50:53]
	v_mfma_f32_16x16x32_bf16 v[58:61], v[190:193], v[236:239], v[58:61]
	v_mfma_f32_16x16x32_bf16 v[34:37], v[198:201], v[236:239], v[34:37]
	v_mfma_f32_16x16x32_bf16 v[42:45], v[202:205], v[236:239], v[42:45]
	s_waitcnt lgkmcnt(2)
	v_mfma_f32_16x16x32_bf16 v[54:57], v[240:243], v[244:247], v[54:57]
	v_mfma_f32_16x16x32_bf16 v[62:65], v[190:193], v[244:247], v[62:65]
	v_mfma_f32_16x16x32_bf16 v[38:41], v[198:201], v[244:247], v[38:41]
	v_mfma_f32_16x16x32_bf16 v[46:49], v[202:205], v[244:247], v[46:49]
	s_waitcnt lgkmcnt(1)
	v_mfma_f32_16x16x32_bf16 v[18:21], v[240:243], v[194:197], v[18:21]
	v_mfma_f32_16x16x32_bf16 v[26:29], v[190:193], v[194:197], v[26:29]
	v_mfma_f32_16x16x32_bf16 v[2:5], v[198:201], v[194:197], v[2:5]
	v_mfma_f32_16x16x32_bf16 v[10:13], v[202:205], v[194:197], v[10:13]
	s_waitcnt lgkmcnt(0)
	v_mfma_f32_16x16x32_bf16 v[22:25], v[240:243], v[216:219], v[22:25]
	v_mfma_f32_16x16x32_bf16 v[30:33], v[190:193], v[216:219], v[30:33]
	v_mfma_f32_16x16x32_bf16 v[6:9], v[198:201], v[216:219], v[6:9]
	v_mfma_f32_16x16x32_bf16 v[14:17], v[202:205], v[216:219], v[14:17]
	s_setprio 0
	s_cbranch_scc1 .Ltail_20
	s_add_i32 s2, s2, 1
	s_cmp_ge_i32 s2, s4
	s_cbranch_scc1 .Lz_20
	s_mul_i32 s0, s2, s82
	s_add_i32 s0, s0, s63
	s_ashr_i32 s1, s0, 31
	s_lshr_b32 s1, s1, 28
	s_add_i32 s1, s0, s1
	s_ashr_i32 s6, s1, 4
	s_and_b32 s1, s1, -16
	s_sub_i32 s0, s0, s1
	s_lshl_b32 s1, s6, 1
	s_and_b32 s6, s0, 1
	s_or_b32 s6, s6, s1
	s_lshr_b32 s7, s0, 1
	v_readlane_b32 s0, v252, 35
	s_sub_i32 s8, 0x7f, s6
	v_readlane_b32 s1, v252, 36
	s_and_b64 s[0:1], s[0:1], exec
	s_mul_i32 s0, s7, 0x58000
	s_cselect_b32 s6, s8, s6
	s_ashr_i32 s1, s0, 31
	v_mov_b32_e32 v0, 0x160000
	v_mad_i64_i32 v[180:181], s[6:7], s6, v0, v[186:187]
	v_lshl_add_u64 v[182:183], s[0:1], 1, v[188:189]

.LBB0_26:
	s_nop 7
	v_permlane16_swap_b32_e32 v114, v118
	v_permlane16_swap_b32_e32 v115, v119
	v_permlane16_swap_b32_e32 v116, v120
	v_permlane16_swap_b32_e32 v117, v121
	v_permlane16_swap_b32_e32 v122, v126
	v_permlane16_swap_b32_e32 v123, v127
	v_permlane16_swap_b32_e32 v124, v128
	v_permlane16_swap_b32_e32 v125, v129
	v_permlane32_swap_b32_e32 v114, v118
	v_permlane32_swap_b32_e32 v115, v119
	v_permlane32_swap_b32_e32 v116, v120
	v_permlane32_swap_b32_e32 v117, v121
	v_permlane32_swap_b32_e32 v122, v126
	v_permlane32_swap_b32_e32 v123, v127
	v_permlane32_swap_b32_e32 v124, v128
	v_permlane32_swap_b32_e32 v125, v129
	v_permlane16_swap_b32_e32 v98, v102
	v_permlane16_swap_b32_e32 v99, v103
	v_permlane16_swap_b32_e32 v100, v104
	v_permlane16_swap_b32_e32 v101, v105
	v_permlane16_swap_b32_e32 v106, v110
	v_permlane16_swap_b32_e32 v107, v111
	v_permlane16_swap_b32_e32 v108, v112
	v_permlane16_swap_b32_e32 v109, v113
	v_permlane32_swap_b32_e32 v98, v102
	v_permlane32_swap_b32_e32 v99, v103
	v_permlane32_swap_b32_e32 v100, v104
	v_permlane32_swap_b32_e32 v101, v105
	v_permlane32_swap_b32_e32 v106, v110
	v_permlane32_swap_b32_e32 v107, v111
	v_permlane32_swap_b32_e32 v108, v112
	v_permlane32_swap_b32_e32 v109, v113
	v_permlane16_swap_b32_e32 v82, v86
	v_permlane16_swap_b32_e32 v83, v87
	v_permlane16_swap_b32_e32 v84, v88
	v_permlane16_swap_b32_e32 v85, v89
	v_permlane16_swap_b32_e32 v90, v94
	v_permlane16_swap_b32_e32 v91, v95
	v_permlane16_swap_b32_e32 v92, v96
	v_permlane16_swap_b32_e32 v93, v97
	v_permlane32_swap_b32_e32 v82, v86
	v_permlane32_swap_b32_e32 v83, v87
	v_permlane32_swap_b32_e32 v84, v88
	v_permlane32_swap_b32_e32 v85, v89
	v_permlane32_swap_b32_e32 v90, v94
	v_permlane32_swap_b32_e32 v91, v95
	v_permlane32_swap_b32_e32 v92, v96
	v_permlane32_swap_b32_e32 v93, v97
	v_permlane16_swap_b32_e32 v66, v70
	v_permlane16_swap_b32_e32 v67, v71
	v_permlane16_swap_b32_e32 v68, v72
	v_permlane16_swap_b32_e32 v69, v73
	v_permlane16_swap_b32_e32 v74, v78
	v_permlane16_swap_b32_e32 v75, v79
	v_permlane16_swap_b32_e32 v76, v80
	v_permlane16_swap_b32_e32 v77, v81
	v_permlane32_swap_b32_e32 v66, v70
	v_permlane32_swap_b32_e32 v67, v71
	v_permlane32_swap_b32_e32 v68, v72
	v_permlane32_swap_b32_e32 v69, v73
	v_permlane32_swap_b32_e32 v74, v78
	v_permlane32_swap_b32_e32 v75, v79
	v_permlane32_swap_b32_e32 v76, v80
	v_permlane32_swap_b32_e32 v77, v81
	v_permlane16_swap_b32_e32 v50, v54
	v_permlane16_swap_b32_e32 v51, v55
	v_permlane16_swap_b32_e32 v52, v56
	v_permlane16_swap_b32_e32 v53, v57
	v_permlane16_swap_b32_e32 v58, v62
	v_permlane16_swap_b32_e32 v59, v63
	v_permlane16_swap_b32_e32 v60, v64
	v_permlane16_swap_b32_e32 v61, v65
	v_permlane32_swap_b32_e32 v50, v54
	v_permlane32_swap_b32_e32 v51, v55
	v_permlane32_swap_b32_e32 v52, v56
	v_permlane32_swap_b32_e32 v53, v57
	v_permlane32_swap_b32_e32 v58, v62
	v_permlane32_swap_b32_e32 v59, v63
	v_permlane32_swap_b32_e32 v60, v64
	v_permlane32_swap_b32_e32 v61, v65
	v_permlane16_swap_b32_e32 v34, v38
	v_permlane16_swap_b32_e32 v35, v39
	v_permlane16_swap_b32_e32 v36, v40
	v_permlane16_swap_b32_e32 v37, v41
	v_permlane16_swap_b32_e32 v42, v46
	v_permlane16_swap_b32_e32 v43, v47
	v_permlane16_swap_b32_e32 v44, v48
	v_permlane16_swap_b32_e32 v45, v49
	v_permlane32_swap_b32_e32 v34, v38
	v_permlane32_swap_b32_e32 v35, v39
	v_permlane32_swap_b32_e32 v36, v40
	v_permlane32_swap_b32_e32 v37, v41
	v_permlane32_swap_b32_e32 v42, v46
	v_permlane32_swap_b32_e32 v43, v47
	v_permlane32_swap_b32_e32 v44, v48
	v_permlane32_swap_b32_e32 v45, v49
	v_permlane16_swap_b32_e32 v18, v22
	v_permlane16_swap_b32_e32 v19, v23
	v_permlane16_swap_b32_e32 v20, v24
	v_permlane16_swap_b32_e32 v21, v25
	v_permlane16_swap_b32_e32 v26, v30
	v_permlane16_swap_b32_e32 v27, v31
	v_permlane16_swap_b32_e32 v28, v32
	v_permlane16_swap_b32_e32 v29, v33
	v_permlane32_swap_b32_e32 v18, v22
	v_permlane32_swap_b32_e32 v19, v23
	v_permlane32_swap_b32_e32 v20, v24
	v_permlane32_swap_b32_e32 v21, v25
	v_permlane32_swap_b32_e32 v26, v30
	v_permlane32_swap_b32_e32 v27, v31
	v_permlane32_swap_b32_e32 v28, v32
	v_permlane32_swap_b32_e32 v29, v33
	v_permlane16_swap_b32_e32 v2, v6
	v_permlane16_swap_b32_e32 v3, v7
	v_permlane16_swap_b32_e32 v4, v8
	v_permlane16_swap_b32_e32 v5, v9
	v_permlane16_swap_b32_e32 v10, v14
	v_permlane16_swap_b32_e32 v11, v15
	v_permlane16_swap_b32_e32 v12, v16
	v_permlane16_swap_b32_e32 v13, v17
	v_permlane32_swap_b32_e32 v2, v6
	v_permlane32_swap_b32_e32 v3, v7
	v_permlane32_swap_b32_e32 v4, v8
	v_permlane32_swap_b32_e32 v5, v9
	v_permlane32_swap_b32_e32 v10, v14
	v_permlane32_swap_b32_e32 v11, v15
	v_permlane32_swap_b32_e32 v12, v16
	v_permlane32_swap_b32_e32 v13, v17
	s_mul_i32 s1, s5, s82
	s_add_i32 s1, s1, s63
	s_ashr_i32 s3, s1, 31
	s_lshr_b32 s3, s3, 28
	s_add_i32 s3, s1, s3
	s_ashr_i32 s6, s3, 4
	s_and_b32 s3, s3, -16
	s_sub_i32 s1, s1, s3
	s_lshl_b32 s3, s6, 1
	s_and_b32 s6, s1, 1
	s_or_b32 s3, s6, s3
	v_readlane_b32 s6, v252, 35
	s_sub_i32 s8, 0x7f, s3
	v_readlane_b32 s7, v252, 36
	s_and_b64 s[6:7], s[6:7], exec
	s_cselect_b32 s6, s8, s3
	v_mov_b32_e32 v0, v222
	s_ashr_i32 s7, s6, 31
	v_and_b32_e32 v190, 0xffffff80, v0
	s_lshl_b64 s[6:7], s[6:7], 8
	v_ashrrev_i32_e32 v191, 31, v190
	v_lshl_add_u64 v[190:191], s[6:7], 0, v[190:191]
	s_lshl_b32 s1, s1, 6
	v_and_b32_e32 v185, 64, v0
	v_and_or_b32 v190, v0, 31, v190
	s_and_b32 s1, s1, 0xffffff80
	v_lshrrev_b32_e32 v0, 3, v0
	v_readlane_b32 s6, v252, 31
	s_ashr_i32 s3, s1, 31
	v_and_b32_e32 v0, 4, v0
	v_lshlrev_b64 v[190:191], 12, v[190:191]
	v_readlane_b32 s7, v252, 32
	v_or3_b32 v192, v0, v185, s1
	v_mov_b32_e32 v193, s3
	v_lshl_add_u64 v[190:191], s[6:7], 0, v[190:191]
	v_lshl_add_u64 v[190:191], v[192:193], 2, v[190:191]
	s_mov_b64 s[98:99], 0x20000
	v_lshl_add_u64 v[192:193], v[190:191], 0, 0
	v_lshl_add_u64 v[220:221], v[190:191], 0, 0
	global_load_dwordx4 v[194:197], v[192:193], off
	global_load_dwordx4 v[198:201], v[192:193], off offset:32
	global_load_dwordx4 v[202:205], v[192:193], off offset:64
	global_load_dwordx4 v[206:209], v[192:193], off offset:96
	global_load_dwordx4 v[216:219], v[192:193], off offset:128
	global_load_dwordx4 v[236:239], v[192:193], off offset:160
	global_load_dwordx4 v[240:243], v[192:193], off offset:192
	global_load_dwordx4 v[244:247], v[192:193], off offset:224
	s_waitcnt vmcnt(7)
	v_pk_fma_f32 v[114:115], v[114:115], 0.5, v[194:195] op_sel_hi:[1,0,1]
	v_pk_fma_f32 v[116:117], v[116:117], 0.5, v[196:197] op_sel_hi:[1,0,1]
	global_store_dwordx4 v[220:221], v[114:117], off
	v_lshl_add_u64 v[192:193], v[192:193], 0, s[98:99]
	global_load_dwordx4 v[194:197], v[192:193], off
	s_waitcnt vmcnt(8)
	v_pk_fma_f32 v[118:119], v[118:119], 0.5, v[198:199] op_sel_hi:[1,0,1]
	v_pk_fma_f32 v[120:121], v[120:121], 0.5, v[200:201] op_sel_hi:[1,0,1]
	global_store_dwordx4 v[220:221], v[118:121], off offset:32
	global_load_dwordx4 v[198:201], v[192:193], off offset:32
	s_waitcnt vmcnt(9)
	v_pk_fma_f32 v[122:123], v[122:123], 0.5, v[202:203] op_sel_hi:[1,0,1]
	v_pk_fma_f32 v[124:125], v[124:125], 0.5, v[204:205] op_sel_hi:[1,0,1]
	global_store_dwordx4 v[220:221], v[122:125], off offset:64
	global_load_dwordx4 v[202:205], v[192:193], off offset:64
	s_waitcnt vmcnt(10)
	v_pk_fma_f32 v[126:127], v[126:127], 0.5, v[206:207] op_sel_hi:[1,0,1]
	v_pk_fma_f32 v[128:129], v[128:129], 0.5, v[208:209] op_sel_hi:[1,0,1]
	global_store_dwordx4 v[220:221], v[126:129], off offset:96
	global_load_dwordx4 v[206:209], v[192:193], off offset:96
	s_waitcnt vmcnt(11)
	v_pk_fma_f32 v[98:99], v[98:99], 0.5, v[216:217] op_sel_hi:[1,0,1]
	v_pk_fma_f32 v[100:101], v[100:101], 0.5, v[218:219] op_sel_hi:[1,0,1]
	global_store_dwordx4 v[220:221], v[98:101], off offset:128
	global_load_dwordx4 v[216:219], v[192:193], off offset:128
	s_waitcnt vmcnt(12)
	v_pk_fma_f32 v[102:103], v[102:103], 0.5, v[236:237] op_sel_hi:[1,0,1]
	v_pk_fma_f32 v[104:105], v[104:105], 0.5, v[238:239] op_sel_hi:[1,0,1]
	global_store_dwordx4 v[220:221], v[102:105], off offset:160
	global_load_dwordx4 v[236:239], v[192:193], off offset:160
	s_waitcnt vmcnt(13)
	v_pk_fma_f32 v[106:107], v[106:107], 0.5, v[240:241] op_sel_hi:[1,0,1]
	v_pk_fma_f32 v[108:109], v[108:109], 0.5, v[242:243] op_sel_hi:[1,0,1]
	global_store_dwordx4 v[220:221], v[106:109], off offset:192
	global_load_dwordx4 v[240:243], v[192:193], off offset:192
	s_waitcnt vmcnt(14)
	v_pk_fma_f32 v[110:111], v[110:111], 0.5, v[244:245] op_sel_hi:[1,0,1]
	v_pk_fma_f32 v[112:113], v[112:113], 0.5, v[246:247] op_sel_hi:[1,0,1]
	global_store_dwordx4 v[220:221], v[110:113], off offset:224
	global_load_dwordx4 v[244:247], v[192:193], off offset:224
	s_waitcnt vmcnt(14)
	v_pk_fma_f32 v[82:83], v[82:83], 0.5, v[194:195] op_sel_hi:[1,0,1]
	v_pk_fma_f32 v[84:85], v[84:85], 0.5, v[196:197] op_sel_hi:[1,0,1]
	v_lshl_add_u64 v[220:221], v[220:221], 0, s[98:99]
	global_store_dwordx4 v[220:221], v[82:85], off
	v_lshl_add_u64 v[192:193], v[192:193], 0, s[98:99]
	global_load_dwordx4 v[194:197], v[192:193], off
	s_waitcnt vmcnt(14)
	v_pk_fma_f32 v[86:87], v[86:87], 0.5, v[198:199] op_sel_hi:[1,0,1]
	v_pk_fma_f32 v[88:89], v[88:89], 0.5, v[200:201] op_sel_hi:[1,0,1]
	global_store_dwordx4 v[220:221], v[86:89], off offset:32
	global_load_dwordx4 v[198:201], v[192:193], off offset:32
	s_waitcnt vmcnt(14)
	v_pk_fma_f32 v[90:91], v[90:91], 0.5, v[202:203] op_sel_hi:[1,0,1]
	v_pk_fma_f32 v[92:93], v[92:93], 0.5, v[204:205] op_sel_hi:[1,0,1]
	global_store_dwordx4 v[220:221], v[90:93], off offset:64
	global_load_dwordx4 v[202:205], v[192:193], off offset:64
	s_waitcnt vmcnt(14)
	v_pk_fma_f32 v[94:95], v[94:95], 0.5, v[206:207] op_sel_hi:[1,0,1]
	v_pk_fma_f32 v[96:97], v[96:97], 0.5, v[208:209] op_sel_hi:[1,0,1]
	global_store_dwordx4 v[220:221], v[94:97], off offset:96
	global_load_dwordx4 v[206:209], v[192:193], off offset:96
	s_waitcnt vmcnt(14)
	v_pk_fma_f32 v[66:67], v[66:67], 0.5, v[216:217] op_sel_hi:[1,0,1]
	v_pk_fma_f32 v[68:69], v[68:69], 0.5, v[218:219] op_sel_hi:[1,0,1]
	global_store_dwordx4 v[220:221], v[66:69], off offset:128
	global_load_dwordx4 v[216:219], v[192:193], off offset:128
	s_waitcnt vmcnt(14)
	v_pk_fma_f32 v[70:71], v[70:71], 0.5, v[236:237] op_sel_hi:[1,0,1]
	v_pk_fma_f32 v[72:73], v[72:73], 0.5, v[238:239] op_sel_hi:[1,0,1]
	global_store_dwordx4 v[220:221], v[70:73], off offset:160
	global_load_dwordx4 v[236:239], v[192:193], off offset:160
	s_waitcnt vmcnt(14)
	v_pk_fma_f32 v[74:75], v[74:75], 0.5, v[240:241] op_sel_hi:[1,0,1]
	v_pk_fma_f32 v[76:77], v[76:77], 0.5, v[242:243] op_sel_hi:[1,0,1]
	global_store_dwordx4 v[220:221], v[74:77], off offset:192
	global_load_dwordx4 v[240:243], v[192:193], off offset:192
	s_waitcnt vmcnt(14)
	v_pk_fma_f32 v[78:79], v[78:79], 0.5, v[244:245] op_sel_hi:[1,0,1]
	v_pk_fma_f32 v[80:81], v[80:81], 0.5, v[246:247] op_sel_hi:[1,0,1]
	global_store_dwordx4 v[220:221], v[78:81], off offset:224
	global_load_dwordx4 v[244:247], v[192:193], off offset:224
	s_waitcnt vmcnt(14)
	v_pk_fma_f32 v[50:51], v[50:51], 0.5, v[194:195] op_sel_hi:[1,0,1]
	v_pk_fma_f32 v[52:53], v[52:53], 0.5, v[196:197] op_sel_hi:[1,0,1]
	v_lshl_add_u64 v[220:221], v[220:221], 0, s[98:99]
	global_store_dwordx4 v[220:221], v[50:53], off
	v_lshl_add_u64 v[192:193], v[192:193], 0, s[98:99]
	global_load_dwordx4 v[194:197], v[192:193], off
	s_waitcnt vmcnt(14)
	v_pk_fma_f32 v[54:55], v[54:55], 0.5, v[198:199] op_sel_hi:[1,0,1]
	v_pk_fma_f32 v[56:57], v[56:57], 0.5, v[200:201] op_sel_hi:[1,0,1]
	global_store_dwordx4 v[220:221], v[54:57], off offset:32
	global_load_dwordx4 v[198:201], v[192:193], off offset:32
	s_waitcnt vmcnt(14)
	v_pk_fma_f32 v[58:59], v[58:59], 0.5, v[202:203] op_sel_hi:[1,0,1]
	v_pk_fma_f32 v[60:61], v[60:61], 0.5, v[204:205] op_sel_hi:[1,0,1]
	global_store_dwordx4 v[220:221], v[58:61], off offset:64
	global_load_dwordx4 v[202:205], v[192:193], off offset:64
	s_waitcnt vmcnt(14)
	v_pk_fma_f32 v[62:63], v[62:63], 0.5, v[206:207] op_sel_hi:[1,0,1]
	v_pk_fma_f32 v[64:65], v[64:65], 0.5, v[208:209] op_sel_hi:[1,0,1]
	global_store_dwordx4 v[220:221], v[62:65], off offset:96
	global_load_dwordx4 v[206:209], v[192:193], off offset:96
	s_waitcnt vmcnt(14)
	v_pk_fma_f32 v[34:35], v[34:35], 0.5, v[216:217] op_sel_hi:[1,0,1]
	v_pk_fma_f32 v[36:37], v[36:37], 0.5, v[218:219] op_sel_hi:[1,0,1]
	global_store_dwordx4 v[220:221], v[34:37], off offset:128
	global_load_dwordx4 v[216:219], v[192:193], off offset:128
	s_waitcnt vmcnt(14)
	v_pk_fma_f32 v[38:39], v[38:39], 0.5, v[236:237] op_sel_hi:[1,0,1]
	v_pk_fma_f32 v[40:41], v[40:41], 0.5, v[238:239] op_sel_hi:[1,0,1]
	global_store_dwordx4 v[220:221], v[38:41], off offset:160
	global_load_dwordx4 v[236:239], v[192:193], off offset:160
	s_waitcnt vmcnt(14)
	v_pk_fma_f32 v[42:43], v[42:43], 0.5, v[240:241] op_sel_hi:[1,0,1]
	v_pk_fma_f32 v[44:45], v[44:45], 0.5, v[242:243] op_sel_hi:[1,0,1]
	global_store_dwordx4 v[220:221], v[42:45], off offset:192
	global_load_dwordx4 v[240:243], v[192:193], off offset:192
	s_waitcnt vmcnt(14)
	v_pk_fma_f32 v[46:47], v[46:47], 0.5, v[244:245] op_sel_hi:[1,0,1]
	v_pk_fma_f32 v[48:49], v[48:49], 0.5, v[246:247] op_sel_hi:[1,0,1]
	global_store_dwordx4 v[220:221], v[46:49], off offset:224
	global_load_dwordx4 v[244:247], v[192:193], off offset:224
	s_waitcnt vmcnt(14)
	v_pk_fma_f32 v[18:19], v[18:19], 0.5, v[194:195] op_sel_hi:[1,0,1]
	v_pk_fma_f32 v[20:21], v[20:21], 0.5, v[196:197] op_sel_hi:[1,0,1]
	v_lshl_add_u64 v[220:221], v[220:221], 0, s[98:99]
	global_store_dwordx4 v[220:221], v[18:21], off
	s_waitcnt vmcnt(13)
	v_pk_fma_f32 v[22:23], v[22:23], 0.5, v[198:199] op_sel_hi:[1,0,1]
	v_pk_fma_f32 v[24:25], v[24:25], 0.5, v[200:201] op_sel_hi:[1,0,1]
	global_store_dwordx4 v[220:221], v[22:25], off offset:32
	s_waitcnt vmcnt(12)
	v_pk_fma_f32 v[26:27], v[26:27], 0.5, v[202:203] op_sel_hi:[1,0,1]
	v_pk_fma_f32 v[28:29], v[28:29], 0.5, v[204:205] op_sel_hi:[1,0,1]
	global_store_dwordx4 v[220:221], v[26:29], off offset:64
	s_waitcnt vmcnt(11)
	v_pk_fma_f32 v[30:31], v[30:31], 0.5, v[206:207] op_sel_hi:[1,0,1]
	v_pk_fma_f32 v[32:33], v[32:33], 0.5, v[208:209] op_sel_hi:[1,0,1]
	global_store_dwordx4 v[220:221], v[30:33], off offset:96
	s_waitcnt vmcnt(10)
	v_pk_fma_f32 v[2:3], v[2:3], 0.5, v[216:217] op_sel_hi:[1,0,1]
	v_pk_fma_f32 v[4:5], v[4:5], 0.5, v[218:219] op_sel_hi:[1,0,1]
	global_store_dwordx4 v[220:221], v[2:5], off offset:128
	s_waitcnt vmcnt(9)
	v_pk_fma_f32 v[6:7], v[6:7], 0.5, v[236:237] op_sel_hi:[1,0,1]
	v_pk_fma_f32 v[8:9], v[8:9], 0.5, v[238:239] op_sel_hi:[1,0,1]
	global_store_dwordx4 v[220:221], v[6:9], off offset:160
	s_waitcnt vmcnt(8)
	v_pk_fma_f32 v[10:11], v[10:11], 0.5, v[240:241] op_sel_hi:[1,0,1]
	v_pk_fma_f32 v[12:13], v[12:13], 0.5, v[242:243] op_sel_hi:[1,0,1]
	global_store_dwordx4 v[220:221], v[10:13], off offset:192
	s_waitcnt vmcnt(7)
	v_pk_fma_f32 v[14:15], v[14:15], 0.5, v[244:245] op_sel_hi:[1,0,1]
	v_pk_fma_f32 v[16:17], v[16:17], 0.5, v[246:247] op_sel_hi:[1,0,1]
	global_store_dwordx4 v[220:221], v[14:17], off offset:224
	s_mov_b32 s3, 0
	s_add_i32 s5, s5, 1
	v_mov_b32_e32 v114, 0
	v_mov_b32_e32 v115, 0
	v_mov_b32_e32 v116, 0
	v_mov_b32_e32 v117, 0
	v_mov_b32_e32 v118, 0
	v_mov_b32_e32 v119, 0
	v_mov_b32_e32 v120, 0
	v_mov_b32_e32 v121, 0
	v_mov_b32_e32 v122, 0
	v_mov_b32_e32 v123, 0
	v_mov_b32_e32 v124, 0
	v_mov_b32_e32 v125, 0
	v_mov_b32_e32 v126, 0
	v_mov_b32_e32 v127, 0
	v_mov_b32_e32 v128, 0
	v_mov_b32_e32 v129, 0
	v_mov_b32_e32 v98, 0
	v_mov_b32_e32 v99, 0
	v_mov_b32_e32 v100, 0
	v_mov_b32_e32 v101, 0
	v_mov_b32_e32 v102, 0
	v_mov_b32_e32 v103, 0
	v_mov_b32_e32 v104, 0
	v_mov_b32_e32 v105, 0
	v_mov_b32_e32 v106, 0
	v_mov_b32_e32 v107, 0
	v_mov_b32_e32 v108, 0
	v_mov_b32_e32 v109, 0
	v_mov_b32_e32 v110, 0
	v_mov_b32_e32 v111, 0
	v_mov_b32_e32 v112, 0
	v_mov_b32_e32 v113, 0
	v_mov_b32_e32 v82, 0
	v_mov_b32_e32 v83, 0
	v_mov_b32_e32 v84, 0
	v_mov_b32_e32 v85, 0
	v_mov_b32_e32 v86, 0
	v_mov_b32_e32 v87, 0
	v_mov_b32_e32 v88, 0
	v_mov_b32_e32 v89, 0
	v_mov_b32_e32 v90, 0
	v_mov_b32_e32 v91, 0
	v_mov_b32_e32 v92, 0
	v_mov_b32_e32 v93, 0
	v_mov_b32_e32 v94, 0
	v_mov_b32_e32 v95, 0
	v_mov_b32_e32 v96, 0
	v_mov_b32_e32 v97, 0
	v_mov_b32_e32 v66, 0
	v_mov_b32_e32 v67, 0
	v_mov_b32_e32 v68, 0
	v_mov_b32_e32 v69, 0
	v_mov_b32_e32 v70, 0
	v_mov_b32_e32 v71, 0
	v_mov_b32_e32 v72, 0
	v_mov_b32_e32 v73, 0
	v_mov_b32_e32 v74, 0
	v_mov_b32_e32 v75, 0
	v_mov_b32_e32 v76, 0
	v_mov_b32_e32 v77, 0
	v_mov_b32_e32 v78, 0
	v_mov_b32_e32 v79, 0
	v_mov_b32_e32 v80, 0
	v_mov_b32_e32 v81, 0
	v_mov_b32_e32 v50, 0
	v_mov_b32_e32 v51, 0
	v_mov_b32_e32 v52, 0
	v_mov_b32_e32 v53, 0
	v_mov_b32_e32 v54, 0
	v_mov_b32_e32 v55, 0
	v_mov_b32_e32 v56, 0
	v_mov_b32_e32 v57, 0
	v_mov_b32_e32 v58, 0
	v_mov_b32_e32 v59, 0
	v_mov_b32_e32 v60, 0
	v_mov_b32_e32 v61, 0
	v_mov_b32_e32 v62, 0
	v_mov_b32_e32 v63, 0
	v_mov_b32_e32 v64, 0
	v_mov_b32_e32 v65, 0
	v_mov_b32_e32 v34, 0
	v_mov_b32_e32 v35, 0
	v_mov_b32_e32 v36, 0
	v_mov_b32_e32 v37, 0
	v_mov_b32_e32 v38, 0
	v_mov_b32_e32 v39, 0
	v_mov_b32_e32 v40, 0
	v_mov_b32_e32 v41, 0
	v_mov_b32_e32 v42, 0
	v_mov_b32_e32 v43, 0
	v_mov_b32_e32 v44, 0
	v_mov_b32_e32 v45, 0
	v_mov_b32_e32 v46, 0
	v_mov_b32_e32 v47, 0
	v_mov_b32_e32 v48, 0
	v_mov_b32_e32 v49, 0
	v_mov_b32_e32 v18, 0
	v_mov_b32_e32 v19, 0
	v_mov_b32_e32 v20, 0
	v_mov_b32_e32 v21, 0
	v_mov_b32_e32 v22, 0
	v_mov_b32_e32 v23, 0
	v_mov_b32_e32 v24, 0
	v_mov_b32_e32 v25, 0
	v_mov_b32_e32 v26, 0
	v_mov_b32_e32 v27, 0
	v_mov_b32_e32 v28, 0
	v_mov_b32_e32 v29, 0
	v_mov_b32_e32 v30, 0
	v_mov_b32_e32 v31, 0
	v_mov_b32_e32 v32, 0
	v_mov_b32_e32 v33, 0
	v_mov_b32_e32 v2, 0
	v_mov_b32_e32 v3, 0
	v_mov_b32_e32 v4, 0
	v_mov_b32_e32 v5, 0
	v_mov_b32_e32 v6, 0
	v_mov_b32_e32 v7, 0
	v_mov_b32_e32 v8, 0
	v_mov_b32_e32 v9, 0
	v_mov_b32_e32 v10, 0
	v_mov_b32_e32 v11, 0
	v_mov_b32_e32 v12, 0
	v_mov_b32_e32 v13, 0
	v_mov_b32_e32 v14, 0
	v_mov_b32_e32 v15, 0
	v_mov_b32_e32 v16, 0
	v_mov_b32_e32 v17, 0
	s_cmp_lt_i32 s5, s4
	s_cbranch_scc1 .LBB0_22

.LcL_34:
	s_waitcnt lgkmcnt(0)
	s_barrier
	s_setprio 2
	v_bfe_u32 v221, v222, 5, 1
	v_bfe_u32 v248, v222, 4, 1
	v_lshl_add_u32 v211, v221, 4, v178
	v_lshl_add_u32 v215, v221, 4, v179
	v_mul_u32_u24_e32 v221, 0x8f0, v248
	v_mul_u32_u24_e32 v248, 0x8f8, v248
	v_sub_u32_e32 v213, v211, v248
	v_sub_u32_e32 v220, v215, v248
	v_sub_u32_e32 v211, v211, v221
	v_sub_u32_e32 v215, v215, v221
	ds_read_b128 v[190:193], v215 offset:36864
	ds_read_b128 v[194:197], v211
	ds_read_b128 v[198:201], v215 offset:39168
	ds_read_b128 v[202:205], v215 offset:41472
	ds_read_b128 v[206:209], v215 offset:43776
	ds_read_b128 v[216:219], v211 offset:2304
	ds_read_b128 v[236:239], v211 offset:4608
	ds_read_b128 v[240:243], v211 offset:6912
	ds_read_b128 v[244:247], v211 offset:9216
	s_waitcnt lgkmcnt(7)
	v_mfma_f32_16x16x32_bf16 v[114:117], v[190:193], v[194:197], v[114:117]
	s_ashr_i32 s1, s0, 31
	s_lshl_b64 s[6:7], s[0:1], 7
	s_waitcnt lgkmcnt(6)
	v_mfma_f32_16x16x32_bf16 v[122:125], v[198:201], v[194:197], v[122:125]
	v_lshl_add_u64 v[154:155], v[180:181], 0, s[6:7]
	v_add_co_u32_e32 v130, vcc, 0x10000, v154
	s_waitcnt lgkmcnt(5)
	v_mfma_f32_16x16x32_bf16 v[98:101], v[202:205], v[194:197], v[98:101]
	v_lshl_add_u64 v[170:171], v[182:183], 0, s[6:7]
	s_nop 0
	s_waitcnt lgkmcnt(4)
	v_mfma_f32_16x16x32_bf16 v[106:109], v[206:209], v[194:197], v[106:109]
	ds_read_b128 v[194:197], v211 offset:11520
	v_addc_co_u32_e32 v131, vcc, 0, v155, vcc
	v_add_co_u32_e32 v134, vcc, 0x20000, v154
	s_waitcnt lgkmcnt(4)
	v_mfma_f32_16x16x32_bf16 v[118:121], v[190:193], v[216:219], v[118:121]
	global_load_dwordx4 v[142:145], v[154:155], off
	s_nop 0
	v_mfma_f32_16x16x32_bf16 v[126:129], v[198:201], v[216:219], v[126:129]
	global_load_dwordx4 v[130:133], v[130:131], off
	v_addc_co_u32_e32 v135, vcc, 0, v155, vcc
	v_mfma_f32_16x16x32_bf16 v[102:105], v[202:205], v[216:219], v[102:105]
	v_add_co_u32_e32 v138, vcc, 0x30000, v154
	s_add_i32 s0, s0, 1
	v_mfma_f32_16x16x32_bf16 v[110:113], v[206:209], v[216:219], v[110:113]
	ds_read_b128 v[216:219], v211 offset:13824
	s_nop 0
	v_addc_co_u32_e32 v139, vcc, 0, v155, vcc
	s_waitcnt lgkmcnt(4)
	v_mfma_f32_16x16x32_bf16 v[82:85], v[190:193], v[236:239], v[82:85]
	v_add_co_u32_e32 v146, vcc, 0x40000, v154
	global_load_dwordx4 v[134:137], v[134:135], off
	v_mfma_f32_16x16x32_bf16 v[90:93], v[198:201], v[236:239], v[90:93]
	s_nop 0
	global_load_dwordx4 v[138:141], v[138:139], off
	v_mfma_f32_16x16x32_bf16 v[66:69], v[202:205], v[236:239], v[66:69]
	v_addc_co_u32_e32 v147, vcc, 0, v155, vcc
	v_add_co_u32_e32 v150, vcc, 0x50000, v154
	v_mfma_f32_16x16x32_bf16 v[74:77], v[206:209], v[236:239], v[74:77]
	ds_read_b128 v[236:239], v211 offset:16128
	s_nop 0
	v_addc_co_u32_e32 v151, vcc, 0, v155, vcc
	s_waitcnt lgkmcnt(4)
	v_mfma_f32_16x16x32_bf16 v[86:89], v[190:193], v[240:243], v[86:89]
	v_add_co_u32_e32 v156, vcc, 0x60000, v154
	global_load_dwordx4 v[146:149], v[146:147], off
	v_mfma_f32_16x16x32_bf16 v[94:97], v[198:201], v[240:243], v[94:97]
	s_nop 0
	global_load_dwordx4 v[150:153], v[150:151], off
	v_mfma_f32_16x16x32_bf16 v[70:73], v[202:205], v[240:243], v[70:73]
	v_addc_co_u32_e32 v157, vcc, 0, v155, vcc
	v_add_co_u32_e32 v158, vcc, 0x70000, v154
	v_mfma_f32_16x16x32_bf16 v[78:81], v[206:209], v[240:243], v[78:81]
	ds_read_b128 v[240:243], v215 offset:36928
	s_nop 1
	v_addc_co_u32_e32 v159, vcc, 0, v155, vcc
	s_waitcnt lgkmcnt(4)
	v_mfma_f32_16x16x32_bf16 v[50:53], v[190:193], v[244:247], v[50:53]
	v_add_co_u32_e32 v166, vcc, 0x10000, v170
	global_load_dwordx4 v[154:157], v[156:157], off
	v_mfma_f32_16x16x32_bf16 v[58:61], v[198:201], v[244:247], v[58:61]
	s_nop 0
	global_load_dwordx4 v[158:161], v[158:159], off
	v_mfma_f32_16x16x32_bf16 v[34:37], v[202:205], v[244:247], v[34:37]
	v_addc_co_u32_e32 v167, vcc, 0, v171, vcc
	v_add_co_u32_e32 v172, vcc, 0x20000, v170
	v_mfma_f32_16x16x32_bf16 v[42:45], v[206:209], v[244:247], v[42:45]
	ds_read_b128 v[244:247], v211 offset:64
	global_load_dwordx4 v[162:165], v[170:171], off
	s_nop 0
	s_waitcnt lgkmcnt(4)
	v_mfma_f32_16x16x32_bf16 v[54:57], v[190:193], v[194:197], v[54:57]
	global_load_dwordx4 v[166:169], v[166:167], off
	v_addc_co_u32_e32 v173, vcc, 0, v171, vcc
	v_mfma_f32_16x16x32_bf16 v[62:65], v[198:201], v[194:197], v[62:65]
	v_add_co_u32_e32 v174, vcc, 0x30000, v170
	s_nop 1
	v_mfma_f32_16x16x32_bf16 v[38:41], v[202:205], v[194:197], v[38:41]
	v_addc_co_u32_e32 v175, vcc, 0, v171, vcc
	global_load_dwordx4 v[170:173], v[172:173], off
	v_mfma_f32_16x16x32_bf16 v[46:49], v[206:209], v[194:197], v[46:49]
	ds_read_b128 v[194:197], v211 offset:2368
	s_nop 0
	global_load_dwordx4 v[174:177], v[174:175], off
	s_waitcnt lgkmcnt(4)
	v_mfma_f32_16x16x32_bf16 v[18:21], v[190:193], v[216:219], v[18:21]
	s_cmp_lg_u32 s0, 16
	s_waitcnt lgkmcnt(3)
	v_mfma_f32_16x16x32_bf16 v[22:25], v[190:193], v[236:239], v[22:25]
	ds_read_b128 v[190:193], v215 offset:39232
	v_mfma_f32_16x16x32_bf16 v[26:29], v[198:201], v[216:219], v[26:29]
	v_mfma_f32_16x16x32_bf16 v[30:33], v[198:201], v[236:239], v[30:33]
	ds_read_b128 v[198:201], v215 offset:41536
	v_mfma_f32_16x16x32_bf16 v[2:5], v[202:205], v[216:219], v[2:5]
	v_mfma_f32_16x16x32_bf16 v[6:9], v[202:205], v[236:239], v[6:9]
	ds_read_b128 v[202:205], v215 offset:43840
	v_mfma_f32_16x16x32_bf16 v[10:13], v[206:209], v[216:219], v[10:13]
	ds_read_b128 v[216:219], v211 offset:4672
	v_mfma_f32_16x16x32_bf16 v[14:17], v[206:209], v[236:239], v[14:17]
	ds_read_b128 v[206:209], v211 offset:6976
	ds_read_b128 v[236:239], v211 offset:9280
	s_waitcnt lgkmcnt(7)
	v_mfma_f32_16x16x32_bf16 v[114:117], v[240:243], v[244:247], v[114:117]
	s_waitcnt lgkmcnt(6)
	v_mfma_f32_16x16x32_bf16 v[118:121], v[240:243], v[194:197], v[118:121]
	s_waitcnt lgkmcnt(5)
	v_mfma_f32_16x16x32_bf16 v[122:125], v[190:193], v[244:247], v[122:125]
	v_mfma_f32_16x16x32_bf16 v[126:129], v[190:193], v[194:197], v[126:129]
	s_waitcnt lgkmcnt(4)
	v_mfma_f32_16x16x32_bf16 v[98:101], v[198:201], v[244:247], v[98:101]
	v_mfma_f32_16x16x32_bf16 v[102:105], v[198:201], v[194:197], v[102:105]
	s_waitcnt lgkmcnt(3)
	v_mfma_f32_16x16x32_bf16 v[106:109], v[202:205], v[244:247], v[106:109]
	ds_read_b128 v[244:247], v211 offset:11584
	v_mfma_f32_16x16x32_bf16 v[110:113], v[202:205], v[194:197], v[110:113]
	ds_read_b128 v[194:197], v211 offset:13888
	s_waitcnt lgkmcnt(4)
	v_mfma_f32_16x16x32_bf16 v[82:85], v[240:243], v[216:219], v[82:85]
	v_mfma_f32_16x16x32_bf16 v[90:93], v[190:193], v[216:219], v[90:93]
	v_mfma_f32_16x16x32_bf16 v[66:69], v[198:201], v[216:219], v[66:69]
	v_mfma_f32_16x16x32_bf16 v[74:77], v[202:205], v[216:219], v[74:77]
	ds_read_b128 v[216:219], v211 offset:16192
	s_waitcnt lgkmcnt(4)
	v_mfma_f32_16x16x32_bf16 v[86:89], v[240:243], v[206:209], v[86:89]
	v_mfma_f32_16x16x32_bf16 v[94:97], v[190:193], v[206:209], v[94:97]
	v_mfma_f32_16x16x32_bf16 v[70:73], v[198:201], v[206:209], v[70:73]
	v_mfma_f32_16x16x32_bf16 v[78:81], v[202:205], v[206:209], v[78:81]
	s_waitcnt lgkmcnt(3)
	v_mfma_f32_16x16x32_bf16 v[50:53], v[240:243], v[236:239], v[50:53]
	v_mfma_f32_16x16x32_bf16 v[58:61], v[190:193], v[236:239], v[58:61]
	v_mfma_f32_16x16x32_bf16 v[34:37], v[198:201], v[236:239], v[34:37]
	v_mfma_f32_16x16x32_bf16 v[42:45], v[202:205], v[236:239], v[42:45]
	s_waitcnt lgkmcnt(2)
	v_mfma_f32_16x16x32_bf16 v[54:57], v[240:243], v[244:247], v[54:57]
	v_mfma_f32_16x16x32_bf16 v[62:65], v[190:193], v[244:247], v[62:65]
	v_mfma_f32_16x16x32_bf16 v[38:41], v[198:201], v[244:247], v[38:41]
	v_mfma_f32_16x16x32_bf16 v[46:49], v[202:205], v[244:247], v[46:49]
	s_waitcnt lgkmcnt(1)
	v_mfma_f32_16x16x32_bf16 v[18:21], v[240:243], v[194:197], v[18:21]
	v_mfma_f32_16x16x32_bf16 v[26:29], v[190:193], v[194:197], v[26:29]
	v_mfma_f32_16x16x32_bf16 v[2:5], v[198:201], v[194:197], v[2:5]
	v_mfma_f32_16x16x32_bf16 v[10:13], v[202:205], v[194:197], v[10:13]
	s_waitcnt lgkmcnt(0)
	v_mfma_f32_16x16x32_bf16 v[22:25], v[240:243], v[216:219], v[22:25]
	v_mfma_f32_16x16x32_bf16 v[30:33], v[190:193], v[216:219], v[30:33]
	v_mfma_f32_16x16x32_bf16 v[6:9], v[198:201], v[216:219], v[6:9]
	v_mfma_f32_16x16x32_bf16 v[14:17], v[202:205], v[216:219], v[14:17]
	s_setprio 0
	s_cbranch_scc1 .Ltail_34
	s_add_i32 s2, s2, 1
	s_cmp_ge_i32 s2, s4
	s_cbranch_scc1 .Lz_34
	s_mul_i32 s0, s2, s82
	s_add_i32 s0, s0, s63
	s_mul_hi_i32 s1, s0, 0x2e8ba2e9
	s_lshr_b32 s6, s1, 31
	s_ashr_i32 s1, s1, 4
	s_add_i32 s1, s1, s6
	s_mul_i32 s6, s1, 0x58
	s_sub_i32 s0, s0, s6
	s_lshl_b32 s1, s1, 1
	s_and_b32 s6, s0, 1
	s_or_b32 s1, s6, s1
	v_readlane_b32 s6, v252, 35
	s_ashr_i32 s0, s0, 1
	s_sub_i32 s8, 0x7f, s1
	v_readlane_b32 s7, v252, 36
	s_and_b64 s[6:7], s[6:7], exec
	s_cselect_b32 s6, s8, s1
	s_ashr_i32 s7, s6, 31
	s_ashr_i32 s1, s0, 31
	s_lshl_b64 s[6:7], s[6:7], 19
	s_lshl_b64 s[0:1], s[0:1], 18
	v_lshl_add_u64 v[180:181], v[186:187], 0, s[6:7]
	v_lshl_add_u64 v[182:183], v[188:189], 0, s[0:1]

.LBB0_40:
	s_nop 7
	v_permlane16_swap_b32_e32 v114, v118
	v_permlane16_swap_b32_e32 v115, v119
	v_permlane16_swap_b32_e32 v116, v120
	v_permlane16_swap_b32_e32 v117, v121
	v_permlane16_swap_b32_e32 v122, v126
	v_permlane16_swap_b32_e32 v123, v127
	v_permlane16_swap_b32_e32 v124, v128
	v_permlane16_swap_b32_e32 v125, v129
	v_permlane32_swap_b32_e32 v114, v118
	v_permlane32_swap_b32_e32 v115, v119
	v_permlane32_swap_b32_e32 v116, v120
	v_permlane32_swap_b32_e32 v117, v121
	v_permlane32_swap_b32_e32 v122, v126
	v_permlane32_swap_b32_e32 v123, v127
	v_permlane32_swap_b32_e32 v124, v128
	v_permlane32_swap_b32_e32 v125, v129
	v_permlane16_swap_b32_e32 v98, v102
	v_permlane16_swap_b32_e32 v99, v103
	v_permlane16_swap_b32_e32 v100, v104
	v_permlane16_swap_b32_e32 v101, v105
	v_permlane16_swap_b32_e32 v106, v110
	v_permlane16_swap_b32_e32 v107, v111
	v_permlane16_swap_b32_e32 v108, v112
	v_permlane16_swap_b32_e32 v109, v113
	v_permlane32_swap_b32_e32 v98, v102
	v_permlane32_swap_b32_e32 v99, v103
	v_permlane32_swap_b32_e32 v100, v104
	v_permlane32_swap_b32_e32 v101, v105
	v_permlane32_swap_b32_e32 v106, v110
	v_permlane32_swap_b32_e32 v107, v111
	v_permlane32_swap_b32_e32 v108, v112
	v_permlane32_swap_b32_e32 v109, v113
	v_permlane16_swap_b32_e32 v82, v86
	v_permlane16_swap_b32_e32 v83, v87
	v_permlane16_swap_b32_e32 v84, v88
	v_permlane16_swap_b32_e32 v85, v89
	v_permlane16_swap_b32_e32 v90, v94
	v_permlane16_swap_b32_e32 v91, v95
	v_permlane16_swap_b32_e32 v92, v96
	v_permlane16_swap_b32_e32 v93, v97
	v_permlane32_swap_b32_e32 v82, v86
	v_permlane32_swap_b32_e32 v83, v87
	v_permlane32_swap_b32_e32 v84, v88
	v_permlane32_swap_b32_e32 v85, v89
	v_permlane32_swap_b32_e32 v90, v94
	v_permlane32_swap_b32_e32 v91, v95
	v_permlane32_swap_b32_e32 v92, v96
	v_permlane32_swap_b32_e32 v93, v97
	v_permlane16_swap_b32_e32 v66, v70
	v_permlane16_swap_b32_e32 v67, v71
	v_permlane16_swap_b32_e32 v68, v72
	v_permlane16_swap_b32_e32 v69, v73
	v_permlane16_swap_b32_e32 v74, v78
	v_permlane16_swap_b32_e32 v75, v79
	v_permlane16_swap_b32_e32 v76, v80
	v_permlane16_swap_b32_e32 v77, v81
	v_permlane32_swap_b32_e32 v66, v70
	v_permlane32_swap_b32_e32 v67, v71
	v_permlane32_swap_b32_e32 v68, v72
	v_permlane32_swap_b32_e32 v69, v73
	v_permlane32_swap_b32_e32 v74, v78
	v_permlane32_swap_b32_e32 v75, v79
	v_permlane32_swap_b32_e32 v76, v80
	v_permlane32_swap_b32_e32 v77, v81
	v_permlane16_swap_b32_e32 v50, v54
	v_permlane16_swap_b32_e32 v51, v55
	v_permlane16_swap_b32_e32 v52, v56
	v_permlane16_swap_b32_e32 v53, v57
	v_permlane16_swap_b32_e32 v58, v62
	v_permlane16_swap_b32_e32 v59, v63
	v_permlane16_swap_b32_e32 v60, v64
	v_permlane16_swap_b32_e32 v61, v65
	v_permlane32_swap_b32_e32 v50, v54
	v_permlane32_swap_b32_e32 v51, v55
	v_permlane32_swap_b32_e32 v52, v56
	v_permlane32_swap_b32_e32 v53, v57
	v_permlane32_swap_b32_e32 v58, v62
	v_permlane32_swap_b32_e32 v59, v63
	v_permlane32_swap_b32_e32 v60, v64
	v_permlane32_swap_b32_e32 v61, v65
	v_permlane16_swap_b32_e32 v34, v38
	v_permlane16_swap_b32_e32 v35, v39
	v_permlane16_swap_b32_e32 v36, v40
	v_permlane16_swap_b32_e32 v37, v41
	v_permlane16_swap_b32_e32 v42, v46
	v_permlane16_swap_b32_e32 v43, v47
	v_permlane16_swap_b32_e32 v44, v48
	v_permlane16_swap_b32_e32 v45, v49
	v_permlane32_swap_b32_e32 v34, v38
	v_permlane32_swap_b32_e32 v35, v39
	v_permlane32_swap_b32_e32 v36, v40
	v_permlane32_swap_b32_e32 v37, v41
	v_permlane32_swap_b32_e32 v42, v46
	v_permlane32_swap_b32_e32 v43, v47
	v_permlane32_swap_b32_e32 v44, v48
	v_permlane32_swap_b32_e32 v45, v49
	v_permlane16_swap_b32_e32 v18, v22
	v_permlane16_swap_b32_e32 v19, v23
	v_permlane16_swap_b32_e32 v20, v24
	v_permlane16_swap_b32_e32 v21, v25
	v_permlane16_swap_b32_e32 v26, v30
	v_permlane16_swap_b32_e32 v27, v31
	v_permlane16_swap_b32_e32 v28, v32
	v_permlane16_swap_b32_e32 v29, v33
	v_permlane32_swap_b32_e32 v18, v22
	v_permlane32_swap_b32_e32 v19, v23
	v_permlane32_swap_b32_e32 v20, v24
	v_permlane32_swap_b32_e32 v21, v25
	v_permlane32_swap_b32_e32 v26, v30
	v_permlane32_swap_b32_e32 v27, v31
	v_permlane32_swap_b32_e32 v28, v32
	v_permlane32_swap_b32_e32 v29, v33
	v_permlane16_swap_b32_e32 v2, v6
	v_permlane16_swap_b32_e32 v3, v7
	v_permlane16_swap_b32_e32 v4, v8
	v_permlane16_swap_b32_e32 v5, v9
	v_permlane16_swap_b32_e32 v10, v14
	v_permlane16_swap_b32_e32 v11, v15
	v_permlane16_swap_b32_e32 v12, v16
	v_permlane16_swap_b32_e32 v13, v17
	v_permlane32_swap_b32_e32 v2, v6
	v_permlane32_swap_b32_e32 v3, v7
	v_permlane32_swap_b32_e32 v4, v8
	v_permlane32_swap_b32_e32 v5, v9
	v_permlane32_swap_b32_e32 v10, v14
	v_permlane32_swap_b32_e32 v11, v15
	v_permlane32_swap_b32_e32 v12, v16
	v_permlane32_swap_b32_e32 v13, v17
	s_mul_i32 s1, s5, s82
	s_add_i32 s1, s1, s63
	s_mul_hi_i32 s3, s1, 0x2e8ba2e9
	s_lshr_b32 s6, s3, 31
	s_ashr_i32 s3, s3, 4
	s_add_i32 s3, s3, s6
	s_mul_i32 s6, s3, 0x58
	s_sub_i32 s1, s1, s6
	s_lshl_b32 s3, s3, 1
	s_and_b32 s6, s1, 1
	s_or_b32 s3, s6, s3
	v_readlane_b32 s6, v252, 35
	s_sub_i32 s8, 0x7f, s3
	v_readlane_b32 s7, v252, 36
	s_and_b64 s[6:7], s[6:7], exec
	s_cselect_b32 s6, s8, s3
	v_mov_b32_e32 v0, v222
	s_ashr_i32 s7, s6, 31
	v_and_b32_e32 v192, 0xffffff80, v0
	s_lshl_b64 s[6:7], s[6:7], 8
	v_ashrrev_i32_e32 v193, 31, v192
	s_lshl_b32 s1, s1, 6
	v_lshl_add_u64 v[192:193], s[6:7], 0, v[192:193]
	v_readlane_b32 s6, v252, 45
	s_and_b32 s1, s1, 0xffffff80
	v_readlane_b32 s7, v252, 46
	v_and_or_b32 v185, v0, 64, s1
	v_lshrrev_b32_e32 v190, 3, v0
	v_and_or_b32 v0, v0, 31, v192
	v_mov_b64_e32 v[194:195], s[6:7]
	s_movk_i32 s1, 0x1600
	v_mad_u64_u32 v[194:195], s[6:7], v0, s1, v[194:195]
	v_mul_f32_e32 v0, 0xbfb8aa3b, v114
	v_exp_f32_e32 v0, v0
	v_mad_i32_i24 v195, v193, s1, v195
	v_ashrrev_i32_e32 v185, 1, v185
	v_and_or_b32 v190, v190, 4, v185
	v_add_f32_e32 v0, 1.0, v0
	v_rcp_f32_e32 v192, v0
	v_mul_f32_e32 v0, 0xbfb8aa3b, v115
	v_exp_f32_e32 v0, v0
	v_ashrrev_i32_e32 v191, 31, v190
	v_lshl_add_u64 v[190:191], v[190:191], 1, v[194:195]
	s_mov_b32 s1, 0x2c000
	v_add_f32_e32 v0, 1.0, v0
	v_rcp_f32_e32 v193, v0
	v_mul_f32_e32 v0, 0xbfb8aa3b, v116
	v_exp_f32_e32 v0, v0
	s_mov_b64 s[6:7], 0x2c000
	v_pk_mul_f32 v[114:115], v[114:115], v[192:193]
	s_mov_b32 s3, 0
	v_add_f32_e32 v0, 1.0, v0
	v_pk_mul_f32 v[98:99], v[98:99], v[114:115]
	v_rcp_f32_e32 v114, v0
	v_mul_f32_e32 v0, 0xbfb8aa3b, v117
	v_exp_f32_e32 v0, v0
	v_cvt_pk_bf16_f32 v98, v98, v99
	s_add_i32 s5, s5, 1
	v_add_f32_e32 v0, 1.0, v0
	v_rcp_f32_e32 v115, v0
	v_mul_f32_e32 v0, 0xbfb8aa3b, v118
	v_exp_f32_e32 v0, v0
	v_pk_mul_f32 v[114:115], v[116:117], v[114:115]
	s_nop 0
	v_pk_mul_f32 v[100:101], v[100:101], v[114:115]
	v_add_f32_e32 v0, 1.0, v0
	v_cvt_pk_bf16_f32 v99, v100, v101
	global_store_dwordx2 v[190:191], v[98:99], off
	v_rcp_f32_e32 v98, v0
	v_mul_f32_e32 v0, 0xbfb8aa3b, v119
	v_exp_f32_e32 v0, v0
	v_mov_b32_e32 v114, 0
	v_mov_b32_e32 v115, v114
	v_mov_b32_e32 v116, v114
	v_add_f32_e32 v0, 1.0, v0
	v_rcp_f32_e32 v99, v0
	v_mul_f32_e32 v0, 0xbfb8aa3b, v120
	v_exp_f32_e32 v0, v0
	v_mov_b32_e32 v117, v114
	v_pk_mul_f32 v[98:99], v[118:119], v[98:99]
	v_mov_b32_e32 v118, v114
	v_add_f32_e32 v0, 1.0, v0
	v_rcp_f32_e32 v100, v0
	v_mul_f32_e32 v0, 0xbfb8aa3b, v121
	v_exp_f32_e32 v0, v0
	v_pk_mul_f32 v[98:99], v[102:103], v[98:99]
	v_mov_b32_e32 v119, v114
	v_cvt_pk_bf16_f32 v98, v98, v99
	v_add_f32_e32 v0, 1.0, v0
	v_rcp_f32_e32 v101, v0
	v_mul_f32_e32 v0, 0xbfb8aa3b, v122
	v_exp_f32_e32 v0, v0
	v_mov_b32_e32 v102, v114
	v_pk_mul_f32 v[100:101], v[120:121], v[100:101]
	v_mov_b32_e32 v120, v114
	v_pk_mul_f32 v[100:101], v[104:105], v[100:101]
	v_add_f32_e32 v0, 1.0, v0
	v_cvt_pk_bf16_f32 v99, v100, v101
	global_store_dwordx2 v[190:191], v[98:99], off offset:16
	v_rcp_f32_e32 v98, v0
	v_mul_f32_e32 v0, 0xbfb8aa3b, v123
	v_exp_f32_e32 v0, v0
	v_mov_b32_e32 v121, v114
	v_mov_b32_e32 v103, v114
	v_mov_b32_e32 v104, v114
	v_add_f32_e32 v0, 1.0, v0
	v_rcp_f32_e32 v99, v0
	v_mul_f32_e32 v0, 0xbfb8aa3b, v124
	v_exp_f32_e32 v0, v0
	v_mov_b32_e32 v105, v114
	v_pk_mul_f32 v[98:99], v[122:123], v[98:99]
	v_mov_b32_e32 v122, v114
	v_add_f32_e32 v0, 1.0, v0
	v_rcp_f32_e32 v100, v0
	v_mul_f32_e32 v0, 0xbfb8aa3b, v125
	v_exp_f32_e32 v0, v0
	v_pk_mul_f32 v[98:99], v[106:107], v[98:99]
	v_mov_b32_e32 v123, v114
	v_cvt_pk_bf16_f32 v98, v98, v99
	v_add_f32_e32 v0, 1.0, v0
	v_rcp_f32_e32 v101, v0
	v_mul_f32_e32 v0, 0xbfb8aa3b, v126
	v_exp_f32_e32 v0, v0
	v_mov_b32_e32 v106, v114
	v_pk_mul_f32 v[100:101], v[124:125], v[100:101]
	v_mov_b32_e32 v124, v114
	v_pk_mul_f32 v[100:101], v[108:109], v[100:101]
	v_add_f32_e32 v0, 1.0, v0
	v_cvt_pk_bf16_f32 v99, v100, v101
	global_store_dwordx2 v[190:191], v[98:99], off offset:32
	v_rcp_f32_e32 v98, v0
	v_mul_f32_e32 v0, 0xbfb8aa3b, v127
	v_exp_f32_e32 v0, v0
	v_mov_b32_e32 v125, v114
	v_mov_b32_e32 v107, v114
	v_mov_b32_e32 v108, v114
	v_add_f32_e32 v0, 1.0, v0
	v_rcp_f32_e32 v99, v0
	v_mul_f32_e32 v0, 0xbfb8aa3b, v128
	v_exp_f32_e32 v0, v0
	v_mov_b32_e32 v109, v114
	v_pk_mul_f32 v[98:99], v[126:127], v[98:99]
	v_mov_b32_e32 v126, v114
	v_add_f32_e32 v0, 1.0, v0
	v_rcp_f32_e32 v100, v0
	v_mul_f32_e32 v0, 0xbfb8aa3b, v129
	v_exp_f32_e32 v0, v0
	v_pk_mul_f32 v[98:99], v[110:111], v[98:99]
	v_mov_b32_e32 v127, v114
	v_cvt_pk_bf16_f32 v98, v98, v99
	v_add_f32_e32 v0, 1.0, v0
	v_rcp_f32_e32 v101, v0
	v_mul_f32_e32 v0, 0xbfb8aa3b, v82
	v_exp_f32_e32 v0, v0
	v_mov_b32_e32 v110, v114
	v_pk_mul_f32 v[100:101], v[128:129], v[100:101]
	v_mov_b32_e32 v128, v114
	v_pk_mul_f32 v[100:101], v[112:113], v[100:101]
	v_add_f32_e32 v0, 1.0, v0
	v_cvt_pk_bf16_f32 v99, v100, v101
	v_rcp_f32_e32 v100, v0
	v_mul_f32_e32 v0, 0xbfb8aa3b, v83
	v_exp_f32_e32 v0, v0
	global_store_dwordx2 v[190:191], v[98:99], off offset:48
	v_lshl_add_u64 v[98:99], v[190:191], 0, s[6:7]
	s_mov_b64 s[6:7], 0x58000
	v_add_f32_e32 v0, 1.0, v0
	v_rcp_f32_e32 v101, v0
	v_mul_f32_e32 v0, 0xbfb8aa3b, v84
	v_exp_f32_e32 v0, v0
	v_mov_b32_e32 v129, v114
	v_pk_mul_f32 v[82:83], v[82:83], v[100:101]
	v_mov_b32_e32 v100, v114
	v_add_f32_e32 v0, 1.0, v0
	v_pk_mul_f32 v[66:67], v[66:67], v[82:83]
	v_rcp_f32_e32 v82, v0
	v_mul_f32_e32 v0, 0xbfb8aa3b, v85
	v_exp_f32_e32 v0, v0
	v_cvt_pk_bf16_f32 v66, v66, v67
	v_mov_b32_e32 v101, v114
	v_mov_b32_e32 v111, v114
	v_add_f32_e32 v0, 1.0, v0
	v_rcp_f32_e32 v83, v0
	v_mul_f32_e32 v0, 0xbfb8aa3b, v86
	v_exp_f32_e32 v0, v0
	v_mov_b32_e32 v112, v114
	v_pk_mul_f32 v[82:83], v[84:85], v[82:83]
	v_mov_b32_e32 v113, v114
	v_pk_mul_f32 v[68:69], v[68:69], v[82:83]
	v_add_f32_e32 v0, 1.0, v0
	v_cvt_pk_bf16_f32 v67, v68, v69
	v_add_co_u32_e32 v68, vcc, s1, v190
	s_mov_b32 s1, 0x58000
	s_nop 0
	v_addc_co_u32_e32 v69, vcc, 0, v191, vcc
	global_store_dwordx2 v[68:69], v[66:67], off
	v_rcp_f32_e32 v66, v0
	v_mul_f32_e32 v0, 0xbfb8aa3b, v87
	v_exp_f32_e32 v0, v0
	v_mov_b32_e32 v82, v114
	v_mov_b32_e32 v83, v114
	v_mov_b32_e32 v84, v114
	v_add_f32_e32 v0, 1.0, v0
	v_rcp_f32_e32 v67, v0
	v_mul_f32_e32 v0, 0xbfb8aa3b, v88
	v_exp_f32_e32 v0, v0
	v_mov_b32_e32 v85, v114
	v_pk_mul_f32 v[66:67], v[86:87], v[66:67]
	v_mov_b32_e32 v86, v114
	v_add_f32_e32 v0, 1.0, v0
	v_rcp_f32_e32 v68, v0
	v_mul_f32_e32 v0, 0xbfb8aa3b, v89
	v_exp_f32_e32 v0, v0
	v_pk_mul_f32 v[66:67], v[70:71], v[66:67]
	v_mov_b32_e32 v87, v114
	v_cvt_pk_bf16_f32 v66, v66, v67
	v_add_f32_e32 v0, 1.0, v0
	v_rcp_f32_e32 v69, v0
	v_mul_f32_e32 v0, 0xbfb8aa3b, v90
	v_exp_f32_e32 v0, v0
	v_mov_b32_e32 v70, v114
	v_pk_mul_f32 v[68:69], v[88:89], v[68:69]
	v_mov_b32_e32 v88, v114
	v_pk_mul_f32 v[68:69], v[72:73], v[68:69]
	v_add_f32_e32 v0, 1.0, v0
	v_cvt_pk_bf16_f32 v67, v68, v69
	global_store_dwordx2 v[98:99], v[66:67], off offset:16
	v_rcp_f32_e32 v66, v0
	v_mul_f32_e32 v0, 0xbfb8aa3b, v91
	v_exp_f32_e32 v0, v0
	v_mov_b32_e32 v89, v114
	v_mov_b32_e32 v71, v114
	v_mov_b32_e32 v72, v114
	v_add_f32_e32 v0, 1.0, v0
	v_rcp_f32_e32 v67, v0
	v_mul_f32_e32 v0, 0xbfb8aa3b, v92
	v_exp_f32_e32 v0, v0
	v_mov_b32_e32 v73, v114
	v_pk_mul_f32 v[66:67], v[90:91], v[66:67]
	v_mov_b32_e32 v90, v114
	v_add_f32_e32 v0, 1.0, v0
	v_rcp_f32_e32 v68, v0
	v_mul_f32_e32 v0, 0xbfb8aa3b, v93
	v_exp_f32_e32 v0, v0
	v_pk_mul_f32 v[66:67], v[74:75], v[66:67]
	v_mov_b32_e32 v91, v114
	v_cvt_pk_bf16_f32 v66, v66, v67
	v_add_f32_e32 v0, 1.0, v0
	v_rcp_f32_e32 v69, v0
	v_mul_f32_e32 v0, 0xbfb8aa3b, v94
	v_exp_f32_e32 v0, v0
	v_mov_b32_e32 v74, v114
	v_pk_mul_f32 v[68:69], v[92:93], v[68:69]
	v_mov_b32_e32 v92, v114
	v_pk_mul_f32 v[68:69], v[76:77], v[68:69]
	v_add_f32_e32 v0, 1.0, v0
	v_cvt_pk_bf16_f32 v67, v68, v69
	global_store_dwordx2 v[98:99], v[66:67], off offset:32
	v_rcp_f32_e32 v66, v0
	v_mul_f32_e32 v0, 0xbfb8aa3b, v95
	v_exp_f32_e32 v0, v0
	v_mov_b32_e32 v93, v114
	v_mov_b32_e32 v75, v114
	v_mov_b32_e32 v76, v114
	v_add_f32_e32 v0, 1.0, v0
	v_rcp_f32_e32 v67, v0
	v_mul_f32_e32 v0, 0xbfb8aa3b, v96
	v_exp_f32_e32 v0, v0
	v_mov_b32_e32 v77, v114
	v_pk_mul_f32 v[66:67], v[94:95], v[66:67]
	v_mov_b32_e32 v94, v114
	v_add_f32_e32 v0, 1.0, v0
	v_rcp_f32_e32 v68, v0
	v_mul_f32_e32 v0, 0xbfb8aa3b, v97
	v_exp_f32_e32 v0, v0
	v_pk_mul_f32 v[66:67], v[78:79], v[66:67]
	v_mov_b32_e32 v95, v114
	v_cvt_pk_bf16_f32 v66, v66, v67
	v_add_f32_e32 v0, 1.0, v0
	v_rcp_f32_e32 v69, v0
	v_mul_f32_e32 v0, 0xbfb8aa3b, v50
	v_exp_f32_e32 v0, v0
	v_mov_b32_e32 v78, v114
	v_pk_mul_f32 v[68:69], v[96:97], v[68:69]
	v_mov_b32_e32 v96, v114
	v_pk_mul_f32 v[68:69], v[80:81], v[68:69]
	v_add_f32_e32 v0, 1.0, v0
	v_cvt_pk_bf16_f32 v67, v68, v69
	v_rcp_f32_e32 v68, v0
	v_mul_f32_e32 v0, 0xbfb8aa3b, v51
	v_exp_f32_e32 v0, v0
	global_store_dwordx2 v[98:99], v[66:67], off offset:48
	v_lshl_add_u64 v[66:67], v[190:191], 0, s[6:7]
	s_mov_b64 s[6:7], 0x84000
	v_add_f32_e32 v0, 1.0, v0
	v_rcp_f32_e32 v69, v0
	v_mul_f32_e32 v0, 0xbfb8aa3b, v52
	v_exp_f32_e32 v0, v0
	v_mov_b32_e32 v98, v114
	v_pk_mul_f32 v[50:51], v[50:51], v[68:69]
	v_mov_b32_e32 v99, v114
	v_add_f32_e32 v0, 1.0, v0
	v_pk_mul_f32 v[34:35], v[34:35], v[50:51]
	v_rcp_f32_e32 v50, v0
	v_mul_f32_e32 v0, 0xbfb8aa3b, v53
	v_exp_f32_e32 v0, v0
	v_cvt_pk_bf16_f32 v34, v34, v35
	v_mov_b32_e32 v97, v114
	v_mov_b32_e32 v68, v114
	v_add_f32_e32 v0, 1.0, v0
	v_rcp_f32_e32 v51, v0
	v_mul_f32_e32 v0, 0xbfb8aa3b, v54
	v_exp_f32_e32 v0, v0
	v_mov_b32_e32 v69, v114
	v_pk_mul_f32 v[50:51], v[52:53], v[50:51]
	v_mov_b32_e32 v79, v114
	v_pk_mul_f32 v[36:37], v[36:37], v[50:51]
	v_add_f32_e32 v0, 1.0, v0
	v_cvt_pk_bf16_f32 v35, v36, v37
	v_add_co_u32_e32 v36, vcc, s1, v190
	s_mov_b32 s1, 0x84000
	s_nop 0
	v_addc_co_u32_e32 v37, vcc, 0, v191, vcc
	global_store_dwordx2 v[36:37], v[34:35], off
	v_rcp_f32_e32 v34, v0
	v_mul_f32_e32 v0, 0xbfb8aa3b, v55
	v_exp_f32_e32 v0, v0
	v_mov_b32_e32 v80, v114
	v_mov_b32_e32 v81, v114
	v_mov_b32_e32 v50, v114
	v_add_f32_e32 v0, 1.0, v0
	v_rcp_f32_e32 v35, v0
	v_mul_f32_e32 v0, 0xbfb8aa3b, v56
	v_exp_f32_e32 v0, v0
	v_mov_b32_e32 v51, v114
	v_pk_mul_f32 v[34:35], v[54:55], v[34:35]
	v_mov_b32_e32 v52, v114
	v_add_f32_e32 v0, 1.0, v0
	v_rcp_f32_e32 v36, v0
	v_mul_f32_e32 v0, 0xbfb8aa3b, v57
	v_exp_f32_e32 v0, v0
	v_pk_mul_f32 v[34:35], v[38:39], v[34:35]
	v_mov_b32_e32 v53, v114
	v_cvt_pk_bf16_f32 v34, v34, v35
	v_add_f32_e32 v0, 1.0, v0
	v_rcp_f32_e32 v37, v0
	v_mul_f32_e32 v0, 0xbfb8aa3b, v58
	v_exp_f32_e32 v0, v0
	v_mov_b32_e32 v54, v114
	v_pk_mul_f32 v[36:37], v[56:57], v[36:37]
	v_mov_b32_e32 v55, v114
	v_pk_mul_f32 v[36:37], v[40:41], v[36:37]
	v_add_f32_e32 v0, 1.0, v0
	v_cvt_pk_bf16_f32 v35, v36, v37
	global_store_dwordx2 v[66:67], v[34:35], off offset:16
	v_rcp_f32_e32 v34, v0
	v_mul_f32_e32 v0, 0xbfb8aa3b, v59
	v_exp_f32_e32 v0, v0
	v_mov_b32_e32 v56, v114
	v_mov_b32_e32 v57, v114
	v_mov_b32_e32 v38, v114
	v_add_f32_e32 v0, 1.0, v0
	v_rcp_f32_e32 v35, v0
	v_mul_f32_e32 v0, 0xbfb8aa3b, v60
	v_exp_f32_e32 v0, v0
	v_mov_b32_e32 v39, v114
	v_pk_mul_f32 v[34:35], v[58:59], v[34:35]
	v_mov_b32_e32 v58, v114
	v_add_f32_e32 v0, 1.0, v0
	v_rcp_f32_e32 v36, v0
	v_mul_f32_e32 v0, 0xbfb8aa3b, v61
	v_exp_f32_e32 v0, v0
	v_pk_mul_f32 v[34:35], v[42:43], v[34:35]
	v_mov_b32_e32 v59, v114
	v_cvt_pk_bf16_f32 v34, v34, v35
	v_add_f32_e32 v0, 1.0, v0
	v_rcp_f32_e32 v37, v0
	v_mul_f32_e32 v0, 0xbfb8aa3b, v62
	v_exp_f32_e32 v0, v0
	v_mov_b32_e32 v40, v114
	v_pk_mul_f32 v[36:37], v[60:61], v[36:37]
	v_mov_b32_e32 v60, v114
	v_pk_mul_f32 v[36:37], v[44:45], v[36:37]
	v_add_f32_e32 v0, 1.0, v0
	v_cvt_pk_bf16_f32 v35, v36, v37
	global_store_dwordx2 v[66:67], v[34:35], off offset:32
	v_rcp_f32_e32 v34, v0
	v_mul_f32_e32 v0, 0xbfb8aa3b, v63
	v_exp_f32_e32 v0, v0
	v_mov_b32_e32 v61, v114
	v_mov_b32_e32 v41, v114
	v_mov_b32_e32 v42, v114
	v_add_f32_e32 v0, 1.0, v0
	v_rcp_f32_e32 v35, v0
	v_mul_f32_e32 v0, 0xbfb8aa3b, v64
	v_exp_f32_e32 v0, v0
	v_mov_b32_e32 v43, v114
	v_pk_mul_f32 v[34:35], v[62:63], v[34:35]
	v_mov_b32_e32 v62, v114
	v_add_f32_e32 v0, 1.0, v0
	v_rcp_f32_e32 v36, v0
	v_mul_f32_e32 v0, 0xbfb8aa3b, v65
	v_exp_f32_e32 v0, v0
	v_pk_mul_f32 v[34:35], v[46:47], v[34:35]
	v_mov_b32_e32 v63, v114
	v_cvt_pk_bf16_f32 v34, v34, v35
	v_add_f32_e32 v0, 1.0, v0
	v_rcp_f32_e32 v37, v0
	v_mul_f32_e32 v0, 0xbfb8aa3b, v18
	v_exp_f32_e32 v0, v0
	v_mov_b32_e32 v44, v114
	v_pk_mul_f32 v[36:37], v[64:65], v[36:37]
	v_mov_b32_e32 v64, v114
	v_pk_mul_f32 v[36:37], v[48:49], v[36:37]
	v_add_f32_e32 v0, 1.0, v0
	v_cvt_pk_bf16_f32 v35, v36, v37
	v_rcp_f32_e32 v36, v0
	v_mul_f32_e32 v0, 0xbfb8aa3b, v19
	v_exp_f32_e32 v0, v0
	global_store_dwordx2 v[66:67], v[34:35], off offset:48
	v_lshl_add_u64 v[34:35], v[190:191], 0, s[6:7]
	v_mov_b32_e32 v66, v114
	v_add_f32_e32 v0, 1.0, v0
	v_rcp_f32_e32 v37, v0
	v_mul_f32_e32 v0, 0xbfb8aa3b, v20
	v_exp_f32_e32 v0, v0
	v_mov_b32_e32 v67, v114
	v_pk_mul_f32 v[18:19], v[18:19], v[36:37]
	v_mov_b32_e32 v65, v114
	v_add_f32_e32 v0, 1.0, v0
	v_pk_mul_f32 v[2:3], v[2:3], v[18:19]
	v_rcp_f32_e32 v18, v0
	v_mul_f32_e32 v0, 0xbfb8aa3b, v21
	v_exp_f32_e32 v0, v0
	v_cvt_pk_bf16_f32 v2, v2, v3
	v_mov_b32_e32 v36, v114
	v_mov_b32_e32 v37, v114
	v_add_f32_e32 v0, 1.0, v0
	v_rcp_f32_e32 v19, v0
	v_mul_f32_e32 v0, 0xbfb8aa3b, v22
	v_exp_f32_e32 v0, v0
	v_mov_b32_e32 v45, v114
	v_pk_mul_f32 v[18:19], v[20:21], v[18:19]
	v_mov_b32_e32 v46, v114
	v_pk_mul_f32 v[4:5], v[4:5], v[18:19]
	v_add_f32_e32 v0, 1.0, v0
	v_cvt_pk_bf16_f32 v3, v4, v5
	v_add_co_u32_e32 v4, vcc, s1, v190
	v_mov_b32_e32 v47, v114
	s_nop 0
	v_addc_co_u32_e32 v5, vcc, 0, v191, vcc
	global_store_dwordx2 v[4:5], v[2:3], off
	v_rcp_f32_e32 v2, v0
	v_mul_f32_e32 v0, 0xbfb8aa3b, v23
	v_exp_f32_e32 v0, v0
	v_mov_b32_e32 v48, v114
	v_mov_b32_e32 v49, v114
	v_mov_b32_e32 v18, v114
	v_add_f32_e32 v0, 1.0, v0
	v_rcp_f32_e32 v3, v0
	v_mul_f32_e32 v0, 0xbfb8aa3b, v24
	v_exp_f32_e32 v0, v0
	v_mov_b32_e32 v19, v114
	v_pk_mul_f32 v[2:3], v[22:23], v[2:3]
	v_mov_b32_e32 v20, v114
	v_add_f32_e32 v0, 1.0, v0
	v_rcp_f32_e32 v4, v0
	v_mul_f32_e32 v0, 0xbfb8aa3b, v25
	v_exp_f32_e32 v0, v0
	v_pk_mul_f32 v[2:3], v[6:7], v[2:3]
	v_mov_b32_e32 v21, v114
	v_cvt_pk_bf16_f32 v2, v2, v3
	v_add_f32_e32 v0, 1.0, v0
	v_rcp_f32_e32 v5, v0
	v_mul_f32_e32 v0, 0xbfb8aa3b, v26
	v_exp_f32_e32 v0, v0
	v_mov_b32_e32 v22, v114
	v_pk_mul_f32 v[4:5], v[24:25], v[4:5]
	v_mov_b32_e32 v23, v114
	v_pk_mul_f32 v[4:5], v[8:9], v[4:5]
	v_add_f32_e32 v0, 1.0, v0
	v_cvt_pk_bf16_f32 v3, v4, v5
	global_store_dwordx2 v[34:35], v[2:3], off offset:16
	v_rcp_f32_e32 v2, v0
	v_mul_f32_e32 v0, 0xbfb8aa3b, v27
	v_exp_f32_e32 v0, v0
	v_mov_b32_e32 v24, v114
	v_mov_b32_e32 v25, v114
	v_mov_b32_e32 v6, v114
	v_add_f32_e32 v0, 1.0, v0
	v_rcp_f32_e32 v3, v0
	v_mul_f32_e32 v0, 0xbfb8aa3b, v28
	v_exp_f32_e32 v0, v0
	v_mov_b32_e32 v7, v114
	v_pk_mul_f32 v[2:3], v[26:27], v[2:3]
	v_mov_b32_e32 v26, v114
	v_add_f32_e32 v0, 1.0, v0
	v_rcp_f32_e32 v4, v0
	v_mul_f32_e32 v0, 0xbfb8aa3b, v29
	v_exp_f32_e32 v0, v0
	v_pk_mul_f32 v[2:3], v[10:11], v[2:3]
	v_mov_b32_e32 v27, v114
	v_cvt_pk_bf16_f32 v2, v2, v3
	v_add_f32_e32 v0, 1.0, v0
	v_rcp_f32_e32 v5, v0
	v_mul_f32_e32 v0, 0xbfb8aa3b, v30
	v_exp_f32_e32 v0, v0
	v_mov_b32_e32 v8, v114
	v_pk_mul_f32 v[4:5], v[28:29], v[4:5]
	v_mov_b32_e32 v28, v114
	v_pk_mul_f32 v[4:5], v[12:13], v[4:5]
	v_add_f32_e32 v0, 1.0, v0
	v_cvt_pk_bf16_f32 v3, v4, v5
	global_store_dwordx2 v[34:35], v[2:3], off offset:32
	v_rcp_f32_e32 v2, v0
	v_mul_f32_e32 v0, 0xbfb8aa3b, v31
	v_exp_f32_e32 v0, v0
	v_mov_b32_e32 v29, v114
	v_mov_b32_e32 v9, v114
	v_mov_b32_e32 v10, v114
	v_add_f32_e32 v0, 1.0, v0
	v_rcp_f32_e32 v3, v0
	v_mul_f32_e32 v0, 0xbfb8aa3b, v32
	v_exp_f32_e32 v0, v0
	v_mov_b32_e32 v11, v114
	v_pk_mul_f32 v[2:3], v[30:31], v[2:3]
	v_mov_b32_e32 v30, v114
	v_add_f32_e32 v0, 1.0, v0
	v_rcp_f32_e32 v4, v0
	v_mul_f32_e32 v0, 0xbfb8aa3b, v33
	v_exp_f32_e32 v0, v0
	v_pk_mul_f32 v[2:3], v[14:15], v[2:3]
	v_mov_b32_e32 v31, v114
	v_cvt_pk_bf16_f32 v2, v2, v3
	v_add_f32_e32 v0, 1.0, v0
	v_rcp_f32_e32 v5, v0
	v_mov_b32_e32 v12, v114
	v_mov_b32_e32 v13, v114
	v_mov_b32_e32 v14, v114
	v_pk_mul_f32 v[4:5], v[32:33], v[4:5]
	v_mov_b32_e32 v32, v114
	v_pk_mul_f32 v[4:5], v[16:17], v[4:5]
	v_mov_b32_e32 v33, v114
	v_cvt_pk_bf16_f32 v3, v4, v5
	global_store_dwordx2 v[34:35], v[2:3], off offset:48
	v_mov_b32_e32 v34, v114
	v_mov_b32_e32 v35, v114
	v_mov_b32_e32 v2, v114
	v_mov_b32_e32 v3, v114
	v_mov_b32_e32 v4, v114
	v_mov_b32_e32 v5, v114
	v_mov_b32_e32 v15, v114
	v_mov_b32_e32 v16, v114
	v_mov_b32_e32 v17, v114
	s_cmp_ge_i32 s5, s4
	s_cbranch_scc0 .LBB0_36

.LcL_62:
	s_waitcnt lgkmcnt(0)
	s_barrier
	s_setprio 2
	v_bfe_u32 v221, v222, 5, 1
	v_bfe_u32 v248, v222, 4, 1
	v_lshl_add_u32 v211, v221, 4, v178
	v_lshl_add_u32 v215, v221, 4, v179
	v_mul_u32_u24_e32 v221, 0x8f0, v248
	v_mul_u32_u24_e32 v248, 0x8f8, v248
	v_sub_u32_e32 v213, v211, v248
	v_sub_u32_e32 v220, v215, v248
	v_sub_u32_e32 v211, v211, v221
	v_sub_u32_e32 v215, v215, v221
	ds_read_b128 v[190:193], v215 offset:36864
	ds_read_b128 v[194:197], v211
	ds_read_b128 v[198:201], v215 offset:39168
	ds_read_b128 v[202:205], v215 offset:41472
	ds_read_b128 v[206:209], v215 offset:43776
	ds_read_b128 v[216:219], v211 offset:2304
	ds_read_b128 v[236:239], v211 offset:4608
	ds_read_b128 v[240:243], v211 offset:6912
	ds_read_b128 v[244:247], v211 offset:9216
	s_waitcnt lgkmcnt(7)
	v_mfma_f32_16x16x32_bf16 v[114:117], v[190:193], v[194:197], v[114:117]
	s_ashr_i32 s1, s0, 31
	s_lshl_b64 s[4:5], s[0:1], 7
	s_waitcnt lgkmcnt(6)
	v_mfma_f32_16x16x32_bf16 v[122:125], v[198:201], v[194:197], v[122:125]
	v_lshl_add_u64 v[154:155], v[180:181], 0, s[4:5]
	v_add_co_u32_e32 v130, vcc, 0x10000, v154
	s_waitcnt lgkmcnt(5)
	v_mfma_f32_16x16x32_bf16 v[98:101], v[202:205], v[194:197], v[98:101]
	v_lshl_add_u64 v[170:171], v[182:183], 0, s[4:5]
	s_nop 0
	s_waitcnt lgkmcnt(4)
	v_mfma_f32_16x16x32_bf16 v[106:109], v[206:209], v[194:197], v[106:109]
	ds_read_b128 v[194:197], v211 offset:11520
	v_addc_co_u32_e32 v131, vcc, 0, v155, vcc
	v_add_co_u32_e32 v134, vcc, 0x20000, v154
	s_waitcnt lgkmcnt(4)
	v_mfma_f32_16x16x32_bf16 v[118:121], v[190:193], v[216:219], v[118:121]
	global_load_dwordx4 v[142:145], v[154:155], off
	s_nop 0
	v_mfma_f32_16x16x32_bf16 v[126:129], v[198:201], v[216:219], v[126:129]
	global_load_dwordx4 v[130:133], v[130:131], off
	v_addc_co_u32_e32 v135, vcc, 0, v155, vcc
	v_mfma_f32_16x16x32_bf16 v[102:105], v[202:205], v[216:219], v[102:105]
	v_add_co_u32_e32 v138, vcc, 0x30000, v154
	s_add_i32 s0, s0, 1
	v_mfma_f32_16x16x32_bf16 v[110:113], v[206:209], v[216:219], v[110:113]
	ds_read_b128 v[216:219], v211 offset:13824
	s_nop 0
	v_addc_co_u32_e32 v139, vcc, 0, v155, vcc
	s_waitcnt lgkmcnt(4)
	v_mfma_f32_16x16x32_bf16 v[82:85], v[190:193], v[236:239], v[82:85]
	v_add_co_u32_e32 v146, vcc, 0x40000, v154
	global_load_dwordx4 v[134:137], v[134:135], off
	v_mfma_f32_16x16x32_bf16 v[90:93], v[198:201], v[236:239], v[90:93]
	s_nop 0
	global_load_dwordx4 v[138:141], v[138:139], off
	v_mfma_f32_16x16x32_bf16 v[66:69], v[202:205], v[236:239], v[66:69]
	v_addc_co_u32_e32 v147, vcc, 0, v155, vcc
	v_add_co_u32_e32 v150, vcc, 0x50000, v154
	v_mfma_f32_16x16x32_bf16 v[74:77], v[206:209], v[236:239], v[74:77]
	ds_read_b128 v[236:239], v211 offset:16128
	s_nop 0
	v_addc_co_u32_e32 v151, vcc, 0, v155, vcc
	s_waitcnt lgkmcnt(4)
	v_mfma_f32_16x16x32_bf16 v[86:89], v[190:193], v[240:243], v[86:89]
	v_add_co_u32_e32 v156, vcc, 0x60000, v154
	global_load_dwordx4 v[146:149], v[146:147], off
	v_mfma_f32_16x16x32_bf16 v[94:97], v[198:201], v[240:243], v[94:97]
	s_nop 0
	global_load_dwordx4 v[150:153], v[150:151], off
	v_mfma_f32_16x16x32_bf16 v[70:73], v[202:205], v[240:243], v[70:73]
	v_addc_co_u32_e32 v157, vcc, 0, v155, vcc
	v_add_co_u32_e32 v158, vcc, 0x70000, v154
	v_mfma_f32_16x16x32_bf16 v[78:81], v[206:209], v[240:243], v[78:81]
	ds_read_b128 v[240:243], v215 offset:36928
	s_nop 1
	v_addc_co_u32_e32 v159, vcc, 0, v155, vcc
	s_waitcnt lgkmcnt(4)
	v_mfma_f32_16x16x32_bf16 v[50:53], v[190:193], v[244:247], v[50:53]
	v_add_co_u32_e32 v166, vcc, 0x10000, v170
	global_load_dwordx4 v[154:157], v[156:157], off
	v_mfma_f32_16x16x32_bf16 v[58:61], v[198:201], v[244:247], v[58:61]
	s_nop 0
	global_load_dwordx4 v[158:161], v[158:159], off
	v_mfma_f32_16x16x32_bf16 v[34:37], v[202:205], v[244:247], v[34:37]
	v_addc_co_u32_e32 v167, vcc, 0, v171, vcc
	v_add_co_u32_e32 v172, vcc, 0x20000, v170
	v_mfma_f32_16x16x32_bf16 v[42:45], v[206:209], v[244:247], v[42:45]
	ds_read_b128 v[244:247], v211 offset:64
	global_load_dwordx4 v[162:165], v[170:171], off
	s_nop 0
	s_waitcnt lgkmcnt(4)
	v_mfma_f32_16x16x32_bf16 v[54:57], v[190:193], v[194:197], v[54:57]
	global_load_dwordx4 v[166:169], v[166:167], off
	v_addc_co_u32_e32 v173, vcc, 0, v171, vcc
	v_mfma_f32_16x16x32_bf16 v[62:65], v[198:201], v[194:197], v[62:65]
	v_add_co_u32_e32 v174, vcc, 0x30000, v170
	s_nop 1
	v_mfma_f32_16x16x32_bf16 v[38:41], v[202:205], v[194:197], v[38:41]
	v_addc_co_u32_e32 v175, vcc, 0, v171, vcc
	global_load_dwordx4 v[170:173], v[172:173], off
	v_mfma_f32_16x16x32_bf16 v[46:49], v[206:209], v[194:197], v[46:49]
	ds_read_b128 v[194:197], v211 offset:2368
	s_nop 0
	global_load_dwordx4 v[174:177], v[174:175], off
	s_waitcnt lgkmcnt(4)
	v_mfma_f32_16x16x32_bf16 v[18:21], v[190:193], v[216:219], v[18:21]
	s_cmp_lg_u32 s0, 16
	s_waitcnt lgkmcnt(3)
	v_mfma_f32_16x16x32_bf16 v[22:25], v[190:193], v[236:239], v[22:25]
	ds_read_b128 v[190:193], v215 offset:39232
	v_mfma_f32_16x16x32_bf16 v[26:29], v[198:201], v[216:219], v[26:29]
	v_mfma_f32_16x16x32_bf16 v[30:33], v[198:201], v[236:239], v[30:33]
	ds_read_b128 v[198:201], v215 offset:41536
	v_mfma_f32_16x16x32_bf16 v[2:5], v[202:205], v[216:219], v[2:5]
	v_mfma_f32_16x16x32_bf16 v[6:9], v[202:205], v[236:239], v[6:9]
	ds_read_b128 v[202:205], v215 offset:43840
	v_mfma_f32_16x16x32_bf16 v[10:13], v[206:209], v[216:219], v[10:13]
	ds_read_b128 v[216:219], v211 offset:4672
	v_mfma_f32_16x16x32_bf16 v[14:17], v[206:209], v[236:239], v[14:17]
	ds_read_b128 v[206:209], v211 offset:6976
	ds_read_b128 v[236:239], v211 offset:9280
	s_waitcnt lgkmcnt(7)
	v_mfma_f32_16x16x32_bf16 v[114:117], v[240:243], v[244:247], v[114:117]
	s_waitcnt lgkmcnt(6)
	v_mfma_f32_16x16x32_bf16 v[118:121], v[240:243], v[194:197], v[118:121]
	s_waitcnt lgkmcnt(5)
	v_mfma_f32_16x16x32_bf16 v[122:125], v[190:193], v[244:247], v[122:125]
	v_mfma_f32_16x16x32_bf16 v[126:129], v[190:193], v[194:197], v[126:129]
	s_waitcnt lgkmcnt(4)
	v_mfma_f32_16x16x32_bf16 v[98:101], v[198:201], v[244:247], v[98:101]
	v_mfma_f32_16x16x32_bf16 v[102:105], v[198:201], v[194:197], v[102:105]
	s_waitcnt lgkmcnt(3)
	v_mfma_f32_16x16x32_bf16 v[106:109], v[202:205], v[244:247], v[106:109]
	ds_read_b128 v[244:247], v211 offset:11584
	v_mfma_f32_16x16x32_bf16 v[110:113], v[202:205], v[194:197], v[110:113]
	ds_read_b128 v[194:197], v211 offset:13888
	s_waitcnt lgkmcnt(4)
	v_mfma_f32_16x16x32_bf16 v[82:85], v[240:243], v[216:219], v[82:85]
	v_mfma_f32_16x16x32_bf16 v[90:93], v[190:193], v[216:219], v[90:93]
	v_mfma_f32_16x16x32_bf16 v[66:69], v[198:201], v[216:219], v[66:69]
	v_mfma_f32_16x16x32_bf16 v[74:77], v[202:205], v[216:219], v[74:77]
	ds_read_b128 v[216:219], v211 offset:16192
	s_waitcnt lgkmcnt(4)
	v_mfma_f32_16x16x32_bf16 v[86:89], v[240:243], v[206:209], v[86:89]
	v_mfma_f32_16x16x32_bf16 v[94:97], v[190:193], v[206:209], v[94:97]
	v_mfma_f32_16x16x32_bf16 v[70:73], v[198:201], v[206:209], v[70:73]
	v_mfma_f32_16x16x32_bf16 v[78:81], v[202:205], v[206:209], v[78:81]
	s_waitcnt lgkmcnt(3)
	v_mfma_f32_16x16x32_bf16 v[50:53], v[240:243], v[236:239], v[50:53]
	v_mfma_f32_16x16x32_bf16 v[58:61], v[190:193], v[236:239], v[58:61]
	v_mfma_f32_16x16x32_bf16 v[34:37], v[198:201], v[236:239], v[34:37]
	v_mfma_f32_16x16x32_bf16 v[42:45], v[202:205], v[236:239], v[42:45]
	s_waitcnt lgkmcnt(2)
	v_mfma_f32_16x16x32_bf16 v[54:57], v[240:243], v[244:247], v[54:57]
	v_mfma_f32_16x16x32_bf16 v[62:65], v[190:193], v[244:247], v[62:65]
	v_mfma_f32_16x16x32_bf16 v[38:41], v[198:201], v[244:247], v[38:41]
	v_mfma_f32_16x16x32_bf16 v[46:49], v[202:205], v[244:247], v[46:49]
	s_waitcnt lgkmcnt(1)
	v_mfma_f32_16x16x32_bf16 v[18:21], v[240:243], v[194:197], v[18:21]
	v_mfma_f32_16x16x32_bf16 v[26:29], v[190:193], v[194:197], v[26:29]
	v_mfma_f32_16x16x32_bf16 v[2:5], v[198:201], v[194:197], v[2:5]
	v_mfma_f32_16x16x32_bf16 v[10:13], v[202:205], v[194:197], v[10:13]
	s_waitcnt lgkmcnt(0)
	v_mfma_f32_16x16x32_bf16 v[22:25], v[240:243], v[216:219], v[22:25]
	v_mfma_f32_16x16x32_bf16 v[30:33], v[190:193], v[216:219], v[30:33]
	v_mfma_f32_16x16x32_bf16 v[6:9], v[198:201], v[216:219], v[6:9]
	v_mfma_f32_16x16x32_bf16 v[14:17], v[202:205], v[216:219], v[14:17]
	s_setprio 0
	s_cbranch_scc1 .Ltail_62
	s_add_i32 s2, s2, 1
	s_cmp_ge_i32 s2, s6
	s_cbranch_scc1 .Lz_62
	s_mul_i32 s0, s2, s82
	s_add_i32 s0, s0, s63
	s_ashr_i32 s1, s0, 31
	s_lshr_b32 s1, s1, 28
	s_add_i32 s1, s0, s1
	s_ashr_i32 s4, s1, 4
	s_and_b32 s1, s1, -16
	s_sub_i32 s0, s0, s1
	s_lshl_b32 s1, s4, 1
	s_and_b32 s4, s0, 1
	s_or_b32 s1, s4, s1
	v_readlane_b32 s4, v252, 35
	s_ashr_i32 s0, s0, 1
	s_sub_i32 s8, 0x7f, s1
	v_readlane_b32 s5, v252, 36
	s_and_b64 s[4:5], s[4:5], exec
	s_cselect_b32 s4, s8, s1
	s_ashr_i32 s5, s4, 31
	s_ashr_i32 s1, s0, 31
	s_lshl_b64 s[4:5], s[4:5], 19
	s_lshl_b64 s[0:1], s[0:1], 18
	v_lshl_add_u64 v[180:181], v[186:187], 0, s[4:5]
	v_lshl_add_u64 v[182:183], v[188:189], 0, s[0:1]

.LBB0_68:
	s_nop 7
	v_permlane16_swap_b32_e32 v114, v118
	v_permlane16_swap_b32_e32 v115, v119
	v_permlane16_swap_b32_e32 v116, v120
	v_permlane16_swap_b32_e32 v117, v121
	v_permlane16_swap_b32_e32 v122, v126
	v_permlane16_swap_b32_e32 v123, v127
	v_permlane16_swap_b32_e32 v124, v128
	v_permlane16_swap_b32_e32 v125, v129
	v_permlane32_swap_b32_e32 v114, v118
	v_permlane32_swap_b32_e32 v115, v119
	v_permlane32_swap_b32_e32 v116, v120
	v_permlane32_swap_b32_e32 v117, v121
	v_permlane32_swap_b32_e32 v122, v126
	v_permlane32_swap_b32_e32 v123, v127
	v_permlane32_swap_b32_e32 v124, v128
	v_permlane32_swap_b32_e32 v125, v129
	v_permlane16_swap_b32_e32 v98, v102
	v_permlane16_swap_b32_e32 v99, v103
	v_permlane16_swap_b32_e32 v100, v104
	v_permlane16_swap_b32_e32 v101, v105
	v_permlane16_swap_b32_e32 v106, v110
	v_permlane16_swap_b32_e32 v107, v111
	v_permlane16_swap_b32_e32 v108, v112
	v_permlane16_swap_b32_e32 v109, v113
	v_permlane32_swap_b32_e32 v98, v102
	v_permlane32_swap_b32_e32 v99, v103
	v_permlane32_swap_b32_e32 v100, v104
	v_permlane32_swap_b32_e32 v101, v105
	v_permlane32_swap_b32_e32 v106, v110
	v_permlane32_swap_b32_e32 v107, v111
	v_permlane32_swap_b32_e32 v108, v112
	v_permlane32_swap_b32_e32 v109, v113
	v_permlane16_swap_b32_e32 v82, v86
	v_permlane16_swap_b32_e32 v83, v87
	v_permlane16_swap_b32_e32 v84, v88
	v_permlane16_swap_b32_e32 v85, v89
	v_permlane16_swap_b32_e32 v90, v94
	v_permlane16_swap_b32_e32 v91, v95
	v_permlane16_swap_b32_e32 v92, v96
	v_permlane16_swap_b32_e32 v93, v97
	v_permlane32_swap_b32_e32 v82, v86
	v_permlane32_swap_b32_e32 v83, v87
	v_permlane32_swap_b32_e32 v84, v88
	v_permlane32_swap_b32_e32 v85, v89
	v_permlane32_swap_b32_e32 v90, v94
	v_permlane32_swap_b32_e32 v91, v95
	v_permlane32_swap_b32_e32 v92, v96
	v_permlane32_swap_b32_e32 v93, v97
	v_permlane16_swap_b32_e32 v66, v70
	v_permlane16_swap_b32_e32 v67, v71
	v_permlane16_swap_b32_e32 v68, v72
	v_permlane16_swap_b32_e32 v69, v73
	v_permlane16_swap_b32_e32 v74, v78
	v_permlane16_swap_b32_e32 v75, v79
	v_permlane16_swap_b32_e32 v76, v80
	v_permlane16_swap_b32_e32 v77, v81
	v_permlane32_swap_b32_e32 v66, v70
	v_permlane32_swap_b32_e32 v67, v71
	v_permlane32_swap_b32_e32 v68, v72
	v_permlane32_swap_b32_e32 v69, v73
	v_permlane32_swap_b32_e32 v74, v78
	v_permlane32_swap_b32_e32 v75, v79
	v_permlane32_swap_b32_e32 v76, v80
	v_permlane32_swap_b32_e32 v77, v81
	v_permlane16_swap_b32_e32 v50, v54
	v_permlane16_swap_b32_e32 v51, v55
	v_permlane16_swap_b32_e32 v52, v56
	v_permlane16_swap_b32_e32 v53, v57
	v_permlane16_swap_b32_e32 v58, v62
	v_permlane16_swap_b32_e32 v59, v63
	v_permlane16_swap_b32_e32 v60, v64
	v_permlane16_swap_b32_e32 v61, v65
	v_permlane32_swap_b32_e32 v50, v54
	v_permlane32_swap_b32_e32 v51, v55
	v_permlane32_swap_b32_e32 v52, v56
	v_permlane32_swap_b32_e32 v53, v57
	v_permlane32_swap_b32_e32 v58, v62
	v_permlane32_swap_b32_e32 v59, v63
	v_permlane32_swap_b32_e32 v60, v64
	v_permlane32_swap_b32_e32 v61, v65
	v_permlane16_swap_b32_e32 v34, v38
	v_permlane16_swap_b32_e32 v35, v39
	v_permlane16_swap_b32_e32 v36, v40
	v_permlane16_swap_b32_e32 v37, v41
	v_permlane16_swap_b32_e32 v42, v46
	v_permlane16_swap_b32_e32 v43, v47
	v_permlane16_swap_b32_e32 v44, v48
	v_permlane16_swap_b32_e32 v45, v49
	v_permlane32_swap_b32_e32 v34, v38
	v_permlane32_swap_b32_e32 v35, v39
	v_permlane32_swap_b32_e32 v36, v40
	v_permlane32_swap_b32_e32 v37, v41
	v_permlane32_swap_b32_e32 v42, v46
	v_permlane32_swap_b32_e32 v43, v47
	v_permlane32_swap_b32_e32 v44, v48
	v_permlane32_swap_b32_e32 v45, v49
	v_permlane16_swap_b32_e32 v18, v22
	v_permlane16_swap_b32_e32 v19, v23
	v_permlane16_swap_b32_e32 v20, v24
	v_permlane16_swap_b32_e32 v21, v25
	v_permlane16_swap_b32_e32 v26, v30
	v_permlane16_swap_b32_e32 v27, v31
	v_permlane16_swap_b32_e32 v28, v32
	v_permlane16_swap_b32_e32 v29, v33
	v_permlane32_swap_b32_e32 v18, v22
	v_permlane32_swap_b32_e32 v19, v23
	v_permlane32_swap_b32_e32 v20, v24
	v_permlane32_swap_b32_e32 v21, v25
	v_permlane32_swap_b32_e32 v26, v30
	v_permlane32_swap_b32_e32 v27, v31
	v_permlane32_swap_b32_e32 v28, v32
	v_permlane32_swap_b32_e32 v29, v33
	v_permlane16_swap_b32_e32 v2, v6
	v_permlane16_swap_b32_e32 v3, v7
	v_permlane16_swap_b32_e32 v4, v8
	v_permlane16_swap_b32_e32 v5, v9
	v_permlane16_swap_b32_e32 v10, v14
	v_permlane16_swap_b32_e32 v11, v15
	v_permlane16_swap_b32_e32 v12, v16
	v_permlane16_swap_b32_e32 v13, v17
	v_permlane32_swap_b32_e32 v2, v6
	v_permlane32_swap_b32_e32 v3, v7
	v_permlane32_swap_b32_e32 v4, v8
	v_permlane32_swap_b32_e32 v5, v9
	v_permlane32_swap_b32_e32 v10, v14
	v_permlane32_swap_b32_e32 v11, v15
	v_permlane32_swap_b32_e32 v12, v16
	v_permlane32_swap_b32_e32 v13, v17
	s_mul_i32 s1, s7, s82
	s_add_i32 s1, s1, s63
	s_ashr_i32 s3, s1, 31
	s_lshr_b32 s3, s3, 28
	s_add_i32 s3, s1, s3
	s_ashr_i32 s4, s3, 4
	s_and_b32 s3, s3, -16
	s_sub_i32 s1, s1, s3
	s_lshl_b32 s3, s4, 1
	s_and_b32 s4, s1, 1
	s_or_b32 s3, s4, s3
	v_readlane_b32 s4, v252, 35
	s_sub_i32 s8, 0x7f, s3
	v_readlane_b32 s5, v252, 36
	s_and_b64 s[4:5], s[4:5], exec
	s_cselect_b32 s4, s8, s3
	v_mov_b32_e32 v0, v222
	s_ashr_i32 s5, s4, 31
	v_and_b32_e32 v190, 0xffffff80, v0
	s_lshl_b64 s[4:5], s[4:5], 8
	v_ashrrev_i32_e32 v191, 31, v190
	v_lshl_add_u64 v[190:191], s[4:5], 0, v[190:191]
	s_lshl_b32 s1, s1, 6
	v_and_b32_e32 v185, 64, v0
	v_and_or_b32 v190, v0, 31, v190
	s_and_b32 s1, s1, 0xffffff80
	v_lshrrev_b32_e32 v0, 3, v0
	v_readlane_b32 s4, v252, 31
	s_ashr_i32 s3, s1, 31
	v_and_b32_e32 v0, 4, v0
	v_lshlrev_b64 v[190:191], 12, v[190:191]
	v_readlane_b32 s5, v252, 32
	v_or3_b32 v192, v0, v185, s1
	v_mov_b32_e32 v193, s3
	v_lshl_add_u64 v[190:191], s[4:5], 0, v[190:191]
	v_lshl_add_u64 v[190:191], v[192:193], 2, v[190:191]
	s_mov_b64 s[98:99], 0x20000
	v_lshl_add_u64 v[192:193], v[190:191], 0, 0
	v_lshl_add_u64 v[220:221], v[190:191], 0, 0
	global_load_dwordx4 v[194:197], v[192:193], off
	global_load_dwordx4 v[198:201], v[192:193], off offset:32
	global_load_dwordx4 v[202:205], v[192:193], off offset:64
	global_load_dwordx4 v[206:209], v[192:193], off offset:96
	global_load_dwordx4 v[216:219], v[192:193], off offset:128
	global_load_dwordx4 v[236:239], v[192:193], off offset:160
	global_load_dwordx4 v[240:243], v[192:193], off offset:192
	global_load_dwordx4 v[244:247], v[192:193], off offset:224
	s_waitcnt vmcnt(7)
	v_pk_add_f32 v[114:115], v[114:115], v[194:195]
	v_pk_add_f32 v[116:117], v[116:117], v[196:197]
	global_store_dwordx4 v[220:221], v[114:117], off
	v_lshl_add_u64 v[192:193], v[192:193], 0, s[98:99]
	global_load_dwordx4 v[194:197], v[192:193], off
	s_waitcnt vmcnt(8)
	v_pk_add_f32 v[118:119], v[118:119], v[198:199]
	v_pk_add_f32 v[120:121], v[120:121], v[200:201]
	global_store_dwordx4 v[220:221], v[118:121], off offset:32
	global_load_dwordx4 v[198:201], v[192:193], off offset:32
	s_waitcnt vmcnt(9)
	v_pk_add_f32 v[122:123], v[122:123], v[202:203]
	v_pk_add_f32 v[124:125], v[124:125], v[204:205]
	global_store_dwordx4 v[220:221], v[122:125], off offset:64
	global_load_dwordx4 v[202:205], v[192:193], off offset:64
	s_waitcnt vmcnt(10)
	v_pk_add_f32 v[126:127], v[126:127], v[206:207]
	v_pk_add_f32 v[128:129], v[128:129], v[208:209]
	global_store_dwordx4 v[220:221], v[126:129], off offset:96
	global_load_dwordx4 v[206:209], v[192:193], off offset:96
	s_waitcnt vmcnt(11)
	v_pk_add_f32 v[98:99], v[98:99], v[216:217]
	v_pk_add_f32 v[100:101], v[100:101], v[218:219]
	global_store_dwordx4 v[220:221], v[98:101], off offset:128
	global_load_dwordx4 v[216:219], v[192:193], off offset:128
	s_waitcnt vmcnt(12)
	v_pk_add_f32 v[102:103], v[102:103], v[236:237]
	v_pk_add_f32 v[104:105], v[104:105], v[238:239]
	global_store_dwordx4 v[220:221], v[102:105], off offset:160
	global_load_dwordx4 v[236:239], v[192:193], off offset:160
	s_waitcnt vmcnt(13)
	v_pk_add_f32 v[106:107], v[106:107], v[240:241]
	v_pk_add_f32 v[108:109], v[108:109], v[242:243]
	global_store_dwordx4 v[220:221], v[106:109], off offset:192
	global_load_dwordx4 v[240:243], v[192:193], off offset:192
	s_waitcnt vmcnt(14)
	v_pk_add_f32 v[110:111], v[110:111], v[244:245]
	v_pk_add_f32 v[112:113], v[112:113], v[246:247]
	global_store_dwordx4 v[220:221], v[110:113], off offset:224
	global_load_dwordx4 v[244:247], v[192:193], off offset:224
	s_waitcnt vmcnt(14)
	v_pk_add_f32 v[82:83], v[82:83], v[194:195]
	v_pk_add_f32 v[84:85], v[84:85], v[196:197]
	v_lshl_add_u64 v[220:221], v[220:221], 0, s[98:99]
	global_store_dwordx4 v[220:221], v[82:85], off
	v_lshl_add_u64 v[192:193], v[192:193], 0, s[98:99]
	global_load_dwordx4 v[194:197], v[192:193], off
	s_waitcnt vmcnt(14)
	v_pk_add_f32 v[86:87], v[86:87], v[198:199]
	v_pk_add_f32 v[88:89], v[88:89], v[200:201]
	global_store_dwordx4 v[220:221], v[86:89], off offset:32
	global_load_dwordx4 v[198:201], v[192:193], off offset:32
	s_waitcnt vmcnt(14)
	v_pk_add_f32 v[90:91], v[90:91], v[202:203]
	v_pk_add_f32 v[92:93], v[92:93], v[204:205]
	global_store_dwordx4 v[220:221], v[90:93], off offset:64
	global_load_dwordx4 v[202:205], v[192:193], off offset:64
	s_waitcnt vmcnt(14)
	v_pk_add_f32 v[94:95], v[94:95], v[206:207]
	v_pk_add_f32 v[96:97], v[96:97], v[208:209]
	global_store_dwordx4 v[220:221], v[94:97], off offset:96
	global_load_dwordx4 v[206:209], v[192:193], off offset:96
	s_waitcnt vmcnt(14)
	v_pk_add_f32 v[66:67], v[66:67], v[216:217]
	v_pk_add_f32 v[68:69], v[68:69], v[218:219]
	global_store_dwordx4 v[220:221], v[66:69], off offset:128
	global_load_dwordx4 v[216:219], v[192:193], off offset:128
	s_waitcnt vmcnt(14)
	v_pk_add_f32 v[70:71], v[70:71], v[236:237]
	v_pk_add_f32 v[72:73], v[72:73], v[238:239]
	global_store_dwordx4 v[220:221], v[70:73], off offset:160
	global_load_dwordx4 v[236:239], v[192:193], off offset:160
	s_waitcnt vmcnt(14)
	v_pk_add_f32 v[74:75], v[74:75], v[240:241]
	v_pk_add_f32 v[76:77], v[76:77], v[242:243]
	global_store_dwordx4 v[220:221], v[74:77], off offset:192
	global_load_dwordx4 v[240:243], v[192:193], off offset:192
	s_waitcnt vmcnt(14)
	v_pk_add_f32 v[78:79], v[78:79], v[244:245]
	v_pk_add_f32 v[80:81], v[80:81], v[246:247]
	global_store_dwordx4 v[220:221], v[78:81], off offset:224
	global_load_dwordx4 v[244:247], v[192:193], off offset:224
	s_waitcnt vmcnt(14)
	v_pk_add_f32 v[50:51], v[50:51], v[194:195]
	v_pk_add_f32 v[52:53], v[52:53], v[196:197]
	v_lshl_add_u64 v[220:221], v[220:221], 0, s[98:99]
	global_store_dwordx4 v[220:221], v[50:53], off
	v_lshl_add_u64 v[192:193], v[192:193], 0, s[98:99]
	global_load_dwordx4 v[194:197], v[192:193], off
	s_waitcnt vmcnt(14)
	v_pk_add_f32 v[54:55], v[54:55], v[198:199]
	v_pk_add_f32 v[56:57], v[56:57], v[200:201]
	global_store_dwordx4 v[220:221], v[54:57], off offset:32
	global_load_dwordx4 v[198:201], v[192:193], off offset:32
	s_waitcnt vmcnt(14)
	v_pk_add_f32 v[58:59], v[58:59], v[202:203]
	v_pk_add_f32 v[60:61], v[60:61], v[204:205]
	global_store_dwordx4 v[220:221], v[58:61], off offset:64
	global_load_dwordx4 v[202:205], v[192:193], off offset:64
	s_waitcnt vmcnt(14)
	v_pk_add_f32 v[62:63], v[62:63], v[206:207]
	v_pk_add_f32 v[64:65], v[64:65], v[208:209]
	global_store_dwordx4 v[220:221], v[62:65], off offset:96
	global_load_dwordx4 v[206:209], v[192:193], off offset:96
	s_waitcnt vmcnt(14)
	v_pk_add_f32 v[34:35], v[34:35], v[216:217]
	v_pk_add_f32 v[36:37], v[36:37], v[218:219]
	global_store_dwordx4 v[220:221], v[34:37], off offset:128
	global_load_dwordx4 v[216:219], v[192:193], off offset:128
	s_waitcnt vmcnt(14)
	v_pk_add_f32 v[38:39], v[38:39], v[236:237]
	v_pk_add_f32 v[40:41], v[40:41], v[238:239]
	global_store_dwordx4 v[220:221], v[38:41], off offset:160
	global_load_dwordx4 v[236:239], v[192:193], off offset:160
	s_waitcnt vmcnt(14)
	v_pk_add_f32 v[42:43], v[42:43], v[240:241]
	v_pk_add_f32 v[44:45], v[44:45], v[242:243]
	global_store_dwordx4 v[220:221], v[42:45], off offset:192
	global_load_dwordx4 v[240:243], v[192:193], off offset:192
	s_waitcnt vmcnt(14)
	v_pk_add_f32 v[46:47], v[46:47], v[244:245]
	v_pk_add_f32 v[48:49], v[48:49], v[246:247]
	global_store_dwordx4 v[220:221], v[46:49], off offset:224
	global_load_dwordx4 v[244:247], v[192:193], off offset:224
	s_waitcnt vmcnt(14)
	v_pk_add_f32 v[18:19], v[18:19], v[194:195]
	v_pk_add_f32 v[20:21], v[20:21], v[196:197]
	v_lshl_add_u64 v[220:221], v[220:221], 0, s[98:99]
	global_store_dwordx4 v[220:221], v[18:21], off
	s_waitcnt vmcnt(13)
	v_pk_add_f32 v[22:23], v[22:23], v[198:199]
	v_pk_add_f32 v[24:25], v[24:25], v[200:201]
	global_store_dwordx4 v[220:221], v[22:25], off offset:32
	s_waitcnt vmcnt(12)
	v_pk_add_f32 v[26:27], v[26:27], v[202:203]
	v_pk_add_f32 v[28:29], v[28:29], v[204:205]
	global_store_dwordx4 v[220:221], v[26:29], off offset:64
	s_waitcnt vmcnt(11)
	v_pk_add_f32 v[30:31], v[30:31], v[206:207]
	v_pk_add_f32 v[32:33], v[32:33], v[208:209]
	global_store_dwordx4 v[220:221], v[30:33], off offset:96
	s_waitcnt vmcnt(10)
	v_pk_add_f32 v[2:3], v[2:3], v[216:217]
	v_pk_add_f32 v[4:5], v[4:5], v[218:219]
	global_store_dwordx4 v[220:221], v[2:5], off offset:128
	s_waitcnt vmcnt(9)
	v_pk_add_f32 v[6:7], v[6:7], v[236:237]
	v_pk_add_f32 v[8:9], v[8:9], v[238:239]
	global_store_dwordx4 v[220:221], v[6:9], off offset:160
	s_waitcnt vmcnt(8)
	v_pk_add_f32 v[10:11], v[10:11], v[240:241]
	v_pk_add_f32 v[12:13], v[12:13], v[242:243]
	global_store_dwordx4 v[220:221], v[10:13], off offset:192
	s_waitcnt vmcnt(7)
	v_pk_add_f32 v[14:15], v[14:15], v[244:245]
	v_pk_add_f32 v[16:17], v[16:17], v[246:247]
	global_store_dwordx4 v[220:221], v[14:17], off offset:224
	s_mov_b32 s3, 0
	s_add_i32 s7, s7, 1
	v_mov_b32_e32 v114, 0
	v_mov_b32_e32 v115, 0
	v_mov_b32_e32 v116, 0
	v_mov_b32_e32 v117, 0
	v_mov_b32_e32 v118, 0
	v_mov_b32_e32 v119, 0
	v_mov_b32_e32 v120, 0
	v_mov_b32_e32 v121, 0
	v_mov_b32_e32 v122, 0
	v_mov_b32_e32 v123, 0
	v_mov_b32_e32 v124, 0
	v_mov_b32_e32 v125, 0
	v_mov_b32_e32 v126, 0
	v_mov_b32_e32 v127, 0
	v_mov_b32_e32 v128, 0
	v_mov_b32_e32 v129, 0
	v_mov_b32_e32 v98, 0
	v_mov_b32_e32 v99, 0
	v_mov_b32_e32 v100, 0
	v_mov_b32_e32 v101, 0
	v_mov_b32_e32 v102, 0
	v_mov_b32_e32 v103, 0
	v_mov_b32_e32 v104, 0
	v_mov_b32_e32 v105, 0
	v_mov_b32_e32 v106, 0
	v_mov_b32_e32 v107, 0
	v_mov_b32_e32 v108, 0
	v_mov_b32_e32 v109, 0
	v_mov_b32_e32 v110, 0
	v_mov_b32_e32 v111, 0
	v_mov_b32_e32 v112, 0
	v_mov_b32_e32 v113, 0
	v_mov_b32_e32 v82, 0
	v_mov_b32_e32 v83, 0
	v_mov_b32_e32 v84, 0
	v_mov_b32_e32 v85, 0
	v_mov_b32_e32 v86, 0
	v_mov_b32_e32 v87, 0
	v_mov_b32_e32 v88, 0
	v_mov_b32_e32 v89, 0
	v_mov_b32_e32 v90, 0
	v_mov_b32_e32 v91, 0
	v_mov_b32_e32 v92, 0
	v_mov_b32_e32 v93, 0
	v_mov_b32_e32 v94, 0
	v_mov_b32_e32 v95, 0
	v_mov_b32_e32 v96, 0
	v_mov_b32_e32 v97, 0
	v_mov_b32_e32 v66, 0
	v_mov_b32_e32 v67, 0
	v_mov_b32_e32 v68, 0
	v_mov_b32_e32 v69, 0
	v_mov_b32_e32 v70, 0
	v_mov_b32_e32 v71, 0
	v_mov_b32_e32 v72, 0
	v_mov_b32_e32 v73, 0
	v_mov_b32_e32 v74, 0
	v_mov_b32_e32 v75, 0
	v_mov_b32_e32 v76, 0
	v_mov_b32_e32 v77, 0
	v_mov_b32_e32 v78, 0
	v_mov_b32_e32 v79, 0
	v_mov_b32_e32 v80, 0
	v_mov_b32_e32 v81, 0
	v_mov_b32_e32 v50, 0
	v_mov_b32_e32 v51, 0
	v_mov_b32_e32 v52, 0
	v_mov_b32_e32 v53, 0
	v_mov_b32_e32 v54, 0
	v_mov_b32_e32 v55, 0
	v_mov_b32_e32 v56, 0
	v_mov_b32_e32 v57, 0
	v_mov_b32_e32 v58, 0
	v_mov_b32_e32 v59, 0
	v_mov_b32_e32 v60, 0
	v_mov_b32_e32 v61, 0
	v_mov_b32_e32 v62, 0
	v_mov_b32_e32 v63, 0
	v_mov_b32_e32 v64, 0
	v_mov_b32_e32 v65, 0
	v_mov_b32_e32 v34, 0
	v_mov_b32_e32 v35, 0
	v_mov_b32_e32 v36, 0
	v_mov_b32_e32 v37, 0
	v_mov_b32_e32 v38, 0
	v_mov_b32_e32 v39, 0
	v_mov_b32_e32 v40, 0
	v_mov_b32_e32 v41, 0
	v_mov_b32_e32 v42, 0
	v_mov_b32_e32 v43, 0
	v_mov_b32_e32 v44, 0
	v_mov_b32_e32 v45, 0
	v_mov_b32_e32 v46, 0
	v_mov_b32_e32 v47, 0
	v_mov_b32_e32 v48, 0
	v_mov_b32_e32 v49, 0
	v_mov_b32_e32 v18, 0
	v_mov_b32_e32 v19, 0
	v_mov_b32_e32 v20, 0
	v_mov_b32_e32 v21, 0
	v_mov_b32_e32 v22, 0
	v_mov_b32_e32 v23, 0
	v_mov_b32_e32 v24, 0
	v_mov_b32_e32 v25, 0
	v_mov_b32_e32 v26, 0
	v_mov_b32_e32 v27, 0
	v_mov_b32_e32 v28, 0
	v_mov_b32_e32 v29, 0
	v_mov_b32_e32 v30, 0
	v_mov_b32_e32 v31, 0
	v_mov_b32_e32 v32, 0
	v_mov_b32_e32 v33, 0
	v_mov_b32_e32 v2, 0
	v_mov_b32_e32 v3, 0
	v_mov_b32_e32 v4, 0
	v_mov_b32_e32 v5, 0
	v_mov_b32_e32 v6, 0
	v_mov_b32_e32 v7, 0
	v_mov_b32_e32 v8, 0
	v_mov_b32_e32 v9, 0
	v_mov_b32_e32 v10, 0
	v_mov_b32_e32 v11, 0
	v_mov_b32_e32 v12, 0
	v_mov_b32_e32 v13, 0
	v_mov_b32_e32 v14, 0
	v_mov_b32_e32 v15, 0
	v_mov_b32_e32 v16, 0
	v_mov_b32_e32 v17, 0
	s_cmp_ge_i32 s7, s6
	s_cbranch_scc0 .LBB0_64

.LcL_92:
	s_waitcnt lgkmcnt(0)
	s_barrier
	s_setprio 2
	v_bfe_u32 v221, v222, 5, 1
	v_bfe_u32 v248, v222, 4, 1
	v_lshl_add_u32 v211, v221, 4, v180
	v_lshl_add_u32 v215, v221, 4, v181
	v_mul_u32_u24_e32 v221, 0x8f0, v248
	v_mul_u32_u24_e32 v248, 0x8f8, v248
	v_sub_u32_e32 v213, v211, v248
	v_sub_u32_e32 v220, v215, v248
	v_sub_u32_e32 v211, v211, v221
	v_sub_u32_e32 v215, v215, v221
	ds_read_b128 v[190:193], v215 offset:36864
	ds_read_b128 v[194:197], v211
	ds_read_b128 v[198:201], v215 offset:39168
	ds_read_b128 v[202:205], v215 offset:41472
	ds_read_b128 v[206:209], v215 offset:43776
	ds_read_b128 v[216:219], v211 offset:2304
	ds_read_b128 v[236:239], v211 offset:4608
	ds_read_b128 v[240:243], v211 offset:6912
	ds_read_b128 v[244:247], v211 offset:9216
	s_waitcnt lgkmcnt(7)
	v_mfma_f32_16x16x32_bf16 v[114:117], v[190:193], v[194:197], v[114:117]
	s_ashr_i32 s9, s8, 31
	s_lshl_b64 s[12:13], s[10:11], 6
	s_waitcnt lgkmcnt(6)
	v_mfma_f32_16x16x32_bf16 v[122:125], v[198:201], v[194:197], v[122:125]
	s_lshl_b64 s[4:5], s[8:9], 7
	v_lshl_add_u64 v[138:139], v[186:187], 0, s[12:13]
	s_waitcnt lgkmcnt(5)
	v_mfma_f32_16x16x32_bf16 v[98:101], v[202:205], v[194:197], v[98:101]
	v_lshl_add_u64 v[134:135], v[138:139], 0, s[4:5]
	v_lshl_add_u64 v[138:139], v[138:139], 0, s[12:13]
	s_waitcnt lgkmcnt(4)
	v_mfma_f32_16x16x32_bf16 v[106:109], v[206:209], v[194:197], v[106:109]
	ds_read_b128 v[194:197], v211 offset:11520
	v_lshl_add_u64 v[146:147], v[138:139], 0, s[12:13]
	v_lshl_add_u64 v[142:143], v[146:147], 0, s[4:5]
	s_waitcnt lgkmcnt(4)
	v_mfma_f32_16x16x32_bf16 v[118:121], v[190:193], v[216:219], v[118:121]
	v_lshl_add_u64 v[146:147], v[146:147], 0, s[12:13]
	v_lshl_add_u64 v[154:155], v[146:147], 0, s[12:13]
	v_mfma_f32_16x16x32_bf16 v[126:129], v[198:201], v[216:219], v[126:129]
	v_lshl_add_u64 v[150:151], v[154:155], 0, s[4:5]
	v_lshl_add_u64 v[154:155], v[154:155], 0, s[12:13]
	v_mfma_f32_16x16x32_bf16 v[102:105], v[202:205], v[216:219], v[102:105]
	v_lshl_add_u64 v[156:157], v[154:155], 0, s[4:5]
	v_lshl_add_u64 v[154:155], v[154:155], 0, s[12:13]
	v_mfma_f32_16x16x32_bf16 v[110:113], v[206:209], v[216:219], v[110:113]
	ds_read_b128 v[216:219], v211 offset:13824
	s_lshl_b64 s[12:13], s[10:11], 6
	v_lshl_add_u64 v[170:171], v[188:189], 0, s[12:13]
	s_waitcnt lgkmcnt(4)
	v_mfma_f32_16x16x32_bf16 v[82:85], v[190:193], v[236:239], v[82:85]
	v_lshl_add_u64 v[166:167], v[170:171], 0, s[4:5]
	v_lshl_add_u64 v[170:171], v[170:171], 0, s[12:13]
	v_mfma_f32_16x16x32_bf16 v[90:93], v[198:201], v[236:239], v[90:93]
	v_lshl_add_u64 v[172:173], v[170:171], 0, s[4:5]
	v_lshl_add_u64 v[170:171], v[170:171], 0, s[12:13]
	v_mfma_f32_16x16x32_bf16 v[66:69], v[202:205], v[236:239], v[66:69]
	v_lshl_add_u64 v[130:131], v[186:187], 0, s[4:5]
	v_lshl_add_u64 v[140:141], v[138:139], 0, s[4:5]
	v_mfma_f32_16x16x32_bf16 v[74:77], v[206:209], v[236:239], v[74:77]
	ds_read_b128 v[236:239], v211 offset:16128
	v_lshl_add_u64 v[148:149], v[146:147], 0, s[4:5]
	v_lshl_add_u64 v[158:159], v[154:155], 0, s[4:5]
	s_waitcnt lgkmcnt(4)
	v_mfma_f32_16x16x32_bf16 v[86:89], v[190:193], v[240:243], v[86:89]
	v_lshl_add_u64 v[162:163], v[188:189], 0, s[4:5]
	v_lshl_add_u64 v[174:175], v[170:171], 0, s[4:5]
	v_mfma_f32_16x16x32_bf16 v[94:97], v[198:201], v[240:243], v[94:97]
	global_load_dwordx4 v[130:133], v[130:131], off
	s_nop 0
	v_mfma_f32_16x16x32_bf16 v[70:73], v[202:205], v[240:243], v[70:73]
	global_load_dwordx4 v[134:137], v[134:135], off
	s_nop 0
	v_mfma_f32_16x16x32_bf16 v[78:81], v[206:209], v[240:243], v[78:81]
	ds_read_b128 v[240:243], v215 offset:36928
	global_load_dwordx4 v[138:141], v[140:141], off
	s_nop 0
	s_waitcnt lgkmcnt(4)
	v_mfma_f32_16x16x32_bf16 v[50:53], v[190:193], v[244:247], v[50:53]
	global_load_dwordx4 v[142:145], v[142:143], off
	s_nop 0
	v_mfma_f32_16x16x32_bf16 v[58:61], v[198:201], v[244:247], v[58:61]
	global_load_dwordx4 v[146:149], v[148:149], off
	s_nop 0
	v_mfma_f32_16x16x32_bf16 v[34:37], v[202:205], v[244:247], v[34:37]
	global_load_dwordx4 v[150:153], v[150:151], off
	s_nop 0
	v_mfma_f32_16x16x32_bf16 v[42:45], v[206:209], v[244:247], v[42:45]
	ds_read_b128 v[244:247], v211 offset:64
	global_load_dwordx4 v[154:157], v[156:157], off
	s_nop 0
	s_waitcnt lgkmcnt(4)
	v_mfma_f32_16x16x32_bf16 v[54:57], v[190:193], v[194:197], v[54:57]
	global_load_dwordx4 v[158:161], v[158:159], off
	s_nop 0
	v_mfma_f32_16x16x32_bf16 v[62:65], v[198:201], v[194:197], v[62:65]
	global_load_dwordx4 v[162:165], v[162:163], off
	s_nop 0
	v_mfma_f32_16x16x32_bf16 v[38:41], v[202:205], v[194:197], v[38:41]
	global_load_dwordx4 v[166:169], v[166:167], off
	s_nop 0
	v_mfma_f32_16x16x32_bf16 v[46:49], v[206:209], v[194:197], v[46:49]
	ds_read_b128 v[194:197], v211 offset:2368
	global_load_dwordx4 v[170:173], v[172:173], off
	s_nop 0
	s_waitcnt lgkmcnt(4)
	v_mfma_f32_16x16x32_bf16 v[18:21], v[190:193], v[216:219], v[18:21]
	global_load_dwordx4 v[174:177], v[174:175], off
	s_add_i32 s8, s8, 1
	s_waitcnt lgkmcnt(3)
	v_mfma_f32_16x16x32_bf16 v[22:25], v[190:193], v[236:239], v[22:25]
	ds_read_b128 v[190:193], v215 offset:39232
	s_cmp_lg_u32 s8, s19
	v_mfma_f32_16x16x32_bf16 v[26:29], v[198:201], v[216:219], v[26:29]
	v_mfma_f32_16x16x32_bf16 v[30:33], v[198:201], v[236:239], v[30:33]
	ds_read_b128 v[198:201], v215 offset:41536
	v_mfma_f32_16x16x32_bf16 v[2:5], v[202:205], v[216:219], v[2:5]
	v_mfma_f32_16x16x32_bf16 v[6:9], v[202:205], v[236:239], v[6:9]
	ds_read_b128 v[202:205], v215 offset:43840
	v_mfma_f32_16x16x32_bf16 v[10:13], v[206:209], v[216:219], v[10:13]
	ds_read_b128 v[216:219], v211 offset:4672
	v_mfma_f32_16x16x32_bf16 v[14:17], v[206:209], v[236:239], v[14:17]
	ds_read_b128 v[206:209], v211 offset:6976
	ds_read_b128 v[236:239], v211 offset:9280
	s_waitcnt lgkmcnt(7)
	v_mfma_f32_16x16x32_bf16 v[114:117], v[240:243], v[244:247], v[114:117]
	s_waitcnt lgkmcnt(6)
	v_mfma_f32_16x16x32_bf16 v[118:121], v[240:243], v[194:197], v[118:121]
	s_waitcnt lgkmcnt(5)
	v_mfma_f32_16x16x32_bf16 v[122:125], v[190:193], v[244:247], v[122:125]
	v_mfma_f32_16x16x32_bf16 v[126:129], v[190:193], v[194:197], v[126:129]
	s_waitcnt lgkmcnt(4)
	v_mfma_f32_16x16x32_bf16 v[98:101], v[198:201], v[244:247], v[98:101]
	v_mfma_f32_16x16x32_bf16 v[102:105], v[198:201], v[194:197], v[102:105]
	s_waitcnt lgkmcnt(3)
	v_mfma_f32_16x16x32_bf16 v[106:109], v[202:205], v[244:247], v[106:109]
	ds_read_b128 v[244:247], v211 offset:11584
	v_mfma_f32_16x16x32_bf16 v[110:113], v[202:205], v[194:197], v[110:113]
	ds_read_b128 v[194:197], v211 offset:13888
	s_waitcnt lgkmcnt(4)
	v_mfma_f32_16x16x32_bf16 v[82:85], v[240:243], v[216:219], v[82:85]
	v_mfma_f32_16x16x32_bf16 v[90:93], v[190:193], v[216:219], v[90:93]
	v_mfma_f32_16x16x32_bf16 v[66:69], v[198:201], v[216:219], v[66:69]
	v_mfma_f32_16x16x32_bf16 v[74:77], v[202:205], v[216:219], v[74:77]
	ds_read_b128 v[216:219], v211 offset:16192
	s_waitcnt lgkmcnt(4)
	v_mfma_f32_16x16x32_bf16 v[86:89], v[240:243], v[206:209], v[86:89]
	v_mfma_f32_16x16x32_bf16 v[94:97], v[190:193], v[206:209], v[94:97]
	v_mfma_f32_16x16x32_bf16 v[70:73], v[198:201], v[206:209], v[70:73]
	v_mfma_f32_16x16x32_bf16 v[78:81], v[202:205], v[206:209], v[78:81]
	s_waitcnt lgkmcnt(3)
	v_mfma_f32_16x16x32_bf16 v[50:53], v[240:243], v[236:239], v[50:53]
	v_mfma_f32_16x16x32_bf16 v[58:61], v[190:193], v[236:239], v[58:61]
	v_mfma_f32_16x16x32_bf16 v[34:37], v[198:201], v[236:239], v[34:37]
	v_mfma_f32_16x16x32_bf16 v[42:45], v[202:205], v[236:239], v[42:45]
	s_waitcnt lgkmcnt(2)
	v_mfma_f32_16x16x32_bf16 v[54:57], v[240:243], v[244:247], v[54:57]
	v_mfma_f32_16x16x32_bf16 v[62:65], v[190:193], v[244:247], v[62:65]
	v_mfma_f32_16x16x32_bf16 v[38:41], v[198:201], v[244:247], v[38:41]
	v_mfma_f32_16x16x32_bf16 v[46:49], v[202:205], v[244:247], v[46:49]
	s_waitcnt lgkmcnt(1)
	v_mfma_f32_16x16x32_bf16 v[18:21], v[240:243], v[194:197], v[18:21]
	v_mfma_f32_16x16x32_bf16 v[26:29], v[190:193], v[194:197], v[26:29]
	v_mfma_f32_16x16x32_bf16 v[2:5], v[198:201], v[194:197], v[2:5]
	v_mfma_f32_16x16x32_bf16 v[10:13], v[202:205], v[194:197], v[10:13]
	s_waitcnt lgkmcnt(0)
	v_mfma_f32_16x16x32_bf16 v[22:25], v[240:243], v[216:219], v[22:25]
	v_mfma_f32_16x16x32_bf16 v[30:33], v[190:193], v[216:219], v[30:33]
	v_mfma_f32_16x16x32_bf16 v[6:9], v[198:201], v[216:219], v[6:9]
	v_mfma_f32_16x16x32_bf16 v[14:17], v[202:205], v[216:219], v[14:17]
	s_setprio 0
	s_cbranch_scc1 .Ltail_92
	s_add_i32 s21, s14, 1
	s_cmp_ge_i32 s21, s16
	s_cbranch_scc1 .Lx91_92
	s_bfe_u32 s22, s21, 0x20001
	s_bitcmp1_b32 s14, 0
	s_cselect_b64 s[4:5], -1, 0
	s_and_b64 vcc, exec, s[4:5]
	s_cbranch_vccnz .Lx89_92
	s_cmp_lt_i32 s22, 1
	s_mov_b64 s[4:5], 0xfc00000
	s_cbranch_scc1 .Lx88_92
	s_cmp_eq_u32 s22, 1
	s_mov_b64 s[8:9], -1
	s_cbranch_scc1 .Lx86_92
	s_cmp_eq_u32 s22, 2
	s_mov_b32 s4, 0x4c00000
	s_cselect_b32 s80, s4, 0x9c00000
	s_mov_b64 s[8:9], 0
	s_mov_b64 s[4:5], s[80:81]

.LBB0_92:
	s_waitcnt lgkmcnt(0)
	s_barrier
	s_setprio 2
	v_bfe_u32 v221, v222, 5, 1
	v_bfe_u32 v248, v222, 4, 1
	v_lshl_add_u32 v211, v221, 4, v180
	v_lshl_add_u32 v215, v221, 4, v181
	v_mul_u32_u24_e32 v221, 0x8f0, v248
	v_mul_u32_u24_e32 v248, 0x8f8, v248
	v_sub_u32_e32 v213, v211, v248
	v_sub_u32_e32 v220, v215, v248
	v_sub_u32_e32 v211, v211, v221
	v_sub_u32_e32 v215, v215, v221
	ds_read_b128 v[190:193], v215 offset:36864
	ds_read_b128 v[194:197], v211
	ds_read_b128 v[198:201], v215 offset:39168
	ds_read_b128 v[202:205], v215 offset:41472
	ds_read_b128 v[206:209], v215 offset:43776
	ds_read_b128 v[216:219], v211 offset:2304
	ds_read_b128 v[236:239], v211 offset:4608
	ds_read_b128 v[240:243], v211 offset:6912
	ds_read_b128 v[244:247], v211 offset:9216
	s_waitcnt lgkmcnt(7)
	v_mfma_f32_16x16x32_bf16 v[114:117], v[190:193], v[194:197], v[114:117]
	s_waitcnt lgkmcnt(6)
	v_mfma_f32_16x16x32_bf16 v[122:125], v[198:201], v[194:197], v[122:125]
	s_waitcnt lgkmcnt(5)
	v_mfma_f32_16x16x32_bf16 v[98:101], v[202:205], v[194:197], v[98:101]
	s_waitcnt lgkmcnt(4)
	v_mfma_f32_16x16x32_bf16 v[106:109], v[206:209], v[194:197], v[106:109]
	ds_read_b128 v[194:197], v211 offset:11520
	s_waitcnt lgkmcnt(4)
	v_mfma_f32_16x16x32_bf16 v[118:121], v[190:193], v[216:219], v[118:121]
	v_mfma_f32_16x16x32_bf16 v[126:129], v[198:201], v[216:219], v[126:129]
	v_mfma_f32_16x16x32_bf16 v[102:105], v[202:205], v[216:219], v[102:105]
	v_mfma_f32_16x16x32_bf16 v[110:113], v[206:209], v[216:219], v[110:113]
	ds_read_b128 v[216:219], v211 offset:13824
	s_waitcnt lgkmcnt(4)
	v_mfma_f32_16x16x32_bf16 v[82:85], v[190:193], v[236:239], v[82:85]
	v_mfma_f32_16x16x32_bf16 v[90:93], v[198:201], v[236:239], v[90:93]
	v_mfma_f32_16x16x32_bf16 v[66:69], v[202:205], v[236:239], v[66:69]
	v_mfma_f32_16x16x32_bf16 v[74:77], v[206:209], v[236:239], v[74:77]
	ds_read_b128 v[236:239], v211 offset:16128
	s_waitcnt lgkmcnt(4)
	v_mfma_f32_16x16x32_bf16 v[86:89], v[190:193], v[240:243], v[86:89]
	v_mfma_f32_16x16x32_bf16 v[94:97], v[198:201], v[240:243], v[94:97]
	v_mfma_f32_16x16x32_bf16 v[70:73], v[202:205], v[240:243], v[70:73]
	v_mfma_f32_16x16x32_bf16 v[78:81], v[206:209], v[240:243], v[78:81]
	ds_read_b128 v[240:243], v215 offset:36928
	s_waitcnt lgkmcnt(4)
	v_mfma_f32_16x16x32_bf16 v[50:53], v[190:193], v[244:247], v[50:53]
	v_mfma_f32_16x16x32_bf16 v[58:61], v[198:201], v[244:247], v[58:61]
	v_mfma_f32_16x16x32_bf16 v[34:37], v[202:205], v[244:247], v[34:37]
	v_mfma_f32_16x16x32_bf16 v[42:45], v[206:209], v[244:247], v[42:45]
	ds_read_b128 v[244:247], v211 offset:64
	s_waitcnt lgkmcnt(4)
	v_mfma_f32_16x16x32_bf16 v[54:57], v[190:193], v[194:197], v[54:57]
	v_mfma_f32_16x16x32_bf16 v[62:65], v[198:201], v[194:197], v[62:65]
	v_mfma_f32_16x16x32_bf16 v[38:41], v[202:205], v[194:197], v[38:41]
	v_mfma_f32_16x16x32_bf16 v[46:49], v[206:209], v[194:197], v[46:49]
	ds_read_b128 v[194:197], v211 offset:2368
	s_waitcnt lgkmcnt(4)
	v_mfma_f32_16x16x32_bf16 v[18:21], v[190:193], v[216:219], v[18:21]
	s_waitcnt lgkmcnt(3)
	v_mfma_f32_16x16x32_bf16 v[22:25], v[190:193], v[236:239], v[22:25]
	ds_read_b128 v[190:193], v215 offset:39232
	v_mfma_f32_16x16x32_bf16 v[26:29], v[198:201], v[216:219], v[26:29]
	v_mfma_f32_16x16x32_bf16 v[30:33], v[198:201], v[236:239], v[30:33]
	ds_read_b128 v[198:201], v215 offset:41536
	v_mfma_f32_16x16x32_bf16 v[2:5], v[202:205], v[216:219], v[2:5]
	v_mfma_f32_16x16x32_bf16 v[6:9], v[202:205], v[236:239], v[6:9]
	ds_read_b128 v[202:205], v215 offset:43840
	v_mfma_f32_16x16x32_bf16 v[10:13], v[206:209], v[216:219], v[10:13]
	ds_read_b128 v[216:219], v211 offset:4672
	v_mfma_f32_16x16x32_bf16 v[14:17], v[206:209], v[236:239], v[14:17]
	ds_read_b128 v[206:209], v211 offset:6976
	ds_read_b128 v[236:239], v211 offset:9280
	s_waitcnt lgkmcnt(7)
	v_mfma_f32_16x16x32_bf16 v[114:117], v[240:243], v[244:247], v[114:117]
	s_waitcnt lgkmcnt(6)
	v_mfma_f32_16x16x32_bf16 v[118:121], v[240:243], v[194:197], v[118:121]
	s_waitcnt lgkmcnt(5)
	v_mfma_f32_16x16x32_bf16 v[122:125], v[190:193], v[244:247], v[122:125]
	v_mfma_f32_16x16x32_bf16 v[126:129], v[190:193], v[194:197], v[126:129]
	s_waitcnt lgkmcnt(4)
	v_mfma_f32_16x16x32_bf16 v[98:101], v[198:201], v[244:247], v[98:101]
	v_mfma_f32_16x16x32_bf16 v[102:105], v[198:201], v[194:197], v[102:105]
	s_waitcnt lgkmcnt(3)
	v_mfma_f32_16x16x32_bf16 v[106:109], v[202:205], v[244:247], v[106:109]
	ds_read_b128 v[244:247], v211 offset:11584
	v_mfma_f32_16x16x32_bf16 v[110:113], v[202:205], v[194:197], v[110:113]
	ds_read_b128 v[194:197], v211 offset:13888
	s_waitcnt lgkmcnt(4)
	v_mfma_f32_16x16x32_bf16 v[82:85], v[240:243], v[216:219], v[82:85]
	v_mfma_f32_16x16x32_bf16 v[90:93], v[190:193], v[216:219], v[90:93]
	v_mfma_f32_16x16x32_bf16 v[66:69], v[198:201], v[216:219], v[66:69]
	v_mfma_f32_16x16x32_bf16 v[74:77], v[202:205], v[216:219], v[74:77]
	ds_read_b128 v[216:219], v211 offset:16192
	s_waitcnt lgkmcnt(4)
	v_mfma_f32_16x16x32_bf16 v[86:89], v[240:243], v[206:209], v[86:89]
	v_mfma_f32_16x16x32_bf16 v[94:97], v[190:193], v[206:209], v[94:97]
	v_mfma_f32_16x16x32_bf16 v[70:73], v[198:201], v[206:209], v[70:73]
	v_mfma_f32_16x16x32_bf16 v[78:81], v[202:205], v[206:209], v[78:81]
	s_waitcnt lgkmcnt(3)
	v_mfma_f32_16x16x32_bf16 v[50:53], v[240:243], v[236:239], v[50:53]
	v_mfma_f32_16x16x32_bf16 v[58:61], v[190:193], v[236:239], v[58:61]
	v_mfma_f32_16x16x32_bf16 v[34:37], v[198:201], v[236:239], v[34:37]
	v_mfma_f32_16x16x32_bf16 v[42:45], v[202:205], v[236:239], v[42:45]
	s_waitcnt lgkmcnt(2)
	v_mfma_f32_16x16x32_bf16 v[54:57], v[240:243], v[244:247], v[54:57]
	v_mfma_f32_16x16x32_bf16 v[62:65], v[190:193], v[244:247], v[62:65]
	v_mfma_f32_16x16x32_bf16 v[38:41], v[198:201], v[244:247], v[38:41]
	v_mfma_f32_16x16x32_bf16 v[46:49], v[202:205], v[244:247], v[46:49]
	s_waitcnt lgkmcnt(1)
	v_mfma_f32_16x16x32_bf16 v[18:21], v[240:243], v[194:197], v[18:21]
	v_mfma_f32_16x16x32_bf16 v[26:29], v[190:193], v[194:197], v[26:29]
	v_mfma_f32_16x16x32_bf16 v[2:5], v[198:201], v[194:197], v[2:5]
	v_mfma_f32_16x16x32_bf16 v[10:13], v[202:205], v[194:197], v[10:13]
	s_waitcnt lgkmcnt(0)
	v_mfma_f32_16x16x32_bf16 v[22:25], v[240:243], v[216:219], v[22:25]
	v_mfma_f32_16x16x32_bf16 v[30:33], v[190:193], v[216:219], v[30:33]
	v_mfma_f32_16x16x32_bf16 v[6:9], v[198:201], v[216:219], v[6:9]
	v_mfma_f32_16x16x32_bf16 v[14:17], v[202:205], v[216:219], v[14:17]
	s_setprio 0
.Ltail_92:
	s_add_i32 s20, s20, 1
	s_cmp_lg_u32 s20, s17
	s_cbranch_scc1 .LBB0_78
	s_nop 7
	v_permlane16_swap_b32_e32 v114, v118
	v_permlane16_swap_b32_e32 v115, v119
	v_permlane16_swap_b32_e32 v116, v120
	v_permlane16_swap_b32_e32 v117, v121
	v_permlane16_swap_b32_e32 v122, v126
	v_permlane16_swap_b32_e32 v123, v127
	v_permlane16_swap_b32_e32 v124, v128
	v_permlane16_swap_b32_e32 v125, v129
	v_permlane32_swap_b32_e32 v114, v118
	v_permlane32_swap_b32_e32 v115, v119
	v_permlane32_swap_b32_e32 v116, v120
	v_permlane32_swap_b32_e32 v117, v121
	v_permlane32_swap_b32_e32 v122, v126
	v_permlane32_swap_b32_e32 v123, v127
	v_permlane32_swap_b32_e32 v124, v128
	v_permlane32_swap_b32_e32 v125, v129
	v_permlane16_swap_b32_e32 v98, v102
	v_permlane16_swap_b32_e32 v99, v103
	v_permlane16_swap_b32_e32 v100, v104
	v_permlane16_swap_b32_e32 v101, v105
	v_permlane16_swap_b32_e32 v106, v110
	v_permlane16_swap_b32_e32 v107, v111
	v_permlane16_swap_b32_e32 v108, v112
	v_permlane16_swap_b32_e32 v109, v113
	v_permlane32_swap_b32_e32 v98, v102
	v_permlane32_swap_b32_e32 v99, v103
	v_permlane32_swap_b32_e32 v100, v104
	v_permlane32_swap_b32_e32 v101, v105
	v_permlane32_swap_b32_e32 v106, v110
	v_permlane32_swap_b32_e32 v107, v111
	v_permlane32_swap_b32_e32 v108, v112
	v_permlane32_swap_b32_e32 v109, v113
	v_permlane16_swap_b32_e32 v82, v86
	v_permlane16_swap_b32_e32 v83, v87
	v_permlane16_swap_b32_e32 v84, v88
	v_permlane16_swap_b32_e32 v85, v89
	v_permlane16_swap_b32_e32 v90, v94
	v_permlane16_swap_b32_e32 v91, v95
	v_permlane16_swap_b32_e32 v92, v96
	v_permlane16_swap_b32_e32 v93, v97
	v_permlane32_swap_b32_e32 v82, v86
	v_permlane32_swap_b32_e32 v83, v87
	v_permlane32_swap_b32_e32 v84, v88
	v_permlane32_swap_b32_e32 v85, v89
	v_permlane32_swap_b32_e32 v90, v94
	v_permlane32_swap_b32_e32 v91, v95
	v_permlane32_swap_b32_e32 v92, v96
	v_permlane32_swap_b32_e32 v93, v97
	v_permlane16_swap_b32_e32 v66, v70
	v_permlane16_swap_b32_e32 v67, v71
	v_permlane16_swap_b32_e32 v68, v72
	v_permlane16_swap_b32_e32 v69, v73
	v_permlane16_swap_b32_e32 v74, v78
	v_permlane16_swap_b32_e32 v75, v79
	v_permlane16_swap_b32_e32 v76, v80
	v_permlane16_swap_b32_e32 v77, v81
	v_permlane32_swap_b32_e32 v66, v70
	v_permlane32_swap_b32_e32 v67, v71
	v_permlane32_swap_b32_e32 v68, v72
	v_permlane32_swap_b32_e32 v69, v73
	v_permlane32_swap_b32_e32 v74, v78
	v_permlane32_swap_b32_e32 v75, v79
	v_permlane32_swap_b32_e32 v76, v80
	v_permlane32_swap_b32_e32 v77, v81
	v_permlane16_swap_b32_e32 v50, v54
	v_permlane16_swap_b32_e32 v51, v55
	v_permlane16_swap_b32_e32 v52, v56
	v_permlane16_swap_b32_e32 v53, v57
	v_permlane16_swap_b32_e32 v58, v62
	v_permlane16_swap_b32_e32 v59, v63
	v_permlane16_swap_b32_e32 v60, v64
	v_permlane16_swap_b32_e32 v61, v65
	v_permlane32_swap_b32_e32 v50, v54
	v_permlane32_swap_b32_e32 v51, v55
	v_permlane32_swap_b32_e32 v52, v56
	v_permlane32_swap_b32_e32 v53, v57
	v_permlane32_swap_b32_e32 v58, v62
	v_permlane32_swap_b32_e32 v59, v63
	v_permlane32_swap_b32_e32 v60, v64
	v_permlane32_swap_b32_e32 v61, v65
	v_permlane16_swap_b32_e32 v34, v38
	v_permlane16_swap_b32_e32 v35, v39
	v_permlane16_swap_b32_e32 v36, v40
	v_permlane16_swap_b32_e32 v37, v41
	v_permlane16_swap_b32_e32 v42, v46
	v_permlane16_swap_b32_e32 v43, v47
	v_permlane16_swap_b32_e32 v44, v48
	v_permlane16_swap_b32_e32 v45, v49
	v_permlane32_swap_b32_e32 v34, v38
	v_permlane32_swap_b32_e32 v35, v39
	v_permlane32_swap_b32_e32 v36, v40
	v_permlane32_swap_b32_e32 v37, v41
	v_permlane32_swap_b32_e32 v42, v46
	v_permlane32_swap_b32_e32 v43, v47
	v_permlane32_swap_b32_e32 v44, v48
	v_permlane32_swap_b32_e32 v45, v49
	v_permlane16_swap_b32_e32 v18, v22
	v_permlane16_swap_b32_e32 v19, v23
	v_permlane16_swap_b32_e32 v20, v24
	v_permlane16_swap_b32_e32 v21, v25
	v_permlane16_swap_b32_e32 v26, v30
	v_permlane16_swap_b32_e32 v27, v31
	v_permlane16_swap_b32_e32 v28, v32
	v_permlane16_swap_b32_e32 v29, v33
	v_permlane32_swap_b32_e32 v18, v22
	v_permlane32_swap_b32_e32 v19, v23
	v_permlane32_swap_b32_e32 v20, v24
	v_permlane32_swap_b32_e32 v21, v25
	v_permlane32_swap_b32_e32 v26, v30
	v_permlane32_swap_b32_e32 v27, v31
	v_permlane32_swap_b32_e32 v28, v32
	v_permlane32_swap_b32_e32 v29, v33
	v_permlane16_swap_b32_e32 v2, v6
	v_permlane16_swap_b32_e32 v3, v7
	v_permlane16_swap_b32_e32 v4, v8
	v_permlane16_swap_b32_e32 v5, v9
	v_permlane16_swap_b32_e32 v10, v14
	v_permlane16_swap_b32_e32 v11, v15
	v_permlane16_swap_b32_e32 v12, v16
	v_permlane16_swap_b32_e32 v13, v17
	v_permlane32_swap_b32_e32 v2, v6
	v_permlane32_swap_b32_e32 v3, v7
	v_permlane32_swap_b32_e32 v4, v8
	v_permlane32_swap_b32_e32 v5, v9
	v_permlane32_swap_b32_e32 v10, v14
	v_permlane32_swap_b32_e32 v11, v15
	v_permlane32_swap_b32_e32 v12, v16
	v_permlane32_swap_b32_e32 v13, v17
	v_mov_b32_e32 v192, v222
	s_bitcmp1_b32 s18, 0
	s_cselect_b64 s[12:13], -1, 0
	v_ashrrev_i32_e32 v193, 31, v192
	v_lshl_add_u64 v[190:191], v[192:193], 2, s[6:7]
	s_mov_b64 s[4:5], -1
	s_and_b64 vcc, exec, s[12:13]
	s_cbranch_vccz .LBB0_159
	s_mov_b64 s[98:99], 0x1000
	global_load_dword v198, v[190:191], off
	global_load_dword v199, v[190:191], off offset:1024
	global_load_dword v202, v[190:191], off offset:2048
	global_load_dword v203, v[190:191], off offset:3072
	v_lshl_add_u64 v[190:191], v[190:191], 0, s[98:99]
	global_load_dword v206, v[190:191], off
	global_load_dword v207, v[190:191], off offset:1024
	global_load_dword v216, v[190:191], off offset:2048
	global_load_dword v217, v[190:191], off offset:3072
	v_lshl_add_u64 v[190:191], v[190:191], 0, s[98:99]
	global_load_dword v236, v[190:191], off
	global_load_dword v237, v[190:191], off offset:1024
	global_load_dword v240, v[190:191], off offset:2048
	global_load_dword v241, v[190:191], off offset:3072
	v_lshl_add_u64 v[190:191], v[190:191], 0, s[98:99]
	global_load_dword v244, v[190:191], off
	global_load_dword v245, v[190:191], off offset:1024
	s_ashr_i32 s4, s18, 3
	s_mul_i32 s4, s4, s82
	s_add_i32 s4, s4, s63
	s_ashr_i32 s5, s4, 31
	s_lshr_b32 s5, s5, 28
	s_add_i32 s5, s4, s5
	s_ashr_i32 s12, s5, 4
	s_and_b32 s5, s5, -16
	s_sub_i32 s13, s4, s5
	s_lshl_b32 s4, s12, 1
	s_and_b32 s5, s13, 1
	s_or_b32 s12, s5, s4
	v_readlane_b32 s4, v252, 35
	s_and_b32 s9, s18, 7
	s_sub_i32 s15, 0x7f, s12
	v_readlane_b32 s5, v252, 36
	s_and_b64 s[4:5], s[4:5], exec
	s_cselect_b32 s4, s15, s12
	s_ashr_i32 s5, s4, 31
	v_and_b32_e32 v194, 0xffffff80, v192
	s_lshl_b64 s[4:5], s[4:5], 8
	v_ashrrev_i32_e32 v195, 31, v194
	v_lshl_add_u64 v[194:195], s[4:5], 0, v[194:195]
	v_lshrrev_b32_e32 v179, 3, v192
	v_and_or_b32 v194, v192, 31, v194
	v_and_b32_e32 v179, 4, v179
	v_and_b32_e32 v0, 64, v192
	v_lshlrev_b64 v[192:193], 11, v[194:195]
	v_lshlrev_b32_e32 v194, 1, v179
	s_lshl_b32 s4, s13, 6
	s_and_b32 s4, s4, 0xffffff80
	s_ashr_i32 s5, s4, 31
	v_lshl_add_u64 v[192:193], s[2:3], 0, v[192:193]
	v_lshl_add_u64 v[192:193], s[4:5], 1, v[192:193]
	v_lshlrev_b32_e32 v0, 1, v0
	s_cmp_lg_u32 s9, 1
	v_lshl_add_u64 v[196:197], v[192:193], 0, v[0:1]
	v_mov_b32_e32 v195, v1
	s_cselect_b64 s[12:13], -1, 0
	s_cmp_eq_u32 s9, 1
	v_lshl_add_u64 v[196:197], v[196:197], 0, v[194:195]
	v_lshl_add_u64 v[192:193], v[196:197], 0, 0
	s_cbranch_scc1 .Lme_noold
	global_load_dwordx2 v[200:201], v[192:193], off
	global_load_dwordx2 v[204:205], v[192:193], off offset:16
	global_load_dwordx2 v[208:209], v[192:193], off offset:32
	global_load_dwordx2 v[218:219], v[192:193], off offset:48
	global_load_dwordx2 v[238:239], v[192:193], off offset:64
	global_load_dwordx2 v[242:243], v[192:193], off offset:80
	global_load_dwordx2 v[246:247], v[192:193], off offset:96
	s_waitcnt vmcnt(6)
	v_lshlrev_b32_e32 v194, 16, v198
	v_and_b32_e32 v195, 0xffff0000, v198
	v_lshlrev_b32_e32 v220, 16, v199
	v_and_b32_e32 v221, 0xffff0000, v199
	v_pk_mul_f32 v[194:195], v[114:115], v[194:195]
	v_pk_mul_f32 v[220:221], v[116:117], v[220:221]
	v_lshlrev_b32_e32 v198, 16, v200
	v_and_b32_e32 v199, 0xffff0000, v200
	v_lshlrev_b32_e32 v200, 16, v201
	v_and_b32_e32 v201, 0xffff0000, v201
	v_pk_add_f32 v[194:195], v[194:195], v[198:199]
	v_pk_add_f32 v[220:221], v[220:221], v[200:201]
	v_cvt_pk_bf16_f32 v198, v194, v195
	v_cvt_pk_bf16_f32 v199, v220, v221
	global_store_dwordx2 v[196:197], v[198:199], off
	global_load_dword v198, v[190:191], off offset:2048
	global_load_dword v199, v[190:191], off offset:3072
	global_load_dwordx2 v[200:201], v[192:193], off offset:112
	s_waitcnt vmcnt(9)
	v_lshlrev_b32_e32 v194, 16, v202
	v_and_b32_e32 v195, 0xffff0000, v202
	v_lshlrev_b32_e32 v220, 16, v203
	v_and_b32_e32 v221, 0xffff0000, v203
	v_pk_mul_f32 v[194:195], v[118:119], v[194:195]
	v_pk_mul_f32 v[220:221], v[120:121], v[220:221]
	v_lshlrev_b32_e32 v202, 16, v204
	v_and_b32_e32 v203, 0xffff0000, v204
	v_lshlrev_b32_e32 v204, 16, v205
	v_and_b32_e32 v205, 0xffff0000, v205
	v_pk_add_f32 v[194:195], v[194:195], v[202:203]
	v_pk_add_f32 v[220:221], v[220:221], v[204:205]
	v_cvt_pk_bf16_f32 v202, v194, v195
	v_cvt_pk_bf16_f32 v203, v220, v221
	global_store_dwordx2 v[196:197], v[202:203], off offset:16
	v_lshl_add_u64 v[190:191], v[190:191], 0, s[98:99]
	global_load_dword v202, v[190:191], off
	global_load_dword v203, v[190:191], off offset:1024
	v_lshl_add_u64 v[192:193], v[192:193], 0, s[90:91]
	global_load_dwordx2 v[204:205], v[192:193], off
	s_waitcnt vmcnt(12)
	v_lshlrev_b32_e32 v194, 16, v206
	v_and_b32_e32 v195, 0xffff0000, v206
	v_lshlrev_b32_e32 v220, 16, v207
	v_and_b32_e32 v221, 0xffff0000, v207
	v_pk_mul_f32 v[194:195], v[122:123], v[194:195]
	v_pk_mul_f32 v[220:221], v[124:125], v[220:221]
	v_lshlrev_b32_e32 v206, 16, v208
	v_and_b32_e32 v207, 0xffff0000, v208
	v_lshlrev_b32_e32 v208, 16, v209
	v_and_b32_e32 v209, 0xffff0000, v209
	v_pk_add_f32 v[194:195], v[194:195], v[206:207]
	v_pk_add_f32 v[220:221], v[220:221], v[208:209]
	v_cvt_pk_bf16_f32 v206, v194, v195
	v_cvt_pk_bf16_f32 v207, v220, v221
	global_store_dwordx2 v[196:197], v[206:207], off offset:32
	global_load_dword v206, v[190:191], off offset:2048
	global_load_dword v207, v[190:191], off offset:3072
	global_load_dwordx2 v[208:209], v[192:193], off offset:16
	s_waitcnt vmcnt(15)
	v_lshlrev_b32_e32 v194, 16, v216
	v_and_b32_e32 v195, 0xffff0000, v216
	v_lshlrev_b32_e32 v220, 16, v217
	v_and_b32_e32 v221, 0xffff0000, v217
	v_pk_mul_f32 v[194:195], v[126:127], v[194:195]
	v_pk_mul_f32 v[220:221], v[128:129], v[220:221]
	v_lshlrev_b32_e32 v216, 16, v218
	v_and_b32_e32 v217, 0xffff0000, v218
	v_lshlrev_b32_e32 v218, 16, v219
	v_and_b32_e32 v219, 0xffff0000, v219
	v_pk_add_f32 v[194:195], v[194:195], v[216:217]
	v_pk_add_f32 v[220:221], v[220:221], v[218:219]
	v_cvt_pk_bf16_f32 v216, v194, v195
	v_cvt_pk_bf16_f32 v217, v220, v221
	global_store_dwordx2 v[196:197], v[216:217], off offset:48
	v_lshl_add_u64 v[190:191], v[190:191], 0, s[98:99]
	global_load_dword v216, v[190:191], off
	global_load_dword v217, v[190:191], off offset:1024
	global_load_dwordx2 v[218:219], v[192:193], off offset:32
	s_waitcnt vmcnt(18)
	v_lshlrev_b32_e32 v194, 16, v236
	v_and_b32_e32 v195, 0xffff0000, v236
	v_lshlrev_b32_e32 v220, 16, v237
	v_and_b32_e32 v221, 0xffff0000, v237
	v_pk_mul_f32 v[194:195], v[98:99], v[194:195]
	v_pk_mul_f32 v[220:221], v[100:101], v[220:221]
	v_lshlrev_b32_e32 v236, 16, v238
	v_and_b32_e32 v237, 0xffff0000, v238
	v_lshlrev_b32_e32 v238, 16, v239
	v_and_b32_e32 v239, 0xffff0000, v239
	v_pk_add_f32 v[194:195], v[194:195], v[236:237]
	v_pk_add_f32 v[220:221], v[220:221], v[238:239]
	v_cvt_pk_bf16_f32 v236, v194, v195
	v_cvt_pk_bf16_f32 v237, v220, v221
	global_store_dwordx2 v[196:197], v[236:237], off offset:64
	global_load_dword v236, v[190:191], off offset:2048
	global_load_dword v237, v[190:191], off offset:3072
	global_load_dwordx2 v[238:239], v[192:193], off offset:48
	s_waitcnt vmcnt(21)
	v_lshlrev_b32_e32 v194, 16, v240
	v_and_b32_e32 v195, 0xffff0000, v240
	v_lshlrev_b32_e32 v220, 16, v241
	v_and_b32_e32 v221, 0xffff0000, v241
	v_pk_mul_f32 v[194:195], v[102:103], v[194:195]
	v_pk_mul_f32 v[220:221], v[104:105], v[220:221]
	v_lshlrev_b32_e32 v240, 16, v242
	v_and_b32_e32 v241, 0xffff0000, v242
	v_lshlrev_b32_e32 v242, 16, v243
	v_and_b32_e32 v243, 0xffff0000, v243
	v_pk_add_f32 v[194:195], v[194:195], v[240:241]
	v_pk_add_f32 v[220:221], v[220:221], v[242:243]
	v_cvt_pk_bf16_f32 v240, v194, v195
	v_cvt_pk_bf16_f32 v241, v220, v221
	global_store_dwordx2 v[196:197], v[240:241], off offset:80
	v_lshl_add_u64 v[190:191], v[190:191], 0, s[98:99]
	global_load_dword v240, v[190:191], off
	global_load_dword v241, v[190:191], off offset:1024
	global_load_dwordx2 v[242:243], v[192:193], off offset:64
	s_waitcnt vmcnt(24)
	v_lshlrev_b32_e32 v194, 16, v244
	v_and_b32_e32 v195, 0xffff0000, v244
	v_lshlrev_b32_e32 v220, 16, v245
	v_and_b32_e32 v221, 0xffff0000, v245
	v_pk_mul_f32 v[194:195], v[106:107], v[194:195]
	v_pk_mul_f32 v[220:221], v[108:109], v[220:221]
	v_lshlrev_b32_e32 v244, 16, v246
	v_and_b32_e32 v245, 0xffff0000, v246
	v_lshlrev_b32_e32 v246, 16, v247
	v_and_b32_e32 v247, 0xffff0000, v247
	v_pk_add_f32 v[194:195], v[194:195], v[244:245]
	v_pk_add_f32 v[220:221], v[220:221], v[246:247]
	v_cvt_pk_bf16_f32 v244, v194, v195
	v_cvt_pk_bf16_f32 v245, v220, v221
	global_store_dwordx2 v[196:197], v[244:245], off offset:96
	global_load_dword v244, v[190:191], off offset:2048
	global_load_dword v245, v[190:191], off offset:3072
	global_load_dwordx2 v[246:247], v[192:193], off offset:80
	s_waitcnt vmcnt(24)
	v_lshlrev_b32_e32 v194, 16, v198
	v_and_b32_e32 v195, 0xffff0000, v198
	v_lshlrev_b32_e32 v220, 16, v199
	v_and_b32_e32 v221, 0xffff0000, v199
	v_pk_mul_f32 v[194:195], v[110:111], v[194:195]
	v_pk_mul_f32 v[220:221], v[112:113], v[220:221]
	v_lshlrev_b32_e32 v198, 16, v200
	v_and_b32_e32 v199, 0xffff0000, v200
	v_lshlrev_b32_e32 v200, 16, v201
	v_and_b32_e32 v201, 0xffff0000, v201
	v_pk_add_f32 v[194:195], v[194:195], v[198:199]
	v_pk_add_f32 v[220:221], v[220:221], v[200:201]
	v_cvt_pk_bf16_f32 v198, v194, v195
	v_cvt_pk_bf16_f32 v199, v220, v221
	global_store_dwordx2 v[196:197], v[198:199], off offset:112
	v_lshl_add_u64 v[190:191], v[190:191], 0, s[98:99]
	global_load_dword v198, v[190:191], off
	global_load_dword v199, v[190:191], off offset:1024
	global_load_dwordx2 v[200:201], v[192:193], off offset:96
	s_waitcnt vmcnt(24)
	v_lshlrev_b32_e32 v194, 16, v202
	v_and_b32_e32 v195, 0xffff0000, v202
	v_lshlrev_b32_e32 v220, 16, v203
	v_and_b32_e32 v221, 0xffff0000, v203
	v_pk_mul_f32 v[194:195], v[82:83], v[194:195]
	v_pk_mul_f32 v[220:221], v[84:85], v[220:221]
	v_lshlrev_b32_e32 v202, 16, v204
	v_and_b32_e32 v203, 0xffff0000, v204
	v_lshlrev_b32_e32 v204, 16, v205
	v_and_b32_e32 v205, 0xffff0000, v205
	v_pk_add_f32 v[194:195], v[194:195], v[202:203]
	v_pk_add_f32 v[220:221], v[220:221], v[204:205]
	v_cvt_pk_bf16_f32 v202, v194, v195
	v_cvt_pk_bf16_f32 v203, v220, v221
	v_lshl_add_u64 v[196:197], v[196:197], 0, s[90:91]
	global_store_dwordx2 v[196:197], v[202:203], off
	global_load_dword v202, v[190:191], off offset:2048
	global_load_dword v203, v[190:191], off offset:3072
	global_load_dwordx2 v[204:205], v[192:193], off offset:112
	s_waitcnt vmcnt(24)
	v_lshlrev_b32_e32 v194, 16, v206
	v_and_b32_e32 v195, 0xffff0000, v206
	v_lshlrev_b32_e32 v220, 16, v207
	v_and_b32_e32 v221, 0xffff0000, v207
	v_pk_mul_f32 v[194:195], v[86:87], v[194:195]
	v_pk_mul_f32 v[220:221], v[88:89], v[220:221]
	v_lshlrev_b32_e32 v206, 16, v208
	v_and_b32_e32 v207, 0xffff0000, v208
	v_lshlrev_b32_e32 v208, 16, v209
	v_and_b32_e32 v209, 0xffff0000, v209
	v_pk_add_f32 v[194:195], v[194:195], v[206:207]
	v_pk_add_f32 v[220:221], v[220:221], v[208:209]
	v_cvt_pk_bf16_f32 v206, v194, v195
	v_cvt_pk_bf16_f32 v207, v220, v221
	global_store_dwordx2 v[196:197], v[206:207], off offset:16
	v_lshl_add_u64 v[190:191], v[190:191], 0, s[98:99]
	global_load_dword v206, v[190:191], off
	global_load_dword v207, v[190:191], off offset:1024
	v_lshl_add_u64 v[192:193], v[192:193], 0, s[90:91]
	global_load_dwordx2 v[208:209], v[192:193], off
	s_waitcnt vmcnt(24)
	v_lshlrev_b32_e32 v194, 16, v216
	v_and_b32_e32 v195, 0xffff0000, v216
	v_lshlrev_b32_e32 v220, 16, v217
	v_and_b32_e32 v221, 0xffff0000, v217
	v_pk_mul_f32 v[194:195], v[90:91], v[194:195]
	v_pk_mul_f32 v[220:221], v[92:93], v[220:221]
	v_lshlrev_b32_e32 v216, 16, v218
	v_and_b32_e32 v217, 0xffff0000, v218
	v_lshlrev_b32_e32 v218, 16, v219
	v_and_b32_e32 v219, 0xffff0000, v219
	v_pk_add_f32 v[194:195], v[194:195], v[216:217]
	v_pk_add_f32 v[220:221], v[220:221], v[218:219]
	v_cvt_pk_bf16_f32 v216, v194, v195
	v_cvt_pk_bf16_f32 v217, v220, v221
	global_store_dwordx2 v[196:197], v[216:217], off offset:32
	global_load_dword v216, v[190:191], off offset:2048
	global_load_dword v217, v[190:191], off offset:3072
	global_load_dwordx2 v[218:219], v[192:193], off offset:16
	s_waitcnt vmcnt(24)
	v_lshlrev_b32_e32 v194, 16, v236
	v_and_b32_e32 v195, 0xffff0000, v236
	v_lshlrev_b32_e32 v220, 16, v237
	v_and_b32_e32 v221, 0xffff0000, v237
	v_pk_mul_f32 v[194:195], v[94:95], v[194:195]
	v_pk_mul_f32 v[220:221], v[96:97], v[220:221]
	v_lshlrev_b32_e32 v236, 16, v238
	v_and_b32_e32 v237, 0xffff0000, v238
	v_lshlrev_b32_e32 v238, 16, v239
	v_and_b32_e32 v239, 0xffff0000, v239
	v_pk_add_f32 v[194:195], v[194:195], v[236:237]
	v_pk_add_f32 v[220:221], v[220:221], v[238:239]
	v_cvt_pk_bf16_f32 v236, v194, v195
	v_cvt_pk_bf16_f32 v237, v220, v221
	global_store_dwordx2 v[196:197], v[236:237], off offset:48
	v_lshl_add_u64 v[190:191], v[190:191], 0, s[98:99]
	global_load_dword v236, v[190:191], off
	global_load_dword v237, v[190:191], off offset:1024
	global_load_dwordx2 v[238:239], v[192:193], off offset:32
	s_waitcnt vmcnt(24)
	v_lshlrev_b32_e32 v194, 16, v240
	v_and_b32_e32 v195, 0xffff0000, v240
	v_lshlrev_b32_e32 v220, 16, v241
	v_and_b32_e32 v221, 0xffff0000, v241
	v_pk_mul_f32 v[194:195], v[66:67], v[194:195]
	v_pk_mul_f32 v[220:221], v[68:69], v[220:221]
	v_lshlrev_b32_e32 v240, 16, v242
	v_and_b32_e32 v241, 0xffff0000, v242
	v_lshlrev_b32_e32 v242, 16, v243
	v_and_b32_e32 v243, 0xffff0000, v243
	v_pk_add_f32 v[194:195], v[194:195], v[240:241]
	v_pk_add_f32 v[220:221], v[220:221], v[242:243]
	v_cvt_pk_bf16_f32 v240, v194, v195
	v_cvt_pk_bf16_f32 v241, v220, v221
	global_store_dwordx2 v[196:197], v[240:241], off offset:64
	global_load_dword v240, v[190:191], off offset:2048
	global_load_dword v241, v[190:191], off offset:3072
	global_load_dwordx2 v[242:243], v[192:193], off offset:48
	s_waitcnt vmcnt(24)
	v_lshlrev_b32_e32 v194, 16, v244
	v_and_b32_e32 v195, 0xffff0000, v244
	v_lshlrev_b32_e32 v220, 16, v245
	v_and_b32_e32 v221, 0xffff0000, v245
	v_pk_mul_f32 v[194:195], v[70:71], v[194:195]
	v_pk_mul_f32 v[220:221], v[72:73], v[220:221]
	v_lshlrev_b32_e32 v244, 16, v246
	v_and_b32_e32 v245, 0xffff0000, v246
	v_lshlrev_b32_e32 v246, 16, v247
	v_and_b32_e32 v247, 0xffff0000, v247
	v_pk_add_f32 v[194:195], v[194:195], v[244:245]
	v_pk_add_f32 v[220:221], v[220:221], v[246:247]
	v_cvt_pk_bf16_f32 v244, v194, v195
	v_cvt_pk_bf16_f32 v245, v220, v221
	global_store_dwordx2 v[196:197], v[244:245], off offset:80
	v_lshl_add_u64 v[190:191], v[190:191], 0, s[98:99]
	global_load_dword v244, v[190:191], off
	global_load_dword v245, v[190:191], off offset:1024
	global_load_dwordx2 v[246:247], v[192:193], off offset:64
	s_waitcnt vmcnt(24)
	v_lshlrev_b32_e32 v194, 16, v198
	v_and_b32_e32 v195, 0xffff0000, v198
	v_lshlrev_b32_e32 v220, 16, v199
	v_and_b32_e32 v221, 0xffff0000, v199
	v_pk_mul_f32 v[194:195], v[74:75], v[194:195]
	v_pk_mul_f32 v[220:221], v[76:77], v[220:221]
	v_lshlrev_b32_e32 v198, 16, v200
	v_and_b32_e32 v199, 0xffff0000, v200
	v_lshlrev_b32_e32 v200, 16, v201
	v_and_b32_e32 v201, 0xffff0000, v201
	v_pk_add_f32 v[194:195], v[194:195], v[198:199]
	v_pk_add_f32 v[220:221], v[220:221], v[200:201]
	v_cvt_pk_bf16_f32 v198, v194, v195
	v_cvt_pk_bf16_f32 v199, v220, v221
	global_store_dwordx2 v[196:197], v[198:199], off offset:96
	global_load_dword v198, v[190:191], off offset:2048
	global_load_dword v199, v[190:191], off offset:3072
	global_load_dwordx2 v[200:201], v[192:193], off offset:80
	s_waitcnt vmcnt(24)
	v_lshlrev_b32_e32 v194, 16, v202
	v_and_b32_e32 v195, 0xffff0000, v202
	v_lshlrev_b32_e32 v220, 16, v203
	v_and_b32_e32 v221, 0xffff0000, v203
	v_pk_mul_f32 v[194:195], v[78:79], v[194:195]
	v_pk_mul_f32 v[220:221], v[80:81], v[220:221]
	v_lshlrev_b32_e32 v202, 16, v204
	v_and_b32_e32 v203, 0xffff0000, v204
	v_lshlrev_b32_e32 v204, 16, v205
	v_and_b32_e32 v205, 0xffff0000, v205
	v_pk_add_f32 v[194:195], v[194:195], v[202:203]
	v_pk_add_f32 v[220:221], v[220:221], v[204:205]
	v_cvt_pk_bf16_f32 v202, v194, v195
	v_cvt_pk_bf16_f32 v203, v220, v221
	global_store_dwordx2 v[196:197], v[202:203], off offset:112
	v_lshl_add_u64 v[190:191], v[190:191], 0, s[98:99]
	global_load_dword v202, v[190:191], off
	global_load_dword v203, v[190:191], off offset:1024
	global_load_dwordx2 v[204:205], v[192:193], off offset:96
	s_waitcnt vmcnt(24)
	v_lshlrev_b32_e32 v194, 16, v206
	v_and_b32_e32 v195, 0xffff0000, v206
	v_lshlrev_b32_e32 v220, 16, v207
	v_and_b32_e32 v221, 0xffff0000, v207
	v_pk_mul_f32 v[194:195], v[50:51], v[194:195]
	v_pk_mul_f32 v[220:221], v[52:53], v[220:221]
	v_lshlrev_b32_e32 v206, 16, v208
	v_and_b32_e32 v207, 0xffff0000, v208
	v_lshlrev_b32_e32 v208, 16, v209
	v_and_b32_e32 v209, 0xffff0000, v209
	v_pk_add_f32 v[194:195], v[194:195], v[206:207]
	v_pk_add_f32 v[220:221], v[220:221], v[208:209]
	v_cvt_pk_bf16_f32 v206, v194, v195
	v_cvt_pk_bf16_f32 v207, v220, v221
	v_lshl_add_u64 v[196:197], v[196:197], 0, s[90:91]
	global_store_dwordx2 v[196:197], v[206:207], off
	global_load_dword v206, v[190:191], off offset:2048
	global_load_dword v207, v[190:191], off offset:3072
	global_load_dwordx2 v[208:209], v[192:193], off offset:112
	s_waitcnt vmcnt(24)
	v_lshlrev_b32_e32 v194, 16, v216
	v_and_b32_e32 v195, 0xffff0000, v216
	v_lshlrev_b32_e32 v220, 16, v217
	v_and_b32_e32 v221, 0xffff0000, v217
	v_pk_mul_f32 v[194:195], v[54:55], v[194:195]
	v_pk_mul_f32 v[220:221], v[56:57], v[220:221]
	v_lshlrev_b32_e32 v216, 16, v218
	v_and_b32_e32 v217, 0xffff0000, v218
	v_lshlrev_b32_e32 v218, 16, v219
	v_and_b32_e32 v219, 0xffff0000, v219
	v_pk_add_f32 v[194:195], v[194:195], v[216:217]
	v_pk_add_f32 v[220:221], v[220:221], v[218:219]
	v_cvt_pk_bf16_f32 v216, v194, v195
	v_cvt_pk_bf16_f32 v217, v220, v221
	global_store_dwordx2 v[196:197], v[216:217], off offset:16
	v_lshl_add_u64 v[190:191], v[190:191], 0, s[98:99]
	global_load_dword v216, v[190:191], off
	global_load_dword v217, v[190:191], off offset:1024
	v_lshl_add_u64 v[192:193], v[192:193], 0, s[90:91]
	global_load_dwordx2 v[218:219], v[192:193], off
	s_waitcnt vmcnt(24)
	v_lshlrev_b32_e32 v194, 16, v236
	v_and_b32_e32 v195, 0xffff0000, v236
	v_lshlrev_b32_e32 v220, 16, v237
	v_and_b32_e32 v221, 0xffff0000, v237
	v_pk_mul_f32 v[194:195], v[58:59], v[194:195]
	v_pk_mul_f32 v[220:221], v[60:61], v[220:221]
	v_lshlrev_b32_e32 v236, 16, v238
	v_and_b32_e32 v237, 0xffff0000, v238
	v_lshlrev_b32_e32 v238, 16, v239
	v_and_b32_e32 v239, 0xffff0000, v239
	v_pk_add_f32 v[194:195], v[194:195], v[236:237]
	v_pk_add_f32 v[220:221], v[220:221], v[238:239]
	v_cvt_pk_bf16_f32 v236, v194, v195
	v_cvt_pk_bf16_f32 v237, v220, v221
	global_store_dwordx2 v[196:197], v[236:237], off offset:32
	global_load_dword v236, v[190:191], off offset:2048
	global_load_dword v237, v[190:191], off offset:3072
	global_load_dwordx2 v[238:239], v[192:193], off offset:16
	s_waitcnt vmcnt(24)
	v_lshlrev_b32_e32 v194, 16, v240
	v_and_b32_e32 v195, 0xffff0000, v240
	v_lshlrev_b32_e32 v220, 16, v241
	v_and_b32_e32 v221, 0xffff0000, v241
	v_pk_mul_f32 v[194:195], v[62:63], v[194:195]
	v_pk_mul_f32 v[220:221], v[64:65], v[220:221]
	v_lshlrev_b32_e32 v240, 16, v242
	v_and_b32_e32 v241, 0xffff0000, v242
	v_lshlrev_b32_e32 v242, 16, v243
	v_and_b32_e32 v243, 0xffff0000, v243
	v_pk_add_f32 v[194:195], v[194:195], v[240:241]
	v_pk_add_f32 v[220:221], v[220:221], v[242:243]
	v_cvt_pk_bf16_f32 v240, v194, v195
	v_cvt_pk_bf16_f32 v241, v220, v221
	global_store_dwordx2 v[196:197], v[240:241], off offset:48
	v_lshl_add_u64 v[190:191], v[190:191], 0, s[98:99]
	global_load_dword v240, v[190:191], off
	global_load_dword v241, v[190:191], off offset:1024
	global_load_dwordx2 v[242:243], v[192:193], off offset:32
	s_waitcnt vmcnt(24)
	v_lshlrev_b32_e32 v194, 16, v244
	v_and_b32_e32 v195, 0xffff0000, v244
	v_lshlrev_b32_e32 v220, 16, v245
	v_and_b32_e32 v221, 0xffff0000, v245
	v_pk_mul_f32 v[194:195], v[34:35], v[194:195]
	v_pk_mul_f32 v[220:221], v[36:37], v[220:221]
	v_lshlrev_b32_e32 v244, 16, v246
	v_and_b32_e32 v245, 0xffff0000, v246
	v_lshlrev_b32_e32 v246, 16, v247
	v_and_b32_e32 v247, 0xffff0000, v247
	v_pk_add_f32 v[194:195], v[194:195], v[244:245]
	v_pk_add_f32 v[220:221], v[220:221], v[246:247]
	v_cvt_pk_bf16_f32 v244, v194, v195
	v_cvt_pk_bf16_f32 v245, v220, v221
	global_store_dwordx2 v[196:197], v[244:245], off offset:64
	global_load_dword v244, v[190:191], off offset:2048
	global_load_dword v245, v[190:191], off offset:3072
	global_load_dwordx2 v[246:247], v[192:193], off offset:48
	s_waitcnt vmcnt(24)
	v_lshlrev_b32_e32 v194, 16, v198
	v_and_b32_e32 v195, 0xffff0000, v198
	v_lshlrev_b32_e32 v220, 16, v199
	v_and_b32_e32 v221, 0xffff0000, v199
	v_pk_mul_f32 v[194:195], v[38:39], v[194:195]
	v_pk_mul_f32 v[220:221], v[40:41], v[220:221]
	v_lshlrev_b32_e32 v198, 16, v200
	v_and_b32_e32 v199, 0xffff0000, v200
	v_lshlrev_b32_e32 v200, 16, v201
	v_and_b32_e32 v201, 0xffff0000, v201
	v_pk_add_f32 v[194:195], v[194:195], v[198:199]
	v_pk_add_f32 v[220:221], v[220:221], v[200:201]
	v_cvt_pk_bf16_f32 v198, v194, v195
	v_cvt_pk_bf16_f32 v199, v220, v221
	global_store_dwordx2 v[196:197], v[198:199], off offset:80
	v_lshl_add_u64 v[190:191], v[190:191], 0, s[98:99]
	global_load_dword v198, v[190:191], off
	global_load_dword v199, v[190:191], off offset:1024
	global_load_dwordx2 v[200:201], v[192:193], off offset:64
	s_waitcnt vmcnt(24)
	v_lshlrev_b32_e32 v194, 16, v202
	v_and_b32_e32 v195, 0xffff0000, v202
	v_lshlrev_b32_e32 v220, 16, v203
	v_and_b32_e32 v221, 0xffff0000, v203
	v_pk_mul_f32 v[194:195], v[42:43], v[194:195]
	v_pk_mul_f32 v[220:221], v[44:45], v[220:221]
	v_lshlrev_b32_e32 v202, 16, v204
	v_and_b32_e32 v203, 0xffff0000, v204
	v_lshlrev_b32_e32 v204, 16, v205
	v_and_b32_e32 v205, 0xffff0000, v205
	v_pk_add_f32 v[194:195], v[194:195], v[202:203]
	v_pk_add_f32 v[220:221], v[220:221], v[204:205]
	v_cvt_pk_bf16_f32 v202, v194, v195
	v_cvt_pk_bf16_f32 v203, v220, v221
	global_store_dwordx2 v[196:197], v[202:203], off offset:96
	global_load_dword v202, v[190:191], off offset:2048
	global_load_dword v203, v[190:191], off offset:3072
	global_load_dwordx2 v[204:205], v[192:193], off offset:80
	s_waitcnt vmcnt(24)
	v_lshlrev_b32_e32 v194, 16, v206
	v_and_b32_e32 v195, 0xffff0000, v206
	v_lshlrev_b32_e32 v220, 16, v207
	v_and_b32_e32 v221, 0xffff0000, v207
	v_pk_mul_f32 v[194:195], v[46:47], v[194:195]
	v_pk_mul_f32 v[220:221], v[48:49], v[220:221]
	v_lshlrev_b32_e32 v206, 16, v208
	v_and_b32_e32 v207, 0xffff0000, v208
	v_lshlrev_b32_e32 v208, 16, v209
	v_and_b32_e32 v209, 0xffff0000, v209
	v_pk_add_f32 v[194:195], v[194:195], v[206:207]
	v_pk_add_f32 v[220:221], v[220:221], v[208:209]
	v_cvt_pk_bf16_f32 v206, v194, v195
	v_cvt_pk_bf16_f32 v207, v220, v221
	global_store_dwordx2 v[196:197], v[206:207], off offset:112
	v_lshl_add_u64 v[190:191], v[190:191], 0, s[98:99]
	global_load_dword v206, v[190:191], off
	global_load_dword v207, v[190:191], off offset:1024
	global_load_dwordx2 v[208:209], v[192:193], off offset:96
	s_waitcnt vmcnt(24)
	v_lshlrev_b32_e32 v194, 16, v216
	v_and_b32_e32 v195, 0xffff0000, v216
	v_lshlrev_b32_e32 v220, 16, v217
	v_and_b32_e32 v221, 0xffff0000, v217
	v_pk_mul_f32 v[194:195], v[18:19], v[194:195]
	v_pk_mul_f32 v[220:221], v[20:21], v[220:221]
	v_lshlrev_b32_e32 v216, 16, v218
	v_and_b32_e32 v217, 0xffff0000, v218
	v_lshlrev_b32_e32 v218, 16, v219
	v_and_b32_e32 v219, 0xffff0000, v219
	v_pk_add_f32 v[194:195], v[194:195], v[216:217]
	v_pk_add_f32 v[220:221], v[220:221], v[218:219]
	v_cvt_pk_bf16_f32 v216, v194, v195
	v_cvt_pk_bf16_f32 v217, v220, v221
	v_lshl_add_u64 v[196:197], v[196:197], 0, s[90:91]
	global_store_dwordx2 v[196:197], v[216:217], off
	global_load_dword v216, v[190:191], off offset:2048
	global_load_dword v217, v[190:191], off offset:3072
	global_load_dwordx2 v[218:219], v[192:193], off offset:112
	s_waitcnt vmcnt(24)
	v_lshlrev_b32_e32 v194, 16, v236
	v_and_b32_e32 v195, 0xffff0000, v236
	v_lshlrev_b32_e32 v220, 16, v237
	v_and_b32_e32 v221, 0xffff0000, v237
	v_pk_mul_f32 v[194:195], v[22:23], v[194:195]
	v_pk_mul_f32 v[220:221], v[24:25], v[220:221]
	v_lshlrev_b32_e32 v236, 16, v238
	v_and_b32_e32 v237, 0xffff0000, v238
	v_lshlrev_b32_e32 v238, 16, v239
	v_and_b32_e32 v239, 0xffff0000, v239
	v_pk_add_f32 v[194:195], v[194:195], v[236:237]
	v_pk_add_f32 v[220:221], v[220:221], v[238:239]
	v_cvt_pk_bf16_f32 v236, v194, v195
	v_cvt_pk_bf16_f32 v237, v220, v221
	global_store_dwordx2 v[196:197], v[236:237], off offset:16
	s_waitcnt vmcnt(21)
	v_lshlrev_b32_e32 v194, 16, v240
	v_and_b32_e32 v195, 0xffff0000, v240
	v_lshlrev_b32_e32 v220, 16, v241
	v_and_b32_e32 v221, 0xffff0000, v241
	v_pk_mul_f32 v[194:195], v[26:27], v[194:195]
	v_pk_mul_f32 v[220:221], v[28:29], v[220:221]
	v_lshlrev_b32_e32 v240, 16, v242
	v_and_b32_e32 v241, 0xffff0000, v242
	v_lshlrev_b32_e32 v242, 16, v243
	v_and_b32_e32 v243, 0xffff0000, v243
	v_pk_add_f32 v[194:195], v[194:195], v[240:241]
	v_pk_add_f32 v[220:221], v[220:221], v[242:243]
	v_cvt_pk_bf16_f32 v240, v194, v195
	v_cvt_pk_bf16_f32 v241, v220, v221
	global_store_dwordx2 v[196:197], v[240:241], off offset:32
	s_waitcnt vmcnt(18)
	v_lshlrev_b32_e32 v194, 16, v244
	v_and_b32_e32 v195, 0xffff0000, v244
	v_lshlrev_b32_e32 v220, 16, v245
	v_and_b32_e32 v221, 0xffff0000, v245
	v_pk_mul_f32 v[194:195], v[30:31], v[194:195]
	v_pk_mul_f32 v[220:221], v[32:33], v[220:221]
	v_lshlrev_b32_e32 v244, 16, v246
	v_and_b32_e32 v245, 0xffff0000, v246
	v_lshlrev_b32_e32 v246, 16, v247
	v_and_b32_e32 v247, 0xffff0000, v247
	v_pk_add_f32 v[194:195], v[194:195], v[244:245]
	v_pk_add_f32 v[220:221], v[220:221], v[246:247]
	v_cvt_pk_bf16_f32 v244, v194, v195
	v_cvt_pk_bf16_f32 v245, v220, v221
	global_store_dwordx2 v[196:197], v[244:245], off offset:48
	s_waitcnt vmcnt(15)
	v_lshlrev_b32_e32 v194, 16, v198
	v_and_b32_e32 v195, 0xffff0000, v198
	v_lshlrev_b32_e32 v220, 16, v199
	v_and_b32_e32 v221, 0xffff0000, v199
	v_pk_mul_f32 v[194:195], v[2:3], v[194:195]
	v_pk_mul_f32 v[220:221], v[4:5], v[220:221]
	v_lshlrev_b32_e32 v198, 16, v200
	v_and_b32_e32 v199, 0xffff0000, v200
	v_lshlrev_b32_e32 v200, 16, v201
	v_and_b32_e32 v201, 0xffff0000, v201
	v_pk_add_f32 v[194:195], v[194:195], v[198:199]
	v_pk_add_f32 v[220:221], v[220:221], v[200:201]
	v_cvt_pk_bf16_f32 v198, v194, v195
	v_cvt_pk_bf16_f32 v199, v220, v221
	global_store_dwordx2 v[196:197], v[198:199], off offset:64
	s_waitcnt vmcnt(12)
	v_lshlrev_b32_e32 v194, 16, v202
	v_and_b32_e32 v195, 0xffff0000, v202
	v_lshlrev_b32_e32 v220, 16, v203
	v_and_b32_e32 v221, 0xffff0000, v203
	v_pk_mul_f32 v[194:195], v[6:7], v[194:195]
	v_pk_mul_f32 v[220:221], v[8:9], v[220:221]
	v_lshlrev_b32_e32 v202, 16, v204
	v_and_b32_e32 v203, 0xffff0000, v204
	v_lshlrev_b32_e32 v204, 16, v205
	v_and_b32_e32 v205, 0xffff0000, v205
	v_pk_add_f32 v[194:195], v[194:195], v[202:203]
	v_pk_add_f32 v[220:221], v[220:221], v[204:205]
	v_cvt_pk_bf16_f32 v202, v194, v195
	v_cvt_pk_bf16_f32 v203, v220, v221
	global_store_dwordx2 v[196:197], v[202:203], off offset:80
	s_waitcnt vmcnt(9)
	v_lshlrev_b32_e32 v194, 16, v206
	v_and_b32_e32 v195, 0xffff0000, v206
	v_lshlrev_b32_e32 v220, 16, v207
	v_and_b32_e32 v221, 0xffff0000, v207
	v_pk_mul_f32 v[194:195], v[10:11], v[194:195]
	v_pk_mul_f32 v[220:221], v[12:13], v[220:221]
	v_lshlrev_b32_e32 v206, 16, v208
	v_and_b32_e32 v207, 0xffff0000, v208
	v_lshlrev_b32_e32 v208, 16, v209
	v_and_b32_e32 v209, 0xffff0000, v209
	v_pk_add_f32 v[194:195], v[194:195], v[206:207]
	v_pk_add_f32 v[220:221], v[220:221], v[208:209]
	v_cvt_pk_bf16_f32 v206, v194, v195
	v_cvt_pk_bf16_f32 v207, v220, v221
	global_store_dwordx2 v[196:197], v[206:207], off offset:96
	s_waitcnt vmcnt(6)
	v_lshlrev_b32_e32 v194, 16, v216
	v_and_b32_e32 v195, 0xffff0000, v216
	v_lshlrev_b32_e32 v220, 16, v217
	v_and_b32_e32 v221, 0xffff0000, v217
	v_pk_mul_f32 v[194:195], v[14:15], v[194:195]
	v_pk_mul_f32 v[220:221], v[16:17], v[220:221]
	v_lshlrev_b32_e32 v216, 16, v218
	v_and_b32_e32 v217, 0xffff0000, v218
	v_lshlrev_b32_e32 v218, 16, v219
	v_and_b32_e32 v219, 0xffff0000, v219
	v_pk_add_f32 v[194:195], v[194:195], v[216:217]
	v_pk_add_f32 v[220:221], v[220:221], v[218:219]
	v_cvt_pk_bf16_f32 v216, v194, v195
	v_cvt_pk_bf16_f32 v217, v220, v221
	global_store_dwordx2 v[196:197], v[216:217], off offset:112
	s_branch .Lme_done

.LcL_647:
	s_waitcnt lgkmcnt(0)
	s_barrier
	s_setprio 2
	v_bfe_u32 v221, v222, 5, 1
	v_bfe_u32 v248, v222, 4, 1
	v_lshl_add_u32 v211, v221, 4, v182
	v_lshl_add_u32 v215, v221, 4, v183
	v_mul_u32_u24_e32 v221, 0x8f0, v248
	v_mul_u32_u24_e32 v248, 0x8f8, v248
	v_sub_u32_e32 v213, v211, v248
	v_sub_u32_e32 v220, v215, v248
	v_sub_u32_e32 v211, v211, v221
	v_sub_u32_e32 v215, v215, v221
	ds_read_b128 v[178:181], v215 offset:36864
	ds_read_b128 v[194:197], v211
	ds_read_b128 v[198:201], v215 offset:39168
	ds_read_b128 v[202:205], v215 offset:41472
	ds_read_b128 v[206:209], v215 offset:43776
	ds_read_b128 v[216:219], v211 offset:2304
	ds_read_b128 v[236:239], v211 offset:4608
	ds_read_b128 v[240:243], v211 offset:6912
	ds_read_b128 v[244:247], v211 offset:9216
	s_waitcnt lgkmcnt(7)
	v_mfma_f32_16x16x32_bf16 v[114:117], v[178:181], v[194:197], v[114:117]
	s_ashr_i32 s1, s0, 31
	s_lshl_b64 s[4:5], s[0:1], 7
	s_waitcnt lgkmcnt(6)
	v_mfma_f32_16x16x32_bf16 v[122:125], v[198:201], v[194:197], v[122:125]
	v_lshl_add_u64 v[154:155], v[184:185], 0, s[4:5]
	v_add_co_u32_e32 v130, vcc, 0x10000, v154
	s_waitcnt lgkmcnt(5)
	v_mfma_f32_16x16x32_bf16 v[50:53], v[202:205], v[194:197], v[50:53]
	v_lshl_add_u64 v[170:171], v[186:187], 0, s[4:5]
	s_nop 0
	s_waitcnt lgkmcnt(4)
	v_mfma_f32_16x16x32_bf16 v[58:61], v[206:209], v[194:197], v[58:61]
	ds_read_b128 v[194:197], v211 offset:11520
	v_addc_co_u32_e32 v131, vcc, 0, v155, vcc
	v_add_co_u32_e32 v134, vcc, 0x20000, v154
	s_waitcnt lgkmcnt(4)
	v_mfma_f32_16x16x32_bf16 v[118:121], v[178:181], v[216:219], v[118:121]
	global_load_dwordx4 v[142:145], v[154:155], off
	s_nop 0
	v_mfma_f32_16x16x32_bf16 v[126:129], v[198:201], v[216:219], v[126:129]
	global_load_dwordx4 v[130:133], v[130:131], off
	v_addc_co_u32_e32 v135, vcc, 0, v155, vcc
	v_mfma_f32_16x16x32_bf16 v[54:57], v[202:205], v[216:219], v[54:57]
	v_add_co_u32_e32 v138, vcc, 0x30000, v154
	s_add_i32 s0, s0, 1
	v_mfma_f32_16x16x32_bf16 v[62:65], v[206:209], v[216:219], v[62:65]
	ds_read_b128 v[216:219], v211 offset:13824
	s_nop 0
	v_addc_co_u32_e32 v139, vcc, 0, v155, vcc
	s_waitcnt lgkmcnt(4)
	v_mfma_f32_16x16x32_bf16 v[98:101], v[178:181], v[236:239], v[98:101]
	v_add_co_u32_e32 v146, vcc, 0x40000, v154
	global_load_dwordx4 v[134:137], v[134:135], off
	v_mfma_f32_16x16x32_bf16 v[106:109], v[198:201], v[236:239], v[106:109]
	s_nop 0
	global_load_dwordx4 v[138:141], v[138:139], off
	v_mfma_f32_16x16x32_bf16 v[34:37], v[202:205], v[236:239], v[34:37]
	v_addc_co_u32_e32 v147, vcc, 0, v155, vcc
	v_add_co_u32_e32 v150, vcc, 0x50000, v154
	v_mfma_f32_16x16x32_bf16 v[42:45], v[206:209], v[236:239], v[42:45]
	ds_read_b128 v[236:239], v211 offset:16128
	s_nop 0
	v_addc_co_u32_e32 v151, vcc, 0, v155, vcc
	s_waitcnt lgkmcnt(4)
	v_mfma_f32_16x16x32_bf16 v[102:105], v[178:181], v[240:243], v[102:105]
	v_add_co_u32_e32 v156, vcc, 0x60000, v154
	global_load_dwordx4 v[146:149], v[146:147], off
	v_mfma_f32_16x16x32_bf16 v[110:113], v[198:201], v[240:243], v[110:113]
	s_nop 0
	global_load_dwordx4 v[150:153], v[150:151], off
	v_mfma_f32_16x16x32_bf16 v[38:41], v[202:205], v[240:243], v[38:41]
	v_addc_co_u32_e32 v157, vcc, 0, v155, vcc
	v_add_co_u32_e32 v158, vcc, 0x70000, v154
	v_mfma_f32_16x16x32_bf16 v[46:49], v[206:209], v[240:243], v[46:49]
	ds_read_b128 v[240:243], v215 offset:36928
	s_nop 1
	v_addc_co_u32_e32 v159, vcc, 0, v155, vcc
	s_waitcnt lgkmcnt(4)
	v_mfma_f32_16x16x32_bf16 v[82:85], v[178:181], v[244:247], v[82:85]
	v_add_co_u32_e32 v166, vcc, 0x10000, v170
	global_load_dwordx4 v[154:157], v[156:157], off
	v_mfma_f32_16x16x32_bf16 v[90:93], v[198:201], v[244:247], v[90:93]
	s_nop 0
	global_load_dwordx4 v[158:161], v[158:159], off
	v_mfma_f32_16x16x32_bf16 v[18:21], v[202:205], v[244:247], v[18:21]
	v_addc_co_u32_e32 v167, vcc, 0, v171, vcc
	v_add_co_u32_e32 v172, vcc, 0x20000, v170
	v_mfma_f32_16x16x32_bf16 v[26:29], v[206:209], v[244:247], v[26:29]
	ds_read_b128 v[244:247], v211 offset:64
	global_load_dwordx4 v[162:165], v[170:171], off
	s_nop 0
	s_waitcnt lgkmcnt(4)
	v_mfma_f32_16x16x32_bf16 v[86:89], v[178:181], v[194:197], v[86:89]
	global_load_dwordx4 v[166:169], v[166:167], off
	v_addc_co_u32_e32 v173, vcc, 0, v171, vcc
	v_mfma_f32_16x16x32_bf16 v[94:97], v[198:201], v[194:197], v[94:97]
	v_add_co_u32_e32 v174, vcc, 0x30000, v170
	s_nop 1
	v_mfma_f32_16x16x32_bf16 v[22:25], v[202:205], v[194:197], v[22:25]
	v_addc_co_u32_e32 v175, vcc, 0, v171, vcc
	global_load_dwordx4 v[170:173], v[172:173], off
	v_mfma_f32_16x16x32_bf16 v[30:33], v[206:209], v[194:197], v[30:33]
	ds_read_b128 v[194:197], v211 offset:2368
	s_nop 0
	global_load_dwordx4 v[174:177], v[174:175], off
	s_waitcnt lgkmcnt(4)
	v_mfma_f32_16x16x32_bf16 v[66:69], v[178:181], v[216:219], v[66:69]
	s_cmp_lg_u32 s0, 16
	s_waitcnt lgkmcnt(3)
	v_mfma_f32_16x16x32_bf16 v[70:73], v[178:181], v[236:239], v[70:73]
	ds_read_b128 v[178:181], v215 offset:39232
	v_mfma_f32_16x16x32_bf16 v[74:77], v[198:201], v[216:219], v[74:77]
	v_mfma_f32_16x16x32_bf16 v[78:81], v[198:201], v[236:239], v[78:81]
	ds_read_b128 v[198:201], v215 offset:41536
	v_mfma_f32_16x16x32_bf16 v[2:5], v[202:205], v[216:219], v[2:5]
	v_mfma_f32_16x16x32_bf16 v[6:9], v[202:205], v[236:239], v[6:9]
	ds_read_b128 v[202:205], v215 offset:43840
	v_mfma_f32_16x16x32_bf16 v[10:13], v[206:209], v[216:219], v[10:13]
	ds_read_b128 v[216:219], v211 offset:4672
	v_mfma_f32_16x16x32_bf16 v[14:17], v[206:209], v[236:239], v[14:17]
	ds_read_b128 v[206:209], v211 offset:6976
	ds_read_b128 v[236:239], v211 offset:9280
	s_waitcnt lgkmcnt(7)
	v_mfma_f32_16x16x32_bf16 v[114:117], v[240:243], v[244:247], v[114:117]
	s_waitcnt lgkmcnt(6)
	v_mfma_f32_16x16x32_bf16 v[118:121], v[240:243], v[194:197], v[118:121]
	s_waitcnt lgkmcnt(5)
	v_mfma_f32_16x16x32_bf16 v[122:125], v[178:181], v[244:247], v[122:125]
	v_mfma_f32_16x16x32_bf16 v[126:129], v[178:181], v[194:197], v[126:129]
	s_waitcnt lgkmcnt(4)
	v_mfma_f32_16x16x32_bf16 v[50:53], v[198:201], v[244:247], v[50:53]
	v_mfma_f32_16x16x32_bf16 v[54:57], v[198:201], v[194:197], v[54:57]
	s_waitcnt lgkmcnt(3)
	v_mfma_f32_16x16x32_bf16 v[58:61], v[202:205], v[244:247], v[58:61]
	ds_read_b128 v[244:247], v211 offset:11584
	v_mfma_f32_16x16x32_bf16 v[62:65], v[202:205], v[194:197], v[62:65]
	ds_read_b128 v[194:197], v211 offset:13888
	s_waitcnt lgkmcnt(4)
	v_mfma_f32_16x16x32_bf16 v[98:101], v[240:243], v[216:219], v[98:101]
	v_mfma_f32_16x16x32_bf16 v[106:109], v[178:181], v[216:219], v[106:109]
	v_mfma_f32_16x16x32_bf16 v[34:37], v[198:201], v[216:219], v[34:37]
	v_mfma_f32_16x16x32_bf16 v[42:45], v[202:205], v[216:219], v[42:45]
	ds_read_b128 v[216:219], v211 offset:16192
	s_waitcnt lgkmcnt(4)
	v_mfma_f32_16x16x32_bf16 v[102:105], v[240:243], v[206:209], v[102:105]
	v_mfma_f32_16x16x32_bf16 v[110:113], v[178:181], v[206:209], v[110:113]
	v_mfma_f32_16x16x32_bf16 v[38:41], v[198:201], v[206:209], v[38:41]
	v_mfma_f32_16x16x32_bf16 v[46:49], v[202:205], v[206:209], v[46:49]
	s_waitcnt lgkmcnt(3)
	v_mfma_f32_16x16x32_bf16 v[82:85], v[240:243], v[236:239], v[82:85]
	v_mfma_f32_16x16x32_bf16 v[90:93], v[178:181], v[236:239], v[90:93]
	v_mfma_f32_16x16x32_bf16 v[18:21], v[198:201], v[236:239], v[18:21]
	v_mfma_f32_16x16x32_bf16 v[26:29], v[202:205], v[236:239], v[26:29]
	s_waitcnt lgkmcnt(2)
	v_mfma_f32_16x16x32_bf16 v[86:89], v[240:243], v[244:247], v[86:89]
	v_mfma_f32_16x16x32_bf16 v[94:97], v[178:181], v[244:247], v[94:97]
	v_mfma_f32_16x16x32_bf16 v[22:25], v[198:201], v[244:247], v[22:25]
	v_mfma_f32_16x16x32_bf16 v[30:33], v[202:205], v[244:247], v[30:33]
	s_waitcnt lgkmcnt(1)
	v_mfma_f32_16x16x32_bf16 v[66:69], v[240:243], v[194:197], v[66:69]
	v_mfma_f32_16x16x32_bf16 v[74:77], v[178:181], v[194:197], v[74:77]
	v_mfma_f32_16x16x32_bf16 v[2:5], v[198:201], v[194:197], v[2:5]
	v_mfma_f32_16x16x32_bf16 v[10:13], v[202:205], v[194:197], v[10:13]
	s_waitcnt lgkmcnt(0)
	v_mfma_f32_16x16x32_bf16 v[70:73], v[240:243], v[216:219], v[70:73]
	v_mfma_f32_16x16x32_bf16 v[78:81], v[178:181], v[216:219], v[78:81]
	v_mfma_f32_16x16x32_bf16 v[6:9], v[198:201], v[216:219], v[6:9]
	v_mfma_f32_16x16x32_bf16 v[14:17], v[202:205], v[216:219], v[14:17]
	s_setprio 0
	s_cbranch_scc1 .Ltail_647
	s_add_i32 s10, s10, 1
	s_cmp_ge_i32 s10, s8
	s_cbranch_scc1 .Lx646_647
	s_mul_i32 s0, s10, s82
	s_add_i32 s0, s0, s63
	s_ashr_i32 s1, s0, 31
	s_lshr_b32 s1, s1, 26
	s_add_i32 s1, s0, s1
	s_ashr_i32 s3, s1, 6
	s_andn2_b32 s1, s1, 63
	s_sub_i32 s0, s0, s1
	s_lshl_b32 s1, s3, 1
	s_and_b32 s3, s0, 1
	s_or_b32 s1, s3, s1
	v_readlane_b32 s4, v252, 35
	s_ashr_i32 s0, s0, 1
	s_sub_i32 s3, 0x7f, s1
	v_readlane_b32 s5, v252, 36
	s_and_b64 s[4:5], s[4:5], exec
	s_cselect_b32 s4, s3, s1
	s_ashr_i32 s5, s4, 31
	s_ashr_i32 s1, s0, 31
	s_lshl_b64 s[4:5], s[4:5], 19
	s_lshl_b64 s[0:1], s[0:1], 18
	v_lshl_add_u64 v[184:185], v[190:191], 0, s[4:5]
	v_lshl_add_u64 v[186:187], v[192:193], 0, s[0:1]

.LBB0_647:
	s_waitcnt lgkmcnt(0)
	s_barrier
	s_setprio 2
	v_bfe_u32 v221, v222, 5, 1
	v_bfe_u32 v248, v222, 4, 1
	v_lshl_add_u32 v211, v221, 4, v182
	v_lshl_add_u32 v215, v221, 4, v183
	v_mul_u32_u24_e32 v221, 0x8f0, v248
	v_mul_u32_u24_e32 v248, 0x8f8, v248
	v_sub_u32_e32 v213, v211, v248
	v_sub_u32_e32 v220, v215, v248
	v_sub_u32_e32 v211, v211, v221
	v_sub_u32_e32 v215, v215, v221
	ds_read_b128 v[178:181], v215 offset:36864
	ds_read_b128 v[194:197], v211
	ds_read_b128 v[198:201], v215 offset:39168
	ds_read_b128 v[202:205], v215 offset:41472
	ds_read_b128 v[206:209], v215 offset:43776
	ds_read_b128 v[216:219], v211 offset:2304
	ds_read_b128 v[236:239], v211 offset:4608
	ds_read_b128 v[240:243], v211 offset:6912
	ds_read_b128 v[244:247], v211 offset:9216
	s_waitcnt lgkmcnt(7)
	v_mfma_f32_16x16x32_bf16 v[114:117], v[178:181], v[194:197], v[114:117]
	s_waitcnt lgkmcnt(6)
	v_mfma_f32_16x16x32_bf16 v[122:125], v[198:201], v[194:197], v[122:125]
	s_waitcnt lgkmcnt(5)
	v_mfma_f32_16x16x32_bf16 v[50:53], v[202:205], v[194:197], v[50:53]
	s_waitcnt lgkmcnt(4)
	v_mfma_f32_16x16x32_bf16 v[58:61], v[206:209], v[194:197], v[58:61]
	ds_read_b128 v[194:197], v211 offset:11520
	s_waitcnt lgkmcnt(4)
	v_mfma_f32_16x16x32_bf16 v[118:121], v[178:181], v[216:219], v[118:121]
	v_mfma_f32_16x16x32_bf16 v[126:129], v[198:201], v[216:219], v[126:129]
	v_mfma_f32_16x16x32_bf16 v[54:57], v[202:205], v[216:219], v[54:57]
	v_mfma_f32_16x16x32_bf16 v[62:65], v[206:209], v[216:219], v[62:65]
	ds_read_b128 v[216:219], v211 offset:13824
	s_waitcnt lgkmcnt(4)
	v_mfma_f32_16x16x32_bf16 v[98:101], v[178:181], v[236:239], v[98:101]
	v_mfma_f32_16x16x32_bf16 v[106:109], v[198:201], v[236:239], v[106:109]
	v_mfma_f32_16x16x32_bf16 v[34:37], v[202:205], v[236:239], v[34:37]
	v_mfma_f32_16x16x32_bf16 v[42:45], v[206:209], v[236:239], v[42:45]
	ds_read_b128 v[236:239], v211 offset:16128
	s_waitcnt lgkmcnt(4)
	v_mfma_f32_16x16x32_bf16 v[102:105], v[178:181], v[240:243], v[102:105]
	v_mfma_f32_16x16x32_bf16 v[110:113], v[198:201], v[240:243], v[110:113]
	v_mfma_f32_16x16x32_bf16 v[38:41], v[202:205], v[240:243], v[38:41]
	v_mfma_f32_16x16x32_bf16 v[46:49], v[206:209], v[240:243], v[46:49]
	ds_read_b128 v[240:243], v215 offset:36928
	s_waitcnt lgkmcnt(4)
	v_mfma_f32_16x16x32_bf16 v[82:85], v[178:181], v[244:247], v[82:85]
	v_mfma_f32_16x16x32_bf16 v[90:93], v[198:201], v[244:247], v[90:93]
	v_mfma_f32_16x16x32_bf16 v[18:21], v[202:205], v[244:247], v[18:21]
	v_mfma_f32_16x16x32_bf16 v[26:29], v[206:209], v[244:247], v[26:29]
	ds_read_b128 v[244:247], v211 offset:64
	s_waitcnt lgkmcnt(4)
	v_mfma_f32_16x16x32_bf16 v[86:89], v[178:181], v[194:197], v[86:89]
	v_mfma_f32_16x16x32_bf16 v[94:97], v[198:201], v[194:197], v[94:97]
	v_mfma_f32_16x16x32_bf16 v[22:25], v[202:205], v[194:197], v[22:25]
	v_mfma_f32_16x16x32_bf16 v[30:33], v[206:209], v[194:197], v[30:33]
	ds_read_b128 v[194:197], v211 offset:2368
	s_waitcnt lgkmcnt(4)
	v_mfma_f32_16x16x32_bf16 v[66:69], v[178:181], v[216:219], v[66:69]
	s_waitcnt lgkmcnt(3)
	v_mfma_f32_16x16x32_bf16 v[70:73], v[178:181], v[236:239], v[70:73]
	ds_read_b128 v[178:181], v215 offset:39232
	v_mfma_f32_16x16x32_bf16 v[74:77], v[198:201], v[216:219], v[74:77]
	v_mfma_f32_16x16x32_bf16 v[78:81], v[198:201], v[236:239], v[78:81]
	ds_read_b128 v[198:201], v215 offset:41536
	v_mfma_f32_16x16x32_bf16 v[2:5], v[202:205], v[216:219], v[2:5]
	v_mfma_f32_16x16x32_bf16 v[6:9], v[202:205], v[236:239], v[6:9]
	ds_read_b128 v[202:205], v215 offset:43840
	v_mfma_f32_16x16x32_bf16 v[10:13], v[206:209], v[216:219], v[10:13]
	ds_read_b128 v[216:219], v211 offset:4672
	v_mfma_f32_16x16x32_bf16 v[14:17], v[206:209], v[236:239], v[14:17]
	ds_read_b128 v[206:209], v211 offset:6976
	ds_read_b128 v[236:239], v211 offset:9280
	s_waitcnt lgkmcnt(7)
	v_mfma_f32_16x16x32_bf16 v[114:117], v[240:243], v[244:247], v[114:117]
	s_waitcnt lgkmcnt(6)
	v_mfma_f32_16x16x32_bf16 v[118:121], v[240:243], v[194:197], v[118:121]
	s_waitcnt lgkmcnt(5)
	v_mfma_f32_16x16x32_bf16 v[122:125], v[178:181], v[244:247], v[122:125]
	v_mfma_f32_16x16x32_bf16 v[126:129], v[178:181], v[194:197], v[126:129]
	s_waitcnt lgkmcnt(4)
	v_mfma_f32_16x16x32_bf16 v[50:53], v[198:201], v[244:247], v[50:53]
	v_mfma_f32_16x16x32_bf16 v[54:57], v[198:201], v[194:197], v[54:57]
	s_waitcnt lgkmcnt(3)
	v_mfma_f32_16x16x32_bf16 v[58:61], v[202:205], v[244:247], v[58:61]
	ds_read_b128 v[244:247], v211 offset:11584
	v_mfma_f32_16x16x32_bf16 v[62:65], v[202:205], v[194:197], v[62:65]
	ds_read_b128 v[194:197], v211 offset:13888
	s_waitcnt lgkmcnt(4)
	v_mfma_f32_16x16x32_bf16 v[98:101], v[240:243], v[216:219], v[98:101]
	v_mfma_f32_16x16x32_bf16 v[106:109], v[178:181], v[216:219], v[106:109]
	v_mfma_f32_16x16x32_bf16 v[34:37], v[198:201], v[216:219], v[34:37]
	v_mfma_f32_16x16x32_bf16 v[42:45], v[202:205], v[216:219], v[42:45]
	ds_read_b128 v[216:219], v211 offset:16192
	s_waitcnt lgkmcnt(4)
	v_mfma_f32_16x16x32_bf16 v[102:105], v[240:243], v[206:209], v[102:105]
	v_mfma_f32_16x16x32_bf16 v[110:113], v[178:181], v[206:209], v[110:113]
	v_mfma_f32_16x16x32_bf16 v[38:41], v[198:201], v[206:209], v[38:41]
	v_mfma_f32_16x16x32_bf16 v[46:49], v[202:205], v[206:209], v[46:49]
	s_waitcnt lgkmcnt(3)
	v_mfma_f32_16x16x32_bf16 v[82:85], v[240:243], v[236:239], v[82:85]
	v_mfma_f32_16x16x32_bf16 v[90:93], v[178:181], v[236:239], v[90:93]
	v_mfma_f32_16x16x32_bf16 v[18:21], v[198:201], v[236:239], v[18:21]
	v_mfma_f32_16x16x32_bf16 v[26:29], v[202:205], v[236:239], v[26:29]
	s_waitcnt lgkmcnt(2)
	v_mfma_f32_16x16x32_bf16 v[86:89], v[240:243], v[244:247], v[86:89]
	v_mfma_f32_16x16x32_bf16 v[94:97], v[178:181], v[244:247], v[94:97]
	v_mfma_f32_16x16x32_bf16 v[22:25], v[198:201], v[244:247], v[22:25]
	v_mfma_f32_16x16x32_bf16 v[30:33], v[202:205], v[244:247], v[30:33]
	s_waitcnt lgkmcnt(1)
	v_mfma_f32_16x16x32_bf16 v[66:69], v[240:243], v[194:197], v[66:69]
	v_mfma_f32_16x16x32_bf16 v[74:77], v[178:181], v[194:197], v[74:77]
	v_mfma_f32_16x16x32_bf16 v[2:5], v[198:201], v[194:197], v[2:5]
	v_mfma_f32_16x16x32_bf16 v[10:13], v[202:205], v[194:197], v[10:13]
	s_waitcnt lgkmcnt(0)
	v_mfma_f32_16x16x32_bf16 v[70:73], v[240:243], v[216:219], v[70:73]
	v_mfma_f32_16x16x32_bf16 v[78:81], v[178:181], v[216:219], v[78:81]
	v_mfma_f32_16x16x32_bf16 v[6:9], v[198:201], v[216:219], v[6:9]
	v_mfma_f32_16x16x32_bf16 v[14:17], v[202:205], v[216:219], v[14:17]
	s_setprio 0
.Ltail_647:
	s_add_i32 s2, s2, 1
	s_cmp_lg_u32 s2, 16
	s_cbranch_scc1 .LBB0_641
	s_nop 7
	v_permlane16_swap_b32_e32 v114, v118
	v_permlane16_swap_b32_e32 v115, v119
	v_permlane16_swap_b32_e32 v116, v120
	v_permlane16_swap_b32_e32 v117, v121
	v_permlane16_swap_b32_e32 v122, v126
	v_permlane16_swap_b32_e32 v123, v127
	v_permlane16_swap_b32_e32 v124, v128
	v_permlane16_swap_b32_e32 v125, v129
	v_permlane32_swap_b32_e32 v114, v118
	v_permlane32_swap_b32_e32 v115, v119
	v_permlane32_swap_b32_e32 v116, v120
	v_permlane32_swap_b32_e32 v117, v121
	v_permlane32_swap_b32_e32 v122, v126
	v_permlane32_swap_b32_e32 v123, v127
	v_permlane32_swap_b32_e32 v124, v128
	v_permlane32_swap_b32_e32 v125, v129
	v_permlane16_swap_b32_e32 v50, v54
	v_permlane16_swap_b32_e32 v51, v55
	v_permlane16_swap_b32_e32 v52, v56
	v_permlane16_swap_b32_e32 v53, v57
	v_permlane16_swap_b32_e32 v58, v62
	v_permlane16_swap_b32_e32 v59, v63
	v_permlane16_swap_b32_e32 v60, v64
	v_permlane16_swap_b32_e32 v61, v65
	v_permlane32_swap_b32_e32 v50, v54
	v_permlane32_swap_b32_e32 v51, v55
	v_permlane32_swap_b32_e32 v52, v56
	v_permlane32_swap_b32_e32 v53, v57
	v_permlane32_swap_b32_e32 v58, v62
	v_permlane32_swap_b32_e32 v59, v63
	v_permlane32_swap_b32_e32 v60, v64
	v_permlane32_swap_b32_e32 v61, v65
	v_permlane16_swap_b32_e32 v98, v102
	v_permlane16_swap_b32_e32 v99, v103
	v_permlane16_swap_b32_e32 v100, v104
	v_permlane16_swap_b32_e32 v101, v105
	v_permlane16_swap_b32_e32 v106, v110
	v_permlane16_swap_b32_e32 v107, v111
	v_permlane16_swap_b32_e32 v108, v112
	v_permlane16_swap_b32_e32 v109, v113
	v_permlane32_swap_b32_e32 v98, v102
	v_permlane32_swap_b32_e32 v99, v103
	v_permlane32_swap_b32_e32 v100, v104
	v_permlane32_swap_b32_e32 v101, v105
	v_permlane32_swap_b32_e32 v106, v110
	v_permlane32_swap_b32_e32 v107, v111
	v_permlane32_swap_b32_e32 v108, v112
	v_permlane32_swap_b32_e32 v109, v113
	v_permlane16_swap_b32_e32 v34, v38
	v_permlane16_swap_b32_e32 v35, v39
	v_permlane16_swap_b32_e32 v36, v40
	v_permlane16_swap_b32_e32 v37, v41
	v_permlane16_swap_b32_e32 v42, v46
	v_permlane16_swap_b32_e32 v43, v47
	v_permlane16_swap_b32_e32 v44, v48
	v_permlane16_swap_b32_e32 v45, v49
	v_permlane32_swap_b32_e32 v34, v38
	v_permlane32_swap_b32_e32 v35, v39
	v_permlane32_swap_b32_e32 v36, v40
	v_permlane32_swap_b32_e32 v37, v41
	v_permlane32_swap_b32_e32 v42, v46
	v_permlane32_swap_b32_e32 v43, v47
	v_permlane32_swap_b32_e32 v44, v48
	v_permlane32_swap_b32_e32 v45, v49
	v_permlane16_swap_b32_e32 v82, v86
	v_permlane16_swap_b32_e32 v83, v87
	v_permlane16_swap_b32_e32 v84, v88
	v_permlane16_swap_b32_e32 v85, v89
	v_permlane16_swap_b32_e32 v90, v94
	v_permlane16_swap_b32_e32 v91, v95
	v_permlane16_swap_b32_e32 v92, v96
	v_permlane16_swap_b32_e32 v93, v97
	v_permlane32_swap_b32_e32 v82, v86
	v_permlane32_swap_b32_e32 v83, v87
	v_permlane32_swap_b32_e32 v84, v88
	v_permlane32_swap_b32_e32 v85, v89
	v_permlane32_swap_b32_e32 v90, v94
	v_permlane32_swap_b32_e32 v91, v95
	v_permlane32_swap_b32_e32 v92, v96
	v_permlane32_swap_b32_e32 v93, v97
	v_permlane16_swap_b32_e32 v18, v22
	v_permlane16_swap_b32_e32 v19, v23
	v_permlane16_swap_b32_e32 v20, v24
	v_permlane16_swap_b32_e32 v21, v25
	v_permlane16_swap_b32_e32 v26, v30
	v_permlane16_swap_b32_e32 v27, v31
	v_permlane16_swap_b32_e32 v28, v32
	v_permlane16_swap_b32_e32 v29, v33
	v_permlane32_swap_b32_e32 v18, v22
	v_permlane32_swap_b32_e32 v19, v23
	v_permlane32_swap_b32_e32 v20, v24
	v_permlane32_swap_b32_e32 v21, v25
	v_permlane32_swap_b32_e32 v26, v30
	v_permlane32_swap_b32_e32 v27, v31
	v_permlane32_swap_b32_e32 v28, v32
	v_permlane32_swap_b32_e32 v29, v33
	v_permlane16_swap_b32_e32 v66, v70
	v_permlane16_swap_b32_e32 v67, v71
	v_permlane16_swap_b32_e32 v68, v72
	v_permlane16_swap_b32_e32 v69, v73
	v_permlane16_swap_b32_e32 v74, v78
	v_permlane16_swap_b32_e32 v75, v79
	v_permlane16_swap_b32_e32 v76, v80
	v_permlane16_swap_b32_e32 v77, v81
	v_permlane32_swap_b32_e32 v66, v70
	v_permlane32_swap_b32_e32 v67, v71
	v_permlane32_swap_b32_e32 v68, v72
	v_permlane32_swap_b32_e32 v69, v73
	v_permlane32_swap_b32_e32 v74, v78
	v_permlane32_swap_b32_e32 v75, v79
	v_permlane32_swap_b32_e32 v76, v80
	v_permlane32_swap_b32_e32 v77, v81
	v_permlane16_swap_b32_e32 v2, v6
	v_permlane16_swap_b32_e32 v3, v7
	v_permlane16_swap_b32_e32 v4, v8
	v_permlane16_swap_b32_e32 v5, v9
	v_permlane16_swap_b32_e32 v10, v14
	v_permlane16_swap_b32_e32 v11, v15
	v_permlane16_swap_b32_e32 v12, v16
	v_permlane16_swap_b32_e32 v13, v17
	v_permlane32_swap_b32_e32 v2, v6
	v_permlane32_swap_b32_e32 v3, v7
	v_permlane32_swap_b32_e32 v4, v8
	v_permlane32_swap_b32_e32 v5, v9
	v_permlane32_swap_b32_e32 v10, v14
	v_permlane32_swap_b32_e32 v11, v15
	v_permlane32_swap_b32_e32 v12, v16
	v_permlane32_swap_b32_e32 v13, v17
	s_mul_i32 s1, s9, s82
	s_add_i32 s1, s1, s63
	s_ashr_i32 s2, s1, 31
	s_lshr_b32 s2, s2, 26
	s_add_i32 s2, s1, s2
	s_ashr_i32 s3, s2, 6
	s_andn2_b32 s2, s2, 63
	s_sub_i32 s1, s1, s2
	s_lshl_b32 s2, s3, 1
	s_and_b32 s3, s1, 1
	s_or_b32 s4, s3, s2
	v_readlane_b32 s2, v252, 35
	s_sub_i32 s5, 0x7f, s4
	v_readlane_b32 s3, v252, 36
	s_and_b64 s[2:3], s[2:3], exec
	v_mov_b32_e32 v0, v222
	s_cselect_b32 s2, s5, s4
	s_lshl_b32 s1, s1, 1
	s_and_b32 s1, s1, -4
	v_lshrrev_b32_e32 v178, 5, v0
	v_and_or_b32 v220, v178, 2, s1
	v_readlane_b32 s1, v250, 18
	s_getpc_b64 s[4:5]
	s_add_u32 s4, s4, c_segs@rel32@lo+16
	s_addc_u32 s5, s5, c_segs@rel32@hi+24
	v_cmp_le_i32_e32 vcc, s1, v220
	v_readlane_b32 s1, v250, 19
	v_and_b32_e32 v189, 31, v0
	v_cndmask_b32_e64 v178, 0, 1, vcc
	v_cmp_gt_i32_e32 vcc, s1, v220
	v_readlane_b32 s1, v250, 20
	v_mov_b32_e32 v203, v1
	v_cndmask_b32_e32 v178, 2, v178, vcc
	v_cmp_gt_i32_e32 vcc, s1, v220
	v_readlane_b32 s1, v250, 21
	v_mov_b32_e32 v201, v1
	v_cndmask_b32_e32 v178, 3, v178, vcc
	v_cmp_gt_i32_e32 vcc, s1, v220
	v_readlane_b32 s1, v250, 22
	v_mov_b32_e32 v199, v1
	v_cndmask_b32_e32 v178, 4, v178, vcc
	v_cmp_gt_i32_e32 vcc, s1, v220
	v_readlane_b32 s1, v250, 23
	v_mov_b32_e32 v197, v1
	v_cndmask_b32_e32 v178, 5, v178, vcc
	v_cmp_gt_i32_e32 vcc, s1, v220
	v_readlane_b32 s1, v250, 24
	s_nop 0
	v_cndmask_b32_e32 v178, 6, v178, vcc
	v_cmp_gt_i32_e32 vcc, s1, v220
	v_readlane_b32 s1, v250, 25
	s_nop 0
	v_cndmask_b32_e32 v178, 7, v178, vcc
	v_cmp_gt_i32_e32 vcc, s1, v220
	v_readlane_b32 s1, v250, 26
	s_nop 0
	v_cndmask_b32_e32 v178, 8, v178, vcc
	v_cmp_gt_i32_e32 vcc, s1, v220
	v_readlane_b32 s1, v250, 27
	s_nop 0
	v_cndmask_b32_e32 v178, 9, v178, vcc
	v_cmp_gt_i32_e32 vcc, s1, v220
	v_readlane_b32 s1, v250, 28
	s_nop 0
	v_cndmask_b32_e32 v178, 10, v178, vcc
	v_cmp_gt_i32_e32 vcc, s1, v220
	v_readlane_b32 s1, v250, 29
	s_nop 0
	v_cndmask_b32_e32 v178, 11, v178, vcc
	v_cmp_gt_i32_e32 vcc, s1, v220
	v_readlane_b32 s1, v250, 30
	s_nop 0
	v_cndmask_b32_e32 v178, 12, v178, vcc
	v_cmp_gt_i32_e32 vcc, s1, v220
	v_readlane_b32 s1, v250, 31
	s_nop 0
	v_cndmask_b32_e32 v178, 13, v178, vcc
	v_cmp_gt_i32_e32 vcc, s1, v220
	v_readlane_b32 s1, v250, 32
	s_nop 0
	v_cndmask_b32_e32 v178, 14, v178, vcc
	v_cmp_gt_i32_e32 vcc, s1, v220
	v_readlane_b32 s1, v250, 33
	s_nop 0
	v_cndmask_b32_e32 v178, 15, v178, vcc
	v_cmp_gt_i32_e32 vcc, s1, v220
	v_readlane_b32 s1, v250, 34
	s_nop 0
	v_cndmask_b32_e32 v178, 16, v178, vcc
	v_cmp_gt_i32_e32 vcc, s1, v220
	s_nop 1
	v_cndmask_b32_e32 v181, 17, v178, vcc
	v_mad_u64_u32 v[178:179], s[4:5], v181, 24, s[4:5]
	s_getpc_b64 s[4:5]
	s_add_u32 s4, s4, c_segs@rel32@lo+4
	s_addc_u32 s5, s5, c_segs@rel32@hi+12
	v_mad_u64_u32 v[194:195], s[4:5], v181, 24, s[4:5]
	global_load_dwordx3 v[178:180], v[178:179], off
	v_lshrrev_b32_e32 v181, 3, v0
	global_load_dword v206, v[194:195], off
	v_and_b32_e32 v194, 0xffffff80, v0
	v_bfe_u32 v0, v0, 3, 3
	v_and_b32_e32 v219, 4, v181
	v_or_b32_e32 v181, 3, v0
	v_or_b32_e32 v196, 11, v0
	v_lshlrev_b32_e32 v204, 14, v0
	v_cvt_f32_ubyte0_e32 v205, v219
	v_or_b32_e32 v207, 1, v219
	v_or_b32_e32 v208, 2, v219
	v_cvt_f32_ubyte0_e32 v181, v181
	v_or_b32_e32 v209, 8, v219
	v_or_b32_e32 v211, 9, v219
	v_or_b32_e32 v213, 10, v219
	v_cvt_f32_ubyte0_e32 v215, v196
	v_and_b32_e32 v0, 0x10000, v204
	v_or_b32_e32 v202, 0xc000, v204
	v_or_b32_e32 v200, 0x2c000, v204
	v_or_b32_e32 v198, 0x4c000, v204
	v_or_b32_e32 v196, 0x6c000, v204
	v_mul_f32_e32 v204, 0xbf549a78, v205
	v_cvt_f32_ubyte0_e32 v205, v207
	v_cvt_f32_ubyte0_e32 v207, v208
	v_mul_f32_e32 v181, 0xbf549a78, v181
	v_cvt_f32_ubyte0_e32 v208, v209
	v_cvt_f32_ubyte0_e32 v209, v211
	v_cvt_f32_ubyte0_e32 v211, v213
	v_mul_f32_e32 v213, 0xbf549a78, v215
	v_exp_f32_e32 v217, v204
	v_mul_f32_e32 v204, 0xbf549a78, v205
	v_mul_f32_e32 v205, 0xbf549a78, v207
	v_exp_f32_e32 v215, v181
	v_mul_f32_e32 v181, 0xbf549a78, v208
	v_mul_f32_e32 v207, 0xbf549a78, v209
	v_mul_f32_e32 v209, 0xbf549a78, v211
	s_ashr_i32 s3, s2, 31
	v_ashrrev_i32_e32 v195, 31, v194
	v_exp_f32_e32 v208, v213
	v_exp_f32_e32 v218, v204
	v_exp_f32_e32 v216, v205
	v_exp_f32_e32 v213, v181
	v_exp_f32_e32 v211, v207
	v_exp_f32_e32 v209, v209
	s_lshl_b64 s[2:3], s[2:3], 8
	v_lshl_add_u64 v[194:195], s[2:3], 0, v[194:195]
	v_mov_b32_e32 v181, v1
	v_readlane_b32 s2, v252, 45
	v_readlane_b32 s3, v252, 46
	v_and_b32_e32 v221, 0x1f80, v194
	v_lshrrev_b64 v[204:205], 13, v[194:195]
	s_waitcnt vmcnt(1)
	v_lshlrev_b64 v[180:181], 10, v[180:181]
	v_lshl_add_u64 v[180:181], s[2:3], 0, v[180:181]
	s_waitcnt vmcnt(0)
	v_sub_u32_e32 v206, v220, v206
	v_lshlrev_b32_e32 v206, 5, v206
	v_cmp_lt_i32_e32 vcc, 0, v179
	s_and_saveexec_b64 s[2:3], vcc
	s_xor_b64 s[2:3], exec, s[2:3]
	s_cbranch_execz .LBB0_656
	v_cmp_lt_i32_e32 vcc, 1, v179
	s_and_saveexec_b64 s[4:5], vcc
	s_xor_b64 s[4:5], exec, s[4:5]
	s_cbranch_execz .LBB0_653
	v_cmp_eq_u32_e32 vcc, 2, v179
	s_and_saveexec_b64 s[6:7], vcc
	s_cbranch_execz .LBB0_652
	v_ashrrev_i32_e32 v207, 31, v206
	v_lshl_add_u64 v[180:181], v[206:207], 1, v[180:181]
	v_lshlrev_b32_e32 v206, 1, v219
	v_mov_b32_e32 v207, v1
	s_movk_i32 s1, 0x1f80
	v_lshl_add_u64 v[180:181], v[180:181], 0, v[206:207]
	v_and_or_b32 v206, v194, s1, v189
	v_cvt_f32_u32_e32 v226, v206
	s_mov_b32 s14, 0x6dc9c883
	s_mov_b32 s15, 0x3fc45f30
	v_ashrrev_i32_e32 v179, 31, v178
	v_mul_f32_e32 v206, v217, v226
	v_cvt_f64_f32_e32 v[206:207], v206
	v_mul_f64 v[236:237], v[206:207], s[14:15]
	v_floor_f64_e32 v[236:237], v[236:237]
	v_fma_f64 v[206:207], v[206:207], s[14:15], -v[236:237]
	v_cvt_f32_f64_e32 v207, v[206:207]
	v_sin_f32_e32 v206, v207
	v_cos_f32_e32 v236, v207
	v_mul_f32_e32 v207, v218, v226
	v_cvt_f64_f32_e32 v[238:239], v207
	v_mul_f64 v[240:241], v[238:239], s[14:15]
	v_floor_f64_e32 v[240:241], v[240:241]
	v_fma_f64 v[238:239], v[238:239], s[14:15], -v[240:241]
	v_cvt_f32_f64_e32 v237, v[238:239]
	v_sin_f32_e32 v207, v237
	v_cos_f32_e32 v237, v237
	s_movk_i32 s1, 0x1fa0
	v_pk_mul_f32 v[238:239], v[122:123], v[206:207]
	v_pk_mul_f32 v[122:123], v[122:123], v[236:237]
	v_pk_fma_f32 v[238:239], v[114:115], v[236:237], v[238:239] neg_lo:[0,0,1] neg_hi:[0,0,1]
	v_pk_fma_f32 v[122:123], v[114:115], v[206:207], v[122:123]
	v_mul_f32_e32 v114, v216, v226
	v_cvt_f64_f32_e32 v[114:115], v114
	v_mul_f64 v[206:207], v[114:115], s[14:15]
	v_floor_f64_e32 v[206:207], v[206:207]
	v_fma_f64 v[114:115], v[114:115], s[14:15], -v[206:207]
	v_cvt_f32_f64_e32 v115, v[114:115]
	v_sin_f32_e32 v114, v115
	v_cos_f32_e32 v206, v115
	v_mul_f32_e32 v115, v215, v226
	v_cvt_f64_f32_e32 v[236:237], v115
	v_mul_f64 v[240:241], v[236:237], s[14:15]
	v_floor_f64_e32 v[240:241], v[240:241]
	v_fma_f64 v[236:237], v[236:237], s[14:15], -v[240:241]
	v_cvt_f32_f64_e32 v207, v[236:237]
	v_sin_f32_e32 v115, v207
	v_cos_f32_e32 v207, v207
	v_cvt_pk_bf16_f32 v122, v122, v123
	v_pk_mul_f32 v[236:237], v[124:125], v[114:115]
	v_pk_mul_f32 v[124:125], v[124:125], v[206:207]
	v_pk_fma_f32 v[236:237], v[116:117], v[206:207], v[236:237] neg_lo:[0,0,1] neg_hi:[0,0,1]
	v_pk_fma_f32 v[116:117], v[116:117], v[114:115], v[124:125]
	v_mul_f32_e32 v114, v213, v226
	v_cvt_f64_f32_e32 v[114:115], v114
	v_mul_f64 v[124:125], v[114:115], s[14:15]
	v_floor_f64_e32 v[124:125], v[124:125]
	v_fma_f64 v[114:115], v[114:115], s[14:15], -v[124:125]
	v_cvt_f32_f64_e32 v115, v[114:115]
	v_sin_f32_e32 v114, v115
	v_cos_f32_e32 v124, v115
	v_mul_f32_e32 v115, v211, v226
	v_cvt_f64_f32_e32 v[206:207], v115
	v_mul_f64 v[240:241], v[206:207], s[14:15]
	v_floor_f64_e32 v[240:241], v[240:241]
	v_fma_f64 v[206:207], v[206:207], s[14:15], -v[240:241]
	v_cvt_f32_f64_e32 v125, v[206:207]
	v_sin_f32_e32 v115, v125
	v_cos_f32_e32 v125, v125
	v_cvt_pk_bf16_f32 v123, v116, v117
	v_pk_mul_f32 v[206:207], v[126:127], v[114:115]
	s_nop 0
	v_pk_fma_f32 v[206:207], v[118:119], v[124:125], v[206:207] neg_lo:[0,0,1] neg_hi:[0,0,1]
	v_pk_mul_f32 v[124:125], v[126:127], v[124:125]
	s_nop 0
	v_pk_fma_f32 v[118:119], v[118:119], v[114:115], v[124:125]
	v_mul_f32_e32 v114, v209, v226
	v_cvt_f64_f32_e32 v[114:115], v114
	v_mul_f64 v[124:125], v[114:115], s[14:15]
	v_floor_f64_e32 v[124:125], v[124:125]
	v_fma_f64 v[114:115], v[114:115], s[14:15], -v[124:125]
	v_cvt_f32_f64_e32 v115, v[114:115]
	v_sin_f32_e32 v114, v115
	v_cos_f32_e32 v124, v115
	v_mul_f32_e32 v115, v208, v226
	v_cvt_f64_f32_e32 v[126:127], v115
	v_mul_f64 v[240:241], v[126:127], s[14:15]
	v_floor_f64_e32 v[240:241], v[240:241]
	v_fma_f64 v[126:127], v[126:127], s[14:15], -v[240:241]
	v_cvt_f32_f64_e32 v125, v[126:127]
	v_sin_f32_e32 v115, v125
	v_cos_f32_e32 v125, v125
	v_cvt_pk_bf16_f32 v116, v118, v119
	v_pk_mul_f32 v[126:127], v[128:129], v[114:115]
	s_nop 0
	v_pk_fma_f32 v[126:127], v[120:121], v[124:125], v[126:127] neg_lo:[0,0,1] neg_hi:[0,0,1]
	v_pk_mul_f32 v[124:125], v[128:129], v[124:125]
	v_cvt_pk_bf16_f32 v129, v236, v237
	v_pk_fma_f32 v[120:121], v[120:121], v[114:115], v[124:125]
	v_or_b32_e32 v115, v194, v189
	v_mul_lo_u32 v128, v115, v179
	v_mul_lo_u32 v114, v195, v178
	v_mad_u64_u32 v[124:125], s[12:13], v115, v178, 0
	v_add3_u32 v125, v125, v128, v114
	v_lshl_add_u64 v[124:125], v[124:125], 1, v[180:181]
	v_cvt_pk_bf16_f32 v128, v238, v239
	v_cvt_pk_bf16_f32 v117, v120, v121
	v_or_b32_e32 v115, 32, v194
	global_store_dwordx2 v[124:125], v[128:129], off
	v_cvt_pk_bf16_f32 v128, v206, v207
	v_cvt_pk_bf16_f32 v129, v126, v127
	global_store_dwordx2 v[124:125], v[116:117], off offset:48
	v_and_or_b32 v116, v115, s1, v189
	global_store_dwordx2 v[124:125], v[128:129], off offset:16
	global_store_dwordx2 v[124:125], v[122:123], off offset:32
	v_cvt_f32_u32_e32 v124, v116
	s_movk_i32 s1, 0x1fc0
	v_mul_f32_e32 v116, v217, v124
	v_cvt_f64_f32_e32 v[116:117], v116
	v_mul_f64 v[118:119], v[116:117], s[14:15]
	v_floor_f64_e32 v[118:119], v[118:119]
	v_fma_f64 v[116:117], v[116:117], s[14:15], -v[118:119]
	v_cvt_f32_f64_e32 v117, v[116:117]
	v_sin_f32_e32 v116, v117
	v_cos_f32_e32 v118, v117
	v_mul_f32_e32 v117, v218, v124
	v_cvt_f64_f32_e32 v[120:121], v117
	v_mul_f64 v[122:123], v[120:121], s[14:15]
	v_floor_f64_e32 v[122:123], v[122:123]
	v_fma_f64 v[120:121], v[120:121], s[14:15], -v[122:123]
	v_cvt_f32_f64_e32 v119, v[120:121]
	v_sin_f32_e32 v117, v119
	v_cos_f32_e32 v119, v119
	v_pk_mul_f32 v[120:121], v[106:107], v[116:117]
	v_pk_mul_f32 v[106:107], v[106:107], v[118:119]
	v_pk_fma_f32 v[120:121], v[98:99], v[118:119], v[120:121] neg_lo:[0,0,1] neg_hi:[0,0,1]
	v_pk_fma_f32 v[98:99], v[98:99], v[116:117], v[106:107]
	v_mul_f32_e32 v106, v216, v124
	v_cvt_f64_f32_e32 v[106:107], v106
	v_mul_f64 v[116:117], v[106:107], s[14:15]
	v_floor_f64_e32 v[116:117], v[116:117]
	v_fma_f64 v[106:107], v[106:107], s[14:15], -v[116:117]
	v_cvt_f32_f64_e32 v107, v[106:107]
	v_sin_f32_e32 v106, v107
	v_cos_f32_e32 v116, v107
	v_mul_f32_e32 v107, v215, v124
	v_cvt_f64_f32_e32 v[118:119], v107
	v_mul_f64 v[122:123], v[118:119], s[14:15]
	v_floor_f64_e32 v[122:123], v[122:123]
	v_fma_f64 v[118:119], v[118:119], s[14:15], -v[122:123]
	v_cvt_f32_f64_e32 v117, v[118:119]
	v_sin_f32_e32 v107, v117
	v_cos_f32_e32 v117, v117
	v_cvt_pk_bf16_f32 v98, v98, v99
	v_pk_mul_f32 v[118:119], v[108:109], v[106:107]
	v_pk_mul_f32 v[108:109], v[108:109], v[116:117]
	v_pk_fma_f32 v[118:119], v[100:101], v[116:117], v[118:119] neg_lo:[0,0,1] neg_hi:[0,0,1]
	v_pk_fma_f32 v[100:101], v[100:101], v[106:107], v[108:109]
	v_mul_f32_e32 v106, v213, v124
	v_cvt_f64_f32_e32 v[106:107], v106
	v_mul_f64 v[108:109], v[106:107], s[14:15]
	v_floor_f64_e32 v[108:109], v[108:109]
	v_fma_f64 v[106:107], v[106:107], s[14:15], -v[108:109]
	v_cvt_f32_f64_e32 v107, v[106:107]
	v_sin_f32_e32 v106, v107
	v_cos_f32_e32 v108, v107
	v_mul_f32_e32 v107, v211, v124
	v_cvt_f64_f32_e32 v[116:117], v107
	v_mul_f64 v[122:123], v[116:117], s[14:15]
	v_floor_f64_e32 v[122:123], v[122:123]
	v_fma_f64 v[116:117], v[116:117], s[14:15], -v[122:123]
	v_cvt_f32_f64_e32 v109, v[116:117]
	v_sin_f32_e32 v107, v109
	v_cos_f32_e32 v109, v109
	v_cvt_pk_bf16_f32 v99, v100, v101
	v_pk_mul_f32 v[116:117], v[110:111], v[106:107]
	s_nop 0
	v_pk_fma_f32 v[116:117], v[102:103], v[108:109], v[116:117] neg_lo:[0,0,1] neg_hi:[0,0,1]
	v_pk_mul_f32 v[108:109], v[110:111], v[108:109]
	s_nop 0
	v_pk_fma_f32 v[102:103], v[102:103], v[106:107], v[108:109]
	v_mul_f32_e32 v106, v209, v124
	v_cvt_f64_f32_e32 v[106:107], v106
	v_mul_f64 v[108:109], v[106:107], s[14:15]
	v_floor_f64_e32 v[108:109], v[108:109]
	v_fma_f64 v[106:107], v[106:107], s[14:15], -v[108:109]
	v_cvt_f32_f64_e32 v107, v[106:107]
	v_sin_f32_e32 v106, v107
	v_cos_f32_e32 v108, v107
	v_mul_f32_e32 v107, v208, v124
	v_cvt_f64_f32_e32 v[110:111], v107
	v_mul_f64 v[122:123], v[110:111], s[14:15]
	v_floor_f64_e32 v[122:123], v[122:123]
	v_fma_f64 v[110:111], v[110:111], s[14:15], -v[122:123]
	v_cvt_f32_f64_e32 v109, v[110:111]
	v_sin_f32_e32 v107, v109
	v_cos_f32_e32 v109, v109
	v_pk_mul_f32 v[110:111], v[112:113], v[106:107]
	s_nop 0
	v_pk_fma_f32 v[110:111], v[104:105], v[108:109], v[110:111] neg_lo:[0,0,1] neg_hi:[0,0,1]
	v_pk_mul_f32 v[108:109], v[112:113], v[108:109]
	s_nop 0
	v_pk_fma_f32 v[104:105], v[104:105], v[106:107], v[108:109]
	v_or_b32_e32 v106, v115, v189
	v_mul_lo_u32 v108, v106, v179
	v_mad_u64_u32 v[106:107], s[12:13], v106, v178, 0
	v_add3_u32 v107, v107, v108, v114
	v_lshl_add_u64 v[106:107], v[106:107], 1, v[180:181]
	v_cvt_pk_bf16_f32 v108, v120, v121
	v_cvt_pk_bf16_f32 v109, v118, v119
	global_store_dwordx2 v[106:107], v[108:109], off
	v_cvt_pk_bf16_f32 v108, v116, v117
	v_cvt_pk_bf16_f32 v109, v110, v111
	global_store_dwordx2 v[106:107], v[98:99], off offset:32
	v_cvt_pk_bf16_f32 v98, v102, v103
	v_cvt_pk_bf16_f32 v99, v104, v105
	global_store_dwordx2 v[106:107], v[108:109], off offset:16
	global_store_dwordx2 v[106:107], v[98:99], off offset:48
	v_or_b32_e32 v106, 64, v194
	v_and_or_b32 v98, v106, s1, v189
	v_cvt_f32_u32_e32 v107, v98
	s_movk_i32 s1, 0x1fe0
	v_mul_f32_e32 v98, v217, v107
	v_cvt_f64_f32_e32 v[98:99], v98
	v_mul_f64 v[100:101], v[98:99], s[14:15]
	v_floor_f64_e32 v[100:101], v[100:101]
	v_fma_f64 v[98:99], v[98:99], s[14:15], -v[100:101]
	v_cvt_f32_f64_e32 v99, v[98:99]
	v_sin_f32_e32 v98, v99
	v_cos_f32_e32 v100, v99
	v_mul_f32_e32 v99, v218, v107
	v_cvt_f64_f32_e32 v[102:103], v99
	v_mul_f64 v[104:105], v[102:103], s[14:15]
	v_floor_f64_e32 v[104:105], v[104:105]
	v_fma_f64 v[102:103], v[102:103], s[14:15], -v[104:105]
	v_cvt_f32_f64_e32 v101, v[102:103]
	v_sin_f32_e32 v99, v101
	v_cos_f32_e32 v101, v101
	v_pk_mul_f32 v[102:103], v[90:91], v[98:99]
	v_pk_mul_f32 v[90:91], v[90:91], v[100:101]
	v_pk_fma_f32 v[102:103], v[82:83], v[100:101], v[102:103] neg_lo:[0,0,1] neg_hi:[0,0,1]
	v_pk_fma_f32 v[82:83], v[82:83], v[98:99], v[90:91]
	v_mul_f32_e32 v90, v216, v107
	v_cvt_f64_f32_e32 v[90:91], v90
	v_mul_f64 v[98:99], v[90:91], s[14:15]
	v_floor_f64_e32 v[98:99], v[98:99]
	v_fma_f64 v[90:91], v[90:91], s[14:15], -v[98:99]
	v_cvt_f32_f64_e32 v91, v[90:91]
	v_sin_f32_e32 v90, v91
	v_cos_f32_e32 v98, v91
	v_mul_f32_e32 v91, v215, v107
	v_cvt_f64_f32_e32 v[100:101], v91
	v_mul_f64 v[104:105], v[100:101], s[14:15]
	v_floor_f64_e32 v[104:105], v[104:105]
	v_fma_f64 v[100:101], v[100:101], s[14:15], -v[104:105]
	v_cvt_f32_f64_e32 v99, v[100:101]
	v_sin_f32_e32 v91, v99
	v_cos_f32_e32 v99, v99
	v_cvt_pk_bf16_f32 v82, v82, v83
	v_pk_mul_f32 v[100:101], v[92:93], v[90:91]
	v_pk_mul_f32 v[92:93], v[92:93], v[98:99]
	v_pk_fma_f32 v[100:101], v[84:85], v[98:99], v[100:101] neg_lo:[0,0,1] neg_hi:[0,0,1]
	v_pk_fma_f32 v[84:85], v[84:85], v[90:91], v[92:93]
	v_mul_f32_e32 v90, v213, v107
	v_cvt_f64_f32_e32 v[90:91], v90
	v_mul_f64 v[92:93], v[90:91], s[14:15]
	v_floor_f64_e32 v[92:93], v[92:93]
	v_fma_f64 v[90:91], v[90:91], s[14:15], -v[92:93]
	v_cvt_f32_f64_e32 v91, v[90:91]
	v_sin_f32_e32 v90, v91
	v_cos_f32_e32 v92, v91
	v_mul_f32_e32 v91, v211, v107
	v_cvt_f64_f32_e32 v[98:99], v91
	v_mul_f64 v[104:105], v[98:99], s[14:15]
	v_floor_f64_e32 v[104:105], v[104:105]
	v_fma_f64 v[98:99], v[98:99], s[14:15], -v[104:105]
	v_cvt_f32_f64_e32 v93, v[98:99]
	v_sin_f32_e32 v91, v93
	v_cos_f32_e32 v93, v93
	v_cvt_pk_bf16_f32 v83, v84, v85
	v_pk_mul_f32 v[98:99], v[94:95], v[90:91]
	s_nop 0
	v_pk_fma_f32 v[98:99], v[86:87], v[92:93], v[98:99] neg_lo:[0,0,1] neg_hi:[0,0,1]
	v_pk_mul_f32 v[92:93], v[94:95], v[92:93]
	s_nop 0
	v_pk_fma_f32 v[86:87], v[86:87], v[90:91], v[92:93]
	v_mul_f32_e32 v90, v209, v107
	v_cvt_f64_f32_e32 v[90:91], v90
	v_mul_f64 v[92:93], v[90:91], s[14:15]
	v_floor_f64_e32 v[92:93], v[92:93]
	v_fma_f64 v[90:91], v[90:91], s[14:15], -v[92:93]
	v_cvt_f32_f64_e32 v91, v[90:91]
	v_sin_f32_e32 v90, v91
	v_cos_f32_e32 v92, v91
	v_mul_f32_e32 v91, v208, v107
	v_cvt_f64_f32_e32 v[94:95], v91
	v_mul_f64 v[104:105], v[94:95], s[14:15]
	v_floor_f64_e32 v[104:105], v[104:105]
	v_fma_f64 v[94:95], v[94:95], s[14:15], -v[104:105]
	v_cvt_f32_f64_e32 v93, v[94:95]
	v_sin_f32_e32 v91, v93
	v_cos_f32_e32 v93, v93
	v_pk_mul_f32 v[94:95], v[96:97], v[90:91]
	s_nop 0
	v_pk_fma_f32 v[94:95], v[88:89], v[92:93], v[94:95] neg_lo:[0,0,1] neg_hi:[0,0,1]
	v_pk_mul_f32 v[92:93], v[96:97], v[92:93]
	s_nop 0
	v_pk_fma_f32 v[88:89], v[88:89], v[90:91], v[92:93]
	v_or_b32_e32 v90, v106, v189
	v_mul_lo_u32 v92, v90, v179
	v_mad_u64_u32 v[90:91], s[12:13], v90, v178, 0
	v_add3_u32 v91, v91, v92, v114
	v_lshl_add_u64 v[90:91], v[90:91], 1, v[180:181]
	v_cvt_pk_bf16_f32 v92, v102, v103
	v_cvt_pk_bf16_f32 v93, v100, v101
	global_store_dwordx2 v[90:91], v[92:93], off
	v_cvt_pk_bf16_f32 v92, v98, v99
	v_cvt_pk_bf16_f32 v93, v94, v95
	global_store_dwordx2 v[90:91], v[82:83], off offset:32
	v_cvt_pk_bf16_f32 v82, v86, v87
	v_cvt_pk_bf16_f32 v83, v88, v89
	global_store_dwordx2 v[90:91], v[92:93], off offset:16
	global_store_dwordx2 v[90:91], v[82:83], off offset:48
	v_or_b32_e32 v90, 0x60, v194
	v_and_or_b32 v82, v90, s1, v189
	v_cvt_f32_u32_e32 v91, v82
	v_mul_f32_e32 v82, v217, v91
	v_cvt_f64_f32_e32 v[82:83], v82
	v_mul_f64 v[84:85], v[82:83], s[14:15]
	v_floor_f64_e32 v[84:85], v[84:85]
	v_fma_f64 v[82:83], v[82:83], s[14:15], -v[84:85]
	v_cvt_f32_f64_e32 v83, v[82:83]
	v_sin_f32_e32 v82, v83
	v_cos_f32_e32 v84, v83
	v_mul_f32_e32 v83, v218, v91
	v_cvt_f64_f32_e32 v[86:87], v83
	v_mul_f64 v[88:89], v[86:87], s[14:15]
	v_floor_f64_e32 v[88:89], v[88:89]
	v_fma_f64 v[86:87], v[86:87], s[14:15], -v[88:89]
	v_cvt_f32_f64_e32 v85, v[86:87]
	v_sin_f32_e32 v83, v85
	v_cos_f32_e32 v85, v85
	v_pk_mul_f32 v[86:87], v[74:75], v[82:83]
	v_pk_mul_f32 v[74:75], v[74:75], v[84:85]
	v_pk_fma_f32 v[86:87], v[66:67], v[84:85], v[86:87] neg_lo:[0,0,1] neg_hi:[0,0,1]
	v_pk_fma_f32 v[66:67], v[66:67], v[82:83], v[74:75]
	v_mul_f32_e32 v74, v216, v91
	v_cvt_f64_f32_e32 v[74:75], v74
	v_mul_f64 v[82:83], v[74:75], s[14:15]
	v_floor_f64_e32 v[82:83], v[82:83]
	v_fma_f64 v[74:75], v[74:75], s[14:15], -v[82:83]
	v_cvt_f32_f64_e32 v75, v[74:75]
	v_sin_f32_e32 v74, v75
	v_cos_f32_e32 v82, v75
	v_mul_f32_e32 v75, v215, v91
	v_cvt_f64_f32_e32 v[84:85], v75
	v_mul_f64 v[88:89], v[84:85], s[14:15]
	v_floor_f64_e32 v[88:89], v[88:89]
	v_fma_f64 v[84:85], v[84:85], s[14:15], -v[88:89]
	v_cvt_f32_f64_e32 v83, v[84:85]
	v_sin_f32_e32 v75, v83
	v_cos_f32_e32 v83, v83
	v_cvt_pk_bf16_f32 v66, v66, v67
	v_pk_mul_f32 v[84:85], v[76:77], v[74:75]
	v_pk_mul_f32 v[76:77], v[76:77], v[82:83]
	v_pk_fma_f32 v[84:85], v[68:69], v[82:83], v[84:85] neg_lo:[0,0,1] neg_hi:[0,0,1]
	v_pk_fma_f32 v[68:69], v[68:69], v[74:75], v[76:77]
	v_mul_f32_e32 v74, v213, v91
	v_cvt_f64_f32_e32 v[74:75], v74
	v_mul_f64 v[76:77], v[74:75], s[14:15]
	v_floor_f64_e32 v[76:77], v[76:77]
	v_fma_f64 v[74:75], v[74:75], s[14:15], -v[76:77]
	v_cvt_f32_f64_e32 v75, v[74:75]
	v_sin_f32_e32 v74, v75
	v_cos_f32_e32 v76, v75
	v_mul_f32_e32 v75, v211, v91
	v_cvt_f64_f32_e32 v[82:83], v75
	v_mul_f64 v[88:89], v[82:83], s[14:15]
	v_floor_f64_e32 v[88:89], v[88:89]
	v_fma_f64 v[82:83], v[82:83], s[14:15], -v[88:89]
	v_cvt_f32_f64_e32 v77, v[82:83]
	v_sin_f32_e32 v75, v77
	v_cos_f32_e32 v77, v77
	v_cvt_pk_bf16_f32 v67, v68, v69
	v_pk_mul_f32 v[82:83], v[78:79], v[74:75]
	s_nop 0
	v_pk_fma_f32 v[82:83], v[70:71], v[76:77], v[82:83] neg_lo:[0,0,1] neg_hi:[0,0,1]
	v_pk_mul_f32 v[76:77], v[78:79], v[76:77]
	s_nop 0
	v_pk_fma_f32 v[70:71], v[70:71], v[74:75], v[76:77]
	v_mul_f32_e32 v74, v209, v91
	v_cvt_f64_f32_e32 v[74:75], v74
	v_mul_f64 v[76:77], v[74:75], s[14:15]
	v_floor_f64_e32 v[76:77], v[76:77]
	v_fma_f64 v[74:75], v[74:75], s[14:15], -v[76:77]
	v_cvt_f32_f64_e32 v75, v[74:75]
	v_sin_f32_e32 v74, v75
	v_cos_f32_e32 v76, v75
	v_mul_f32_e32 v75, v208, v91
	v_cvt_f64_f32_e32 v[78:79], v75
	v_mul_f64 v[88:89], v[78:79], s[14:15]
	v_floor_f64_e32 v[88:89], v[88:89]
	v_fma_f64 v[78:79], v[78:79], s[14:15], -v[88:89]
	v_cvt_f32_f64_e32 v77, v[78:79]
	v_sin_f32_e32 v75, v77
	v_cos_f32_e32 v77, v77
	v_pk_mul_f32 v[78:79], v[80:81], v[74:75]
	s_nop 0
	v_pk_fma_f32 v[78:79], v[72:73], v[76:77], v[78:79] neg_lo:[0,0,1] neg_hi:[0,0,1]
	v_pk_mul_f32 v[76:77], v[80:81], v[76:77]
	s_nop 0
	v_pk_fma_f32 v[72:73], v[72:73], v[74:75], v[76:77]
	v_or_b32_e32 v74, v90, v189
	v_mul_lo_u32 v76, v74, v179
	v_mad_u64_u32 v[74:75], s[12:13], v74, v178, 0
	v_add3_u32 v75, v75, v76, v114
	v_lshl_add_u64 v[74:75], v[74:75], 1, v[180:181]
	v_cvt_pk_bf16_f32 v76, v86, v87
	v_cvt_pk_bf16_f32 v77, v84, v85
	global_store_dwordx2 v[74:75], v[76:77], off
	v_cvt_pk_bf16_f32 v76, v82, v83
	v_cvt_pk_bf16_f32 v77, v78, v79
	global_store_dwordx2 v[74:75], v[66:67], off offset:32
	v_cvt_pk_bf16_f32 v66, v70, v71
	v_cvt_pk_bf16_f32 v67, v72, v73
	global_store_dwordx2 v[74:75], v[76:77], off offset:16
	global_store_dwordx2 v[74:75], v[66:67], off offset:48

.LBB0_801:
	s_waitcnt lgkmcnt(0)
	s_barrier
	s_setprio 2
	v_bfe_u32 v221, v222, 5, 1
	v_bfe_u32 v248, v222, 4, 1
	v_lshl_add_u32 v211, v221, 4, v178
	v_lshl_add_u32 v215, v221, 4, v179
	v_mul_u32_u24_e32 v221, 0x8f0, v248
	v_mul_u32_u24_e32 v248, 0x8f8, v248
	v_sub_u32_e32 v213, v211, v248
	v_sub_u32_e32 v220, v215, v248
	v_sub_u32_e32 v211, v211, v221
	v_sub_u32_e32 v215, v215, v221
	ds_read_b128 v[190:193], v215 offset:36864
	ds_read_b128 v[194:197], v211
	ds_read_b128 v[198:201], v215 offset:39168
	ds_read_b128 v[202:205], v215 offset:41472
	ds_read_b128 v[206:209], v215 offset:43776
	ds_read_b128 v[216:219], v211 offset:2304
	ds_read_b128 v[236:239], v211 offset:4608
	ds_read_b128 v[240:243], v211 offset:6912
	ds_read_b128 v[244:247], v211 offset:9216
	s_waitcnt lgkmcnt(7)
	v_mfma_f32_16x16x32_bf16 v[98:101], v[190:193], v[194:197], v[98:101]
	s_waitcnt lgkmcnt(6)
	v_mfma_f32_16x16x32_bf16 v[106:109], v[198:201], v[194:197], v[106:109]
	s_waitcnt lgkmcnt(5)
	v_mfma_f32_16x16x32_bf16 v[114:117], v[202:205], v[194:197], v[114:117]
	s_waitcnt lgkmcnt(4)
	v_mfma_f32_16x16x32_bf16 v[122:125], v[206:209], v[194:197], v[122:125]
	ds_read_b128 v[194:197], v211 offset:11520
	s_waitcnt lgkmcnt(4)
	v_mfma_f32_16x16x32_bf16 v[102:105], v[190:193], v[216:219], v[102:105]
	v_mfma_f32_16x16x32_bf16 v[110:113], v[198:201], v[216:219], v[110:113]
	v_mfma_f32_16x16x32_bf16 v[118:121], v[202:205], v[216:219], v[118:121]
	v_mfma_f32_16x16x32_bf16 v[126:129], v[206:209], v[216:219], v[126:129]
	ds_read_b128 v[216:219], v211 offset:13824
	s_waitcnt lgkmcnt(4)
	v_mfma_f32_16x16x32_bf16 v[82:85], v[190:193], v[236:239], v[82:85]
	v_mfma_f32_16x16x32_bf16 v[90:93], v[198:201], v[236:239], v[90:93]
	v_mfma_f32_16x16x32_bf16 v[66:69], v[202:205], v[236:239], v[66:69]
	v_mfma_f32_16x16x32_bf16 v[74:77], v[206:209], v[236:239], v[74:77]
	ds_read_b128 v[236:239], v211 offset:16128
	s_waitcnt lgkmcnt(4)
	v_mfma_f32_16x16x32_bf16 v[86:89], v[190:193], v[240:243], v[86:89]
	v_mfma_f32_16x16x32_bf16 v[94:97], v[198:201], v[240:243], v[94:97]
	v_mfma_f32_16x16x32_bf16 v[70:73], v[202:205], v[240:243], v[70:73]
	v_mfma_f32_16x16x32_bf16 v[78:81], v[206:209], v[240:243], v[78:81]
	ds_read_b128 v[240:243], v215 offset:36928
	s_waitcnt lgkmcnt(4)
	v_mfma_f32_16x16x32_bf16 v[50:53], v[190:193], v[244:247], v[50:53]
	v_mfma_f32_16x16x32_bf16 v[58:61], v[198:201], v[244:247], v[58:61]
	v_mfma_f32_16x16x32_bf16 v[34:37], v[202:205], v[244:247], v[34:37]
	v_mfma_f32_16x16x32_bf16 v[42:45], v[206:209], v[244:247], v[42:45]
	ds_read_b128 v[244:247], v211 offset:64
	s_waitcnt lgkmcnt(4)
	v_mfma_f32_16x16x32_bf16 v[54:57], v[190:193], v[194:197], v[54:57]
	v_mfma_f32_16x16x32_bf16 v[62:65], v[198:201], v[194:197], v[62:65]
	v_mfma_f32_16x16x32_bf16 v[38:41], v[202:205], v[194:197], v[38:41]
	v_mfma_f32_16x16x32_bf16 v[46:49], v[206:209], v[194:197], v[46:49]
	ds_read_b128 v[194:197], v211 offset:2368
	s_waitcnt lgkmcnt(4)
	v_mfma_f32_16x16x32_bf16 v[18:21], v[190:193], v[216:219], v[18:21]
	s_waitcnt lgkmcnt(3)
	v_mfma_f32_16x16x32_bf16 v[22:25], v[190:193], v[236:239], v[22:25]
	ds_read_b128 v[190:193], v215 offset:39232
	v_mfma_f32_16x16x32_bf16 v[26:29], v[198:201], v[216:219], v[26:29]
	v_mfma_f32_16x16x32_bf16 v[30:33], v[198:201], v[236:239], v[30:33]
	ds_read_b128 v[198:201], v215 offset:41536
	v_mfma_f32_16x16x32_bf16 v[2:5], v[202:205], v[216:219], v[2:5]
	v_mfma_f32_16x16x32_bf16 v[6:9], v[202:205], v[236:239], v[6:9]
	ds_read_b128 v[202:205], v215 offset:43840
	v_mfma_f32_16x16x32_bf16 v[10:13], v[206:209], v[216:219], v[10:13]
	ds_read_b128 v[216:219], v211 offset:4672
	v_mfma_f32_16x16x32_bf16 v[14:17], v[206:209], v[236:239], v[14:17]
	ds_read_b128 v[206:209], v211 offset:6976
	ds_read_b128 v[236:239], v211 offset:9280
	s_waitcnt lgkmcnt(7)
	v_mfma_f32_16x16x32_bf16 v[98:101], v[240:243], v[244:247], v[98:101]
	s_waitcnt lgkmcnt(6)
	v_mfma_f32_16x16x32_bf16 v[102:105], v[240:243], v[194:197], v[102:105]
	s_waitcnt lgkmcnt(5)
	v_mfma_f32_16x16x32_bf16 v[106:109], v[190:193], v[244:247], v[106:109]
	v_mfma_f32_16x16x32_bf16 v[110:113], v[190:193], v[194:197], v[110:113]
	s_waitcnt lgkmcnt(4)
	v_mfma_f32_16x16x32_bf16 v[114:117], v[198:201], v[244:247], v[114:117]
	v_mfma_f32_16x16x32_bf16 v[118:121], v[198:201], v[194:197], v[118:121]
	s_waitcnt lgkmcnt(3)
	v_mfma_f32_16x16x32_bf16 v[122:125], v[202:205], v[244:247], v[122:125]
	ds_read_b128 v[244:247], v211 offset:11584
	v_mfma_f32_16x16x32_bf16 v[126:129], v[202:205], v[194:197], v[126:129]
	ds_read_b128 v[194:197], v211 offset:13888
	s_waitcnt lgkmcnt(4)
	v_mfma_f32_16x16x32_bf16 v[82:85], v[240:243], v[216:219], v[82:85]
	v_mfma_f32_16x16x32_bf16 v[90:93], v[190:193], v[216:219], v[90:93]
	v_mfma_f32_16x16x32_bf16 v[66:69], v[198:201], v[216:219], v[66:69]
	v_mfma_f32_16x16x32_bf16 v[74:77], v[202:205], v[216:219], v[74:77]
	ds_read_b128 v[216:219], v211 offset:16192
	s_waitcnt lgkmcnt(4)
	v_mfma_f32_16x16x32_bf16 v[86:89], v[240:243], v[206:209], v[86:89]
	v_mfma_f32_16x16x32_bf16 v[94:97], v[190:193], v[206:209], v[94:97]
	v_mfma_f32_16x16x32_bf16 v[70:73], v[198:201], v[206:209], v[70:73]
	v_mfma_f32_16x16x32_bf16 v[78:81], v[202:205], v[206:209], v[78:81]
	s_waitcnt lgkmcnt(3)
	v_mfma_f32_16x16x32_bf16 v[50:53], v[240:243], v[236:239], v[50:53]
	v_mfma_f32_16x16x32_bf16 v[58:61], v[190:193], v[236:239], v[58:61]
	v_mfma_f32_16x16x32_bf16 v[34:37], v[198:201], v[236:239], v[34:37]
	v_mfma_f32_16x16x32_bf16 v[42:45], v[202:205], v[236:239], v[42:45]
	s_waitcnt lgkmcnt(2)
	v_mfma_f32_16x16x32_bf16 v[54:57], v[240:243], v[244:247], v[54:57]
	v_mfma_f32_16x16x32_bf16 v[62:65], v[190:193], v[244:247], v[62:65]
	v_mfma_f32_16x16x32_bf16 v[38:41], v[198:201], v[244:247], v[38:41]
	v_mfma_f32_16x16x32_bf16 v[46:49], v[202:205], v[244:247], v[46:49]
	s_waitcnt lgkmcnt(1)
	v_mfma_f32_16x16x32_bf16 v[18:21], v[240:243], v[194:197], v[18:21]
	v_mfma_f32_16x16x32_bf16 v[26:29], v[190:193], v[194:197], v[26:29]
	v_mfma_f32_16x16x32_bf16 v[2:5], v[198:201], v[194:197], v[2:5]
	v_mfma_f32_16x16x32_bf16 v[10:13], v[202:205], v[194:197], v[10:13]
	s_waitcnt lgkmcnt(0)
	v_mfma_f32_16x16x32_bf16 v[22:25], v[240:243], v[216:219], v[22:25]
	v_mfma_f32_16x16x32_bf16 v[30:33], v[190:193], v[216:219], v[30:33]
	v_mfma_f32_16x16x32_bf16 v[6:9], v[198:201], v[216:219], v[6:9]
	v_mfma_f32_16x16x32_bf16 v[14:17], v[202:205], v[216:219], v[14:17]
	s_setprio 0

.LcL_801:
	s_waitcnt lgkmcnt(0)
	s_barrier
	s_setprio 2
	v_bfe_u32 v221, v222, 5, 1
	v_bfe_u32 v248, v222, 4, 1
	v_lshl_add_u32 v211, v221, 4, v178
	v_lshl_add_u32 v215, v221, 4, v179
	v_mul_u32_u24_e32 v221, 0x8f0, v248
	v_mul_u32_u24_e32 v248, 0x8f8, v248
	v_sub_u32_e32 v213, v211, v248
	v_sub_u32_e32 v220, v215, v248
	v_sub_u32_e32 v211, v211, v221
	v_sub_u32_e32 v215, v215, v221
	ds_read_b128 v[190:193], v215 offset:36864
	ds_read_b128 v[194:197], v211
	ds_read_b128 v[198:201], v215 offset:39168
	ds_read_b128 v[202:205], v215 offset:41472
	ds_read_b128 v[206:209], v215 offset:43776
	ds_read_b128 v[216:219], v211 offset:2304
	ds_read_b128 v[236:239], v211 offset:4608
	ds_read_b128 v[240:243], v211 offset:6912
	ds_read_b128 v[244:247], v211 offset:9216
	s_waitcnt lgkmcnt(7)
	v_mfma_f32_16x16x32_bf16 v[98:101], v[190:193], v[194:197], v[98:101]
	s_ashr_i32 s3, s2, 31
	s_lshl_b64 s[10:11], s[2:3], 7
	s_waitcnt lgkmcnt(6)
	v_mfma_f32_16x16x32_bf16 v[106:109], v[198:201], v[194:197], v[106:109]
	v_lshl_add_u64 v[154:155], v[180:181], 0, s[10:11]
	v_add_co_u32_e32 v130, vcc, 0x2c000, v154
	s_waitcnt lgkmcnt(5)
	v_mfma_f32_16x16x32_bf16 v[114:117], v[202:205], v[194:197], v[114:117]
	v_lshl_add_u64 v[170:171], v[182:183], 0, s[10:11]
	s_nop 0
	s_waitcnt lgkmcnt(4)
	v_mfma_f32_16x16x32_bf16 v[122:125], v[206:209], v[194:197], v[122:125]
	ds_read_b128 v[194:197], v211 offset:11520
	v_addc_co_u32_e32 v131, vcc, 0, v155, vcc
	v_add_co_u32_e32 v134, vcc, 0x58000, v154
	s_waitcnt lgkmcnt(4)
	v_mfma_f32_16x16x32_bf16 v[102:105], v[190:193], v[216:219], v[102:105]
	global_load_dwordx4 v[142:145], v[154:155], off
	s_nop 0
	v_mfma_f32_16x16x32_bf16 v[110:113], v[198:201], v[216:219], v[110:113]
	global_load_dwordx4 v[130:133], v[130:131], off
	v_addc_co_u32_e32 v135, vcc, 0, v155, vcc
	v_mfma_f32_16x16x32_bf16 v[118:121], v[202:205], v[216:219], v[118:121]
	v_add_co_u32_e32 v138, vcc, 0x84000, v154
	s_add_i32 s2, s2, 1
	v_mfma_f32_16x16x32_bf16 v[126:129], v[206:209], v[216:219], v[126:129]
	ds_read_b128 v[216:219], v211 offset:13824
	s_nop 0
	v_addc_co_u32_e32 v139, vcc, 0, v155, vcc
	s_waitcnt lgkmcnt(4)
	v_mfma_f32_16x16x32_bf16 v[82:85], v[190:193], v[236:239], v[82:85]
	v_add_co_u32_e32 v146, vcc, 0xb0000, v154
	global_load_dwordx4 v[134:137], v[134:135], off
	v_mfma_f32_16x16x32_bf16 v[90:93], v[198:201], v[236:239], v[90:93]
	s_nop 0
	global_load_dwordx4 v[138:141], v[138:139], off
	v_mfma_f32_16x16x32_bf16 v[66:69], v[202:205], v[236:239], v[66:69]
	v_addc_co_u32_e32 v147, vcc, 0, v155, vcc
	v_add_co_u32_e32 v150, vcc, 0xdc000, v154
	v_mfma_f32_16x16x32_bf16 v[74:77], v[206:209], v[236:239], v[74:77]
	ds_read_b128 v[236:239], v211 offset:16128
	s_nop 0
	v_addc_co_u32_e32 v151, vcc, 0, v155, vcc
	s_waitcnt lgkmcnt(4)
	v_mfma_f32_16x16x32_bf16 v[86:89], v[190:193], v[240:243], v[86:89]
	v_add_co_u32_e32 v156, vcc, 0x108000, v154
	global_load_dwordx4 v[146:149], v[146:147], off
	v_mfma_f32_16x16x32_bf16 v[94:97], v[198:201], v[240:243], v[94:97]
	s_nop 0
	global_load_dwordx4 v[150:153], v[150:151], off
	v_mfma_f32_16x16x32_bf16 v[70:73], v[202:205], v[240:243], v[70:73]
	v_addc_co_u32_e32 v157, vcc, 0, v155, vcc
	v_add_co_u32_e32 v158, vcc, 0x134000, v154
	v_mfma_f32_16x16x32_bf16 v[78:81], v[206:209], v[240:243], v[78:81]
	ds_read_b128 v[240:243], v215 offset:36928
	s_nop 1
	v_addc_co_u32_e32 v159, vcc, 0, v155, vcc
	s_waitcnt lgkmcnt(4)
	v_mfma_f32_16x16x32_bf16 v[50:53], v[190:193], v[244:247], v[50:53]
	v_add_co_u32_e32 v166, vcc, 0x2c000, v170
	global_load_dwordx4 v[154:157], v[156:157], off
	v_mfma_f32_16x16x32_bf16 v[58:61], v[198:201], v[244:247], v[58:61]
	s_nop 0
	global_load_dwordx4 v[158:161], v[158:159], off
	v_mfma_f32_16x16x32_bf16 v[34:37], v[202:205], v[244:247], v[34:37]
	v_addc_co_u32_e32 v167, vcc, 0, v171, vcc
	v_add_co_u32_e32 v172, vcc, 0x58000, v170
	v_mfma_f32_16x16x32_bf16 v[42:45], v[206:209], v[244:247], v[42:45]
	ds_read_b128 v[244:247], v211 offset:64
	global_load_dwordx4 v[162:165], v[170:171], off
	s_nop 0
	s_waitcnt lgkmcnt(4)
	v_mfma_f32_16x16x32_bf16 v[54:57], v[190:193], v[194:197], v[54:57]
	global_load_dwordx4 v[166:169], v[166:167], off
	v_addc_co_u32_e32 v173, vcc, 0, v171, vcc
	v_mfma_f32_16x16x32_bf16 v[62:65], v[198:201], v[194:197], v[62:65]
	v_add_co_u32_e32 v174, vcc, 0x84000, v170
	s_nop 1
	v_mfma_f32_16x16x32_bf16 v[38:41], v[202:205], v[194:197], v[38:41]
	v_addc_co_u32_e32 v175, vcc, 0, v171, vcc
	global_load_dwordx4 v[170:173], v[172:173], off
	v_mfma_f32_16x16x32_bf16 v[46:49], v[206:209], v[194:197], v[46:49]
	ds_read_b128 v[194:197], v211 offset:2368
	s_nop 0
	global_load_dwordx4 v[174:177], v[174:175], off
	s_waitcnt lgkmcnt(4)
	v_mfma_f32_16x16x32_bf16 v[18:21], v[190:193], v[216:219], v[18:21]
	s_cmp_lg_u32 s2, 44
	s_waitcnt lgkmcnt(3)
	v_mfma_f32_16x16x32_bf16 v[22:25], v[190:193], v[236:239], v[22:25]
	ds_read_b128 v[190:193], v215 offset:39232
	v_mfma_f32_16x16x32_bf16 v[26:29], v[198:201], v[216:219], v[26:29]
	v_mfma_f32_16x16x32_bf16 v[30:33], v[198:201], v[236:239], v[30:33]
	ds_read_b128 v[198:201], v215 offset:41536
	v_mfma_f32_16x16x32_bf16 v[2:5], v[202:205], v[216:219], v[2:5]
	v_mfma_f32_16x16x32_bf16 v[6:9], v[202:205], v[236:239], v[6:9]
	ds_read_b128 v[202:205], v215 offset:43840
	v_mfma_f32_16x16x32_bf16 v[10:13], v[206:209], v[216:219], v[10:13]
	ds_read_b128 v[216:219], v211 offset:4672
	v_mfma_f32_16x16x32_bf16 v[14:17], v[206:209], v[236:239], v[14:17]
	ds_read_b128 v[206:209], v211 offset:6976
	ds_read_b128 v[236:239], v211 offset:9280
	s_waitcnt lgkmcnt(7)
	v_mfma_f32_16x16x32_bf16 v[98:101], v[240:243], v[244:247], v[98:101]
	s_waitcnt lgkmcnt(6)
	v_mfma_f32_16x16x32_bf16 v[102:105], v[240:243], v[194:197], v[102:105]
	s_waitcnt lgkmcnt(5)
	v_mfma_f32_16x16x32_bf16 v[106:109], v[190:193], v[244:247], v[106:109]
	v_mfma_f32_16x16x32_bf16 v[110:113], v[190:193], v[194:197], v[110:113]
	s_waitcnt lgkmcnt(4)
	v_mfma_f32_16x16x32_bf16 v[114:117], v[198:201], v[244:247], v[114:117]
	v_mfma_f32_16x16x32_bf16 v[118:121], v[198:201], v[194:197], v[118:121]
	s_waitcnt lgkmcnt(3)
	v_mfma_f32_16x16x32_bf16 v[122:125], v[202:205], v[244:247], v[122:125]
	ds_read_b128 v[244:247], v211 offset:11584
	v_mfma_f32_16x16x32_bf16 v[126:129], v[202:205], v[194:197], v[126:129]
	ds_read_b128 v[194:197], v211 offset:13888
	s_waitcnt lgkmcnt(4)
	v_mfma_f32_16x16x32_bf16 v[82:85], v[240:243], v[216:219], v[82:85]
	v_mfma_f32_16x16x32_bf16 v[90:93], v[190:193], v[216:219], v[90:93]
	v_mfma_f32_16x16x32_bf16 v[66:69], v[198:201], v[216:219], v[66:69]
	v_mfma_f32_16x16x32_bf16 v[74:77], v[202:205], v[216:219], v[74:77]
	ds_read_b128 v[216:219], v211 offset:16192
	s_waitcnt lgkmcnt(4)
	v_mfma_f32_16x16x32_bf16 v[86:89], v[240:243], v[206:209], v[86:89]
	v_mfma_f32_16x16x32_bf16 v[94:97], v[190:193], v[206:209], v[94:97]
	v_mfma_f32_16x16x32_bf16 v[70:73], v[198:201], v[206:209], v[70:73]
	v_mfma_f32_16x16x32_bf16 v[78:81], v[202:205], v[206:209], v[78:81]
	s_waitcnt lgkmcnt(3)
	v_mfma_f32_16x16x32_bf16 v[50:53], v[240:243], v[236:239], v[50:53]
	v_mfma_f32_16x16x32_bf16 v[58:61], v[190:193], v[236:239], v[58:61]
	v_mfma_f32_16x16x32_bf16 v[34:37], v[198:201], v[236:239], v[34:37]
	v_mfma_f32_16x16x32_bf16 v[42:45], v[202:205], v[236:239], v[42:45]
	s_waitcnt lgkmcnt(2)
	v_mfma_f32_16x16x32_bf16 v[54:57], v[240:243], v[244:247], v[54:57]
	v_mfma_f32_16x16x32_bf16 v[62:65], v[190:193], v[244:247], v[62:65]
	v_mfma_f32_16x16x32_bf16 v[38:41], v[198:201], v[244:247], v[38:41]
	v_mfma_f32_16x16x32_bf16 v[46:49], v[202:205], v[244:247], v[46:49]
	s_waitcnt lgkmcnt(1)
	v_mfma_f32_16x16x32_bf16 v[18:21], v[240:243], v[194:197], v[18:21]
	v_mfma_f32_16x16x32_bf16 v[26:29], v[190:193], v[194:197], v[26:29]
	v_mfma_f32_16x16x32_bf16 v[2:5], v[198:201], v[194:197], v[2:5]
	v_mfma_f32_16x16x32_bf16 v[10:13], v[202:205], v[194:197], v[10:13]
	s_waitcnt lgkmcnt(0)
	v_mfma_f32_16x16x32_bf16 v[22:25], v[240:243], v[216:219], v[22:25]
	v_mfma_f32_16x16x32_bf16 v[30:33], v[190:193], v[216:219], v[30:33]
	v_mfma_f32_16x16x32_bf16 v[6:9], v[198:201], v[216:219], v[6:9]
	v_mfma_f32_16x16x32_bf16 v[14:17], v[202:205], v[216:219], v[14:17]
	s_setprio 0
	s_cbranch_scc1 .Ltail_801
	s_add_i32 s4, s4, 1
	s_cmp_ge_i32 s4, s8
	s_cbranch_scc1 .Lz_801
	s_mul_i32 s2, s4, s82
	s_add_i32 s2, s2, s63
	s_ashr_i32 s3, s2, 31
	s_lshr_b32 s3, s3, 28
	s_add_i32 s3, s2, s3
	s_ashr_i32 s10, s3, 4
	s_and_b32 s3, s3, -16
	s_sub_i32 s2, s2, s3
	s_lshl_b32 s3, s10, 1
	s_and_b32 s10, s2, 1
	s_or_b32 s10, s10, s3
	s_lshr_b32 s11, s2, 1
	v_readlane_b32 s2, v252, 35
	s_sub_i32 s12, 0x7f, s10
	v_readlane_b32 s3, v252, 36
	s_and_b64 s[2:3], s[2:3], exec
	s_mul_i32 s2, s11, 0x58000
	s_cselect_b32 s10, s12, s10
	s_ashr_i32 s3, s2, 31
	v_mov_b32_e32 v0, 0x160000
	v_mad_i64_i32 v[180:181], s[10:11], s10, v0, v[186:187]
	v_lshl_add_u64 v[182:183], s[2:3], 1, v[188:189]

.LBB0_807:
	s_nop 7
	v_permlane16_swap_b32_e32 v98, v102
	v_permlane16_swap_b32_e32 v99, v103
	v_permlane16_swap_b32_e32 v100, v104
	v_permlane16_swap_b32_e32 v101, v105
	v_permlane16_swap_b32_e32 v106, v110
	v_permlane16_swap_b32_e32 v107, v111
	v_permlane16_swap_b32_e32 v108, v112
	v_permlane16_swap_b32_e32 v109, v113
	v_permlane32_swap_b32_e32 v98, v102
	v_permlane32_swap_b32_e32 v99, v103
	v_permlane32_swap_b32_e32 v100, v104
	v_permlane32_swap_b32_e32 v101, v105
	v_permlane32_swap_b32_e32 v106, v110
	v_permlane32_swap_b32_e32 v107, v111
	v_permlane32_swap_b32_e32 v108, v112
	v_permlane32_swap_b32_e32 v109, v113
	v_permlane16_swap_b32_e32 v114, v118
	v_permlane16_swap_b32_e32 v115, v119
	v_permlane16_swap_b32_e32 v116, v120
	v_permlane16_swap_b32_e32 v117, v121
	v_permlane16_swap_b32_e32 v122, v126
	v_permlane16_swap_b32_e32 v123, v127
	v_permlane16_swap_b32_e32 v124, v128
	v_permlane16_swap_b32_e32 v125, v129
	v_permlane32_swap_b32_e32 v114, v118
	v_permlane32_swap_b32_e32 v115, v119
	v_permlane32_swap_b32_e32 v116, v120
	v_permlane32_swap_b32_e32 v117, v121
	v_permlane32_swap_b32_e32 v122, v126
	v_permlane32_swap_b32_e32 v123, v127
	v_permlane32_swap_b32_e32 v124, v128
	v_permlane32_swap_b32_e32 v125, v129
	v_permlane16_swap_b32_e32 v82, v86
	v_permlane16_swap_b32_e32 v83, v87
	v_permlane16_swap_b32_e32 v84, v88
	v_permlane16_swap_b32_e32 v85, v89
	v_permlane16_swap_b32_e32 v90, v94
	v_permlane16_swap_b32_e32 v91, v95
	v_permlane16_swap_b32_e32 v92, v96
	v_permlane16_swap_b32_e32 v93, v97
	v_permlane32_swap_b32_e32 v82, v86
	v_permlane32_swap_b32_e32 v83, v87
	v_permlane32_swap_b32_e32 v84, v88
	v_permlane32_swap_b32_e32 v85, v89
	v_permlane32_swap_b32_e32 v90, v94
	v_permlane32_swap_b32_e32 v91, v95
	v_permlane32_swap_b32_e32 v92, v96
	v_permlane32_swap_b32_e32 v93, v97
	v_permlane16_swap_b32_e32 v66, v70
	v_permlane16_swap_b32_e32 v67, v71
	v_permlane16_swap_b32_e32 v68, v72
	v_permlane16_swap_b32_e32 v69, v73
	v_permlane16_swap_b32_e32 v74, v78
	v_permlane16_swap_b32_e32 v75, v79
	v_permlane16_swap_b32_e32 v76, v80
	v_permlane16_swap_b32_e32 v77, v81
	v_permlane32_swap_b32_e32 v66, v70
	v_permlane32_swap_b32_e32 v67, v71
	v_permlane32_swap_b32_e32 v68, v72
	v_permlane32_swap_b32_e32 v69, v73
	v_permlane32_swap_b32_e32 v74, v78
	v_permlane32_swap_b32_e32 v75, v79
	v_permlane32_swap_b32_e32 v76, v80
	v_permlane32_swap_b32_e32 v77, v81
	v_permlane16_swap_b32_e32 v50, v54
	v_permlane16_swap_b32_e32 v51, v55
	v_permlane16_swap_b32_e32 v52, v56
	v_permlane16_swap_b32_e32 v53, v57
	v_permlane16_swap_b32_e32 v58, v62
	v_permlane16_swap_b32_e32 v59, v63
	v_permlane16_swap_b32_e32 v60, v64
	v_permlane16_swap_b32_e32 v61, v65
	v_permlane32_swap_b32_e32 v50, v54
	v_permlane32_swap_b32_e32 v51, v55
	v_permlane32_swap_b32_e32 v52, v56
	v_permlane32_swap_b32_e32 v53, v57
	v_permlane32_swap_b32_e32 v58, v62
	v_permlane32_swap_b32_e32 v59, v63
	v_permlane32_swap_b32_e32 v60, v64
	v_permlane32_swap_b32_e32 v61, v65
	v_permlane16_swap_b32_e32 v34, v38
	v_permlane16_swap_b32_e32 v35, v39
	v_permlane16_swap_b32_e32 v36, v40
	v_permlane16_swap_b32_e32 v37, v41
	v_permlane16_swap_b32_e32 v42, v46
	v_permlane16_swap_b32_e32 v43, v47
	v_permlane16_swap_b32_e32 v44, v48
	v_permlane16_swap_b32_e32 v45, v49
	v_permlane32_swap_b32_e32 v34, v38
	v_permlane32_swap_b32_e32 v35, v39
	v_permlane32_swap_b32_e32 v36, v40
	v_permlane32_swap_b32_e32 v37, v41
	v_permlane32_swap_b32_e32 v42, v46
	v_permlane32_swap_b32_e32 v43, v47
	v_permlane32_swap_b32_e32 v44, v48
	v_permlane32_swap_b32_e32 v45, v49
	v_permlane16_swap_b32_e32 v18, v22
	v_permlane16_swap_b32_e32 v19, v23
	v_permlane16_swap_b32_e32 v20, v24
	v_permlane16_swap_b32_e32 v21, v25
	v_permlane16_swap_b32_e32 v26, v30
	v_permlane16_swap_b32_e32 v27, v31
	v_permlane16_swap_b32_e32 v28, v32
	v_permlane16_swap_b32_e32 v29, v33
	v_permlane32_swap_b32_e32 v18, v22
	v_permlane32_swap_b32_e32 v19, v23
	v_permlane32_swap_b32_e32 v20, v24
	v_permlane32_swap_b32_e32 v21, v25
	v_permlane32_swap_b32_e32 v26, v30
	v_permlane32_swap_b32_e32 v27, v31
	v_permlane32_swap_b32_e32 v28, v32
	v_permlane32_swap_b32_e32 v29, v33
	v_permlane16_swap_b32_e32 v2, v6
	v_permlane16_swap_b32_e32 v3, v7
	v_permlane16_swap_b32_e32 v4, v8
	v_permlane16_swap_b32_e32 v5, v9
	v_permlane16_swap_b32_e32 v10, v14
	v_permlane16_swap_b32_e32 v11, v15
	v_permlane16_swap_b32_e32 v12, v16
	v_permlane16_swap_b32_e32 v13, v17
	v_permlane32_swap_b32_e32 v2, v6
	v_permlane32_swap_b32_e32 v3, v7
	v_permlane32_swap_b32_e32 v4, v8
	v_permlane32_swap_b32_e32 v5, v9
	v_permlane32_swap_b32_e32 v10, v14
	v_permlane32_swap_b32_e32 v11, v15
	v_permlane32_swap_b32_e32 v12, v16
	v_permlane32_swap_b32_e32 v13, v17
	s_mul_i32 s3, s9, s82
	s_add_i32 s3, s3, s63
	s_ashr_i32 s5, s3, 31
	s_lshr_b32 s5, s5, 28
	s_add_i32 s5, s3, s5
	s_ashr_i32 s10, s5, 4
	s_and_b32 s5, s5, -16
	s_sub_i32 s3, s3, s5
	s_lshl_b32 s5, s10, 1
	s_and_b32 s10, s3, 1
	s_or_b32 s5, s10, s5
	v_readlane_b32 s10, v252, 35
	s_sub_i32 s12, 0x7f, s5
	v_readlane_b32 s11, v252, 36
	s_and_b64 s[10:11], s[10:11], exec
	s_cselect_b32 s10, s12, s5
	v_mov_b32_e32 v0, v222
	s_ashr_i32 s11, s10, 31
	v_and_b32_e32 v190, 0xffffff80, v0
	s_lshl_b64 s[10:11], s[10:11], 8
	v_ashrrev_i32_e32 v191, 31, v190
	v_lshl_add_u64 v[190:191], s[10:11], 0, v[190:191]
	s_lshl_b32 s3, s3, 6
	v_and_b32_e32 v185, 64, v0
	v_and_or_b32 v190, v0, 31, v190
	s_and_b32 s3, s3, 0xffffff80
	v_lshrrev_b32_e32 v0, 3, v0
	s_ashr_i32 s5, s3, 31
	v_and_b32_e32 v0, 4, v0
	v_or3_b32 v192, v0, v185, s3
	v_mov_b32_e32 v193, s5
	v_lshlrev_b64 v[190:191], 10, v[190:191]
	v_lshl_add_u64 v[190:191], v[190:191], 0, v[192:193]
	v_lshlrev_b64 v[190:191], 2, v[190:191]
	v_lshl_add_u64 v[196:197], s[0:1], 0, v[190:191]
	s_mov_b64 s[98:99], 0x20000
	v_readlane_b32 s12, v252, 31
	v_readlane_b32 s13, v252, 32
	v_lshl_add_u64 v[220:221], s[12:13], 0, v[190:191]
	v_lshl_add_u64 v[192:193], v[196:197], 0, 0
	global_load_dwordx4 v[194:197], v[192:193], off
	global_load_dwordx4 v[198:201], v[192:193], off offset:32
	global_load_dwordx4 v[202:205], v[192:193], off offset:64
	global_load_dwordx4 v[206:209], v[192:193], off offset:96
	global_load_dwordx4 v[216:219], v[192:193], off offset:128
	global_load_dwordx4 v[236:239], v[192:193], off offset:160
	global_load_dwordx4 v[240:243], v[192:193], off offset:192
	global_load_dwordx4 v[244:247], v[192:193], off offset:224
	s_waitcnt vmcnt(7)
	v_pk_fma_f32 v[98:99], v[98:99], 0.5, v[194:195] op_sel_hi:[1,0,1]
	v_pk_fma_f32 v[100:101], v[100:101], 0.5, v[196:197] op_sel_hi:[1,0,1]
	global_store_dwordx4 v[220:221], v[98:101], off
	v_lshl_add_u64 v[192:193], v[192:193], 0, s[98:99]
	global_load_dwordx4 v[194:197], v[192:193], off
	s_waitcnt vmcnt(8)
	v_pk_fma_f32 v[102:103], v[102:103], 0.5, v[198:199] op_sel_hi:[1,0,1]
	v_pk_fma_f32 v[104:105], v[104:105], 0.5, v[200:201] op_sel_hi:[1,0,1]
	global_store_dwordx4 v[220:221], v[102:105], off offset:32
	global_load_dwordx4 v[198:201], v[192:193], off offset:32
	s_waitcnt vmcnt(9)
	v_pk_fma_f32 v[106:107], v[106:107], 0.5, v[202:203] op_sel_hi:[1,0,1]
	v_pk_fma_f32 v[108:109], v[108:109], 0.5, v[204:205] op_sel_hi:[1,0,1]
	global_store_dwordx4 v[220:221], v[106:109], off offset:64
	global_load_dwordx4 v[202:205], v[192:193], off offset:64
	s_waitcnt vmcnt(10)
	v_pk_fma_f32 v[110:111], v[110:111], 0.5, v[206:207] op_sel_hi:[1,0,1]
	v_pk_fma_f32 v[112:113], v[112:113], 0.5, v[208:209] op_sel_hi:[1,0,1]
	global_store_dwordx4 v[220:221], v[110:113], off offset:96
	global_load_dwordx4 v[206:209], v[192:193], off offset:96
	s_waitcnt vmcnt(11)
	v_pk_fma_f32 v[114:115], v[114:115], 0.5, v[216:217] op_sel_hi:[1,0,1]
	v_pk_fma_f32 v[116:117], v[116:117], 0.5, v[218:219] op_sel_hi:[1,0,1]
	global_store_dwordx4 v[220:221], v[114:117], off offset:128
	global_load_dwordx4 v[216:219], v[192:193], off offset:128
	s_waitcnt vmcnt(12)
	v_pk_fma_f32 v[118:119], v[118:119], 0.5, v[236:237] op_sel_hi:[1,0,1]
	v_pk_fma_f32 v[120:121], v[120:121], 0.5, v[238:239] op_sel_hi:[1,0,1]
	global_store_dwordx4 v[220:221], v[118:121], off offset:160
	global_load_dwordx4 v[236:239], v[192:193], off offset:160
	s_waitcnt vmcnt(13)
	v_pk_fma_f32 v[122:123], v[122:123], 0.5, v[240:241] op_sel_hi:[1,0,1]
	v_pk_fma_f32 v[124:125], v[124:125], 0.5, v[242:243] op_sel_hi:[1,0,1]
	global_store_dwordx4 v[220:221], v[122:125], off offset:192
	global_load_dwordx4 v[240:243], v[192:193], off offset:192
	s_waitcnt vmcnt(14)
	v_pk_fma_f32 v[126:127], v[126:127], 0.5, v[244:245] op_sel_hi:[1,0,1]
	v_pk_fma_f32 v[128:129], v[128:129], 0.5, v[246:247] op_sel_hi:[1,0,1]
	global_store_dwordx4 v[220:221], v[126:129], off offset:224
	global_load_dwordx4 v[244:247], v[192:193], off offset:224
	s_waitcnt vmcnt(14)
	v_pk_fma_f32 v[82:83], v[82:83], 0.5, v[194:195] op_sel_hi:[1,0,1]
	v_pk_fma_f32 v[84:85], v[84:85], 0.5, v[196:197] op_sel_hi:[1,0,1]
	v_lshl_add_u64 v[220:221], v[220:221], 0, s[98:99]
	global_store_dwordx4 v[220:221], v[82:85], off
	v_lshl_add_u64 v[192:193], v[192:193], 0, s[98:99]
	global_load_dwordx4 v[194:197], v[192:193], off
	s_waitcnt vmcnt(14)
	v_pk_fma_f32 v[86:87], v[86:87], 0.5, v[198:199] op_sel_hi:[1,0,1]
	v_pk_fma_f32 v[88:89], v[88:89], 0.5, v[200:201] op_sel_hi:[1,0,1]
	global_store_dwordx4 v[220:221], v[86:89], off offset:32
	global_load_dwordx4 v[198:201], v[192:193], off offset:32
	s_waitcnt vmcnt(14)
	v_pk_fma_f32 v[90:91], v[90:91], 0.5, v[202:203] op_sel_hi:[1,0,1]
	v_pk_fma_f32 v[92:93], v[92:93], 0.5, v[204:205] op_sel_hi:[1,0,1]
	global_store_dwordx4 v[220:221], v[90:93], off offset:64
	global_load_dwordx4 v[202:205], v[192:193], off offset:64
	s_waitcnt vmcnt(14)
	v_pk_fma_f32 v[94:95], v[94:95], 0.5, v[206:207] op_sel_hi:[1,0,1]
	v_pk_fma_f32 v[96:97], v[96:97], 0.5, v[208:209] op_sel_hi:[1,0,1]
	global_store_dwordx4 v[220:221], v[94:97], off offset:96
	global_load_dwordx4 v[206:209], v[192:193], off offset:96
	s_waitcnt vmcnt(14)
	v_pk_fma_f32 v[66:67], v[66:67], 0.5, v[216:217] op_sel_hi:[1,0,1]
	v_pk_fma_f32 v[68:69], v[68:69], 0.5, v[218:219] op_sel_hi:[1,0,1]
	global_store_dwordx4 v[220:221], v[66:69], off offset:128
	global_load_dwordx4 v[216:219], v[192:193], off offset:128
	s_waitcnt vmcnt(14)
	v_pk_fma_f32 v[70:71], v[70:71], 0.5, v[236:237] op_sel_hi:[1,0,1]
	v_pk_fma_f32 v[72:73], v[72:73], 0.5, v[238:239] op_sel_hi:[1,0,1]
	global_store_dwordx4 v[220:221], v[70:73], off offset:160
	global_load_dwordx4 v[236:239], v[192:193], off offset:160
	s_waitcnt vmcnt(14)
	v_pk_fma_f32 v[74:75], v[74:75], 0.5, v[240:241] op_sel_hi:[1,0,1]
	v_pk_fma_f32 v[76:77], v[76:77], 0.5, v[242:243] op_sel_hi:[1,0,1]
	global_store_dwordx4 v[220:221], v[74:77], off offset:192
	global_load_dwordx4 v[240:243], v[192:193], off offset:192
	s_waitcnt vmcnt(14)
	v_pk_fma_f32 v[78:79], v[78:79], 0.5, v[244:245] op_sel_hi:[1,0,1]
	v_pk_fma_f32 v[80:81], v[80:81], 0.5, v[246:247] op_sel_hi:[1,0,1]
	global_store_dwordx4 v[220:221], v[78:81], off offset:224
	global_load_dwordx4 v[244:247], v[192:193], off offset:224
	s_waitcnt vmcnt(14)
	v_pk_fma_f32 v[50:51], v[50:51], 0.5, v[194:195] op_sel_hi:[1,0,1]
	v_pk_fma_f32 v[52:53], v[52:53], 0.5, v[196:197] op_sel_hi:[1,0,1]
	v_lshl_add_u64 v[220:221], v[220:221], 0, s[98:99]
	global_store_dwordx4 v[220:221], v[50:53], off
	v_lshl_add_u64 v[192:193], v[192:193], 0, s[98:99]
	global_load_dwordx4 v[194:197], v[192:193], off
	s_waitcnt vmcnt(14)
	v_pk_fma_f32 v[54:55], v[54:55], 0.5, v[198:199] op_sel_hi:[1,0,1]
	v_pk_fma_f32 v[56:57], v[56:57], 0.5, v[200:201] op_sel_hi:[1,0,1]
	global_store_dwordx4 v[220:221], v[54:57], off offset:32
	global_load_dwordx4 v[198:201], v[192:193], off offset:32
	s_waitcnt vmcnt(14)
	v_pk_fma_f32 v[58:59], v[58:59], 0.5, v[202:203] op_sel_hi:[1,0,1]
	v_pk_fma_f32 v[60:61], v[60:61], 0.5, v[204:205] op_sel_hi:[1,0,1]
	global_store_dwordx4 v[220:221], v[58:61], off offset:64
	global_load_dwordx4 v[202:205], v[192:193], off offset:64
	s_waitcnt vmcnt(14)
	v_pk_fma_f32 v[62:63], v[62:63], 0.5, v[206:207] op_sel_hi:[1,0,1]
	v_pk_fma_f32 v[64:65], v[64:65], 0.5, v[208:209] op_sel_hi:[1,0,1]
	global_store_dwordx4 v[220:221], v[62:65], off offset:96
	global_load_dwordx4 v[206:209], v[192:193], off offset:96
	s_waitcnt vmcnt(14)
	v_pk_fma_f32 v[34:35], v[34:35], 0.5, v[216:217] op_sel_hi:[1,0,1]
	v_pk_fma_f32 v[36:37], v[36:37], 0.5, v[218:219] op_sel_hi:[1,0,1]
	global_store_dwordx4 v[220:221], v[34:37], off offset:128
	global_load_dwordx4 v[216:219], v[192:193], off offset:128
	s_waitcnt vmcnt(14)
	v_pk_fma_f32 v[38:39], v[38:39], 0.5, v[236:237] op_sel_hi:[1,0,1]
	v_pk_fma_f32 v[40:41], v[40:41], 0.5, v[238:239] op_sel_hi:[1,0,1]
	global_store_dwordx4 v[220:221], v[38:41], off offset:160
	global_load_dwordx4 v[236:239], v[192:193], off offset:160
	s_waitcnt vmcnt(14)
	v_pk_fma_f32 v[42:43], v[42:43], 0.5, v[240:241] op_sel_hi:[1,0,1]
	v_pk_fma_f32 v[44:45], v[44:45], 0.5, v[242:243] op_sel_hi:[1,0,1]
	global_store_dwordx4 v[220:221], v[42:45], off offset:192
	global_load_dwordx4 v[240:243], v[192:193], off offset:192
	s_waitcnt vmcnt(14)
	v_pk_fma_f32 v[46:47], v[46:47], 0.5, v[244:245] op_sel_hi:[1,0,1]
	v_pk_fma_f32 v[48:49], v[48:49], 0.5, v[246:247] op_sel_hi:[1,0,1]
	global_store_dwordx4 v[220:221], v[46:49], off offset:224
	global_load_dwordx4 v[244:247], v[192:193], off offset:224
	s_waitcnt vmcnt(14)
	v_pk_fma_f32 v[18:19], v[18:19], 0.5, v[194:195] op_sel_hi:[1,0,1]
	v_pk_fma_f32 v[20:21], v[20:21], 0.5, v[196:197] op_sel_hi:[1,0,1]
	v_lshl_add_u64 v[220:221], v[220:221], 0, s[98:99]
	global_store_dwordx4 v[220:221], v[18:21], off
	s_waitcnt vmcnt(13)
	v_pk_fma_f32 v[22:23], v[22:23], 0.5, v[198:199] op_sel_hi:[1,0,1]
	v_pk_fma_f32 v[24:25], v[24:25], 0.5, v[200:201] op_sel_hi:[1,0,1]
	global_store_dwordx4 v[220:221], v[22:25], off offset:32
	s_waitcnt vmcnt(12)
	v_pk_fma_f32 v[26:27], v[26:27], 0.5, v[202:203] op_sel_hi:[1,0,1]
	v_pk_fma_f32 v[28:29], v[28:29], 0.5, v[204:205] op_sel_hi:[1,0,1]
	global_store_dwordx4 v[220:221], v[26:29], off offset:64
	s_waitcnt vmcnt(11)
	v_pk_fma_f32 v[30:31], v[30:31], 0.5, v[206:207] op_sel_hi:[1,0,1]
	v_pk_fma_f32 v[32:33], v[32:33], 0.5, v[208:209] op_sel_hi:[1,0,1]
	global_store_dwordx4 v[220:221], v[30:33], off offset:96
	s_waitcnt vmcnt(10)
	v_pk_fma_f32 v[2:3], v[2:3], 0.5, v[216:217] op_sel_hi:[1,0,1]
	v_pk_fma_f32 v[4:5], v[4:5], 0.5, v[218:219] op_sel_hi:[1,0,1]
	global_store_dwordx4 v[220:221], v[2:5], off offset:128
	s_waitcnt vmcnt(9)
	v_pk_fma_f32 v[6:7], v[6:7], 0.5, v[236:237] op_sel_hi:[1,0,1]
	v_pk_fma_f32 v[8:9], v[8:9], 0.5, v[238:239] op_sel_hi:[1,0,1]
	global_store_dwordx4 v[220:221], v[6:9], off offset:160
	s_waitcnt vmcnt(8)
	v_pk_fma_f32 v[10:11], v[10:11], 0.5, v[240:241] op_sel_hi:[1,0,1]
	v_pk_fma_f32 v[12:13], v[12:13], 0.5, v[242:243] op_sel_hi:[1,0,1]
	global_store_dwordx4 v[220:221], v[10:13], off offset:192
	s_waitcnt vmcnt(7)
	v_pk_fma_f32 v[14:15], v[14:15], 0.5, v[244:245] op_sel_hi:[1,0,1]
	v_pk_fma_f32 v[16:17], v[16:17], 0.5, v[246:247] op_sel_hi:[1,0,1]
	global_store_dwordx4 v[220:221], v[14:17], off offset:224
	s_add_i32 s9, s9, 1
	s_mov_b32 s5, 0
	v_mov_b32_e32 v98, 0
	v_mov_b32_e32 v99, 0
	v_mov_b32_e32 v100, 0
	v_mov_b32_e32 v101, 0
	v_mov_b32_e32 v102, 0
	v_mov_b32_e32 v103, 0
	v_mov_b32_e32 v104, 0
	v_mov_b32_e32 v105, 0
	v_mov_b32_e32 v106, 0
	v_mov_b32_e32 v107, 0
	v_mov_b32_e32 v108, 0
	v_mov_b32_e32 v109, 0
	v_mov_b32_e32 v110, 0
	v_mov_b32_e32 v111, 0
	v_mov_b32_e32 v112, 0
	v_mov_b32_e32 v113, 0
	v_mov_b32_e32 v114, 0
	v_mov_b32_e32 v115, 0
	v_mov_b32_e32 v116, 0
	v_mov_b32_e32 v117, 0
	v_mov_b32_e32 v118, 0
	v_mov_b32_e32 v119, 0
	v_mov_b32_e32 v120, 0
	v_mov_b32_e32 v121, 0
	v_mov_b32_e32 v122, 0
	v_mov_b32_e32 v123, 0
	v_mov_b32_e32 v124, 0
	v_mov_b32_e32 v125, 0
	v_mov_b32_e32 v126, 0
	v_mov_b32_e32 v127, 0
	v_mov_b32_e32 v128, 0
	v_mov_b32_e32 v129, 0
	v_mov_b32_e32 v82, 0
	v_mov_b32_e32 v83, 0
	v_mov_b32_e32 v84, 0
	v_mov_b32_e32 v85, 0
	v_mov_b32_e32 v86, 0
	v_mov_b32_e32 v87, 0
	v_mov_b32_e32 v88, 0
	v_mov_b32_e32 v89, 0
	v_mov_b32_e32 v90, 0
	v_mov_b32_e32 v91, 0
	v_mov_b32_e32 v92, 0
	v_mov_b32_e32 v93, 0
	v_mov_b32_e32 v94, 0
	v_mov_b32_e32 v95, 0
	v_mov_b32_e32 v96, 0
	v_mov_b32_e32 v97, 0
	v_mov_b32_e32 v66, 0
	v_mov_b32_e32 v67, 0
	v_mov_b32_e32 v68, 0
	v_mov_b32_e32 v69, 0
	v_mov_b32_e32 v70, 0
	v_mov_b32_e32 v71, 0
	v_mov_b32_e32 v72, 0
	v_mov_b32_e32 v73, 0
	v_mov_b32_e32 v74, 0
	v_mov_b32_e32 v75, 0
	v_mov_b32_e32 v76, 0
	v_mov_b32_e32 v77, 0
	v_mov_b32_e32 v78, 0
	v_mov_b32_e32 v79, 0
	v_mov_b32_e32 v80, 0
	v_mov_b32_e32 v81, 0
	v_mov_b32_e32 v50, 0
	v_mov_b32_e32 v51, 0
	v_mov_b32_e32 v52, 0
	v_mov_b32_e32 v53, 0
	v_mov_b32_e32 v54, 0
	v_mov_b32_e32 v55, 0
	v_mov_b32_e32 v56, 0
	v_mov_b32_e32 v57, 0
	v_mov_b32_e32 v58, 0
	v_mov_b32_e32 v59, 0
	v_mov_b32_e32 v60, 0
	v_mov_b32_e32 v61, 0
	v_mov_b32_e32 v62, 0
	v_mov_b32_e32 v63, 0
	v_mov_b32_e32 v64, 0
	v_mov_b32_e32 v65, 0
	v_mov_b32_e32 v34, 0
	v_mov_b32_e32 v35, 0
	v_mov_b32_e32 v36, 0
	v_mov_b32_e32 v37, 0
	v_mov_b32_e32 v38, 0
	v_mov_b32_e32 v39, 0
	v_mov_b32_e32 v40, 0
	v_mov_b32_e32 v41, 0
	v_mov_b32_e32 v42, 0
	v_mov_b32_e32 v43, 0
	v_mov_b32_e32 v44, 0
	v_mov_b32_e32 v45, 0
	v_mov_b32_e32 v46, 0
	v_mov_b32_e32 v47, 0
	v_mov_b32_e32 v48, 0
	v_mov_b32_e32 v49, 0
	v_mov_b32_e32 v18, 0
	v_mov_b32_e32 v19, 0
	v_mov_b32_e32 v20, 0
	v_mov_b32_e32 v21, 0
	v_mov_b32_e32 v22, 0
	v_mov_b32_e32 v23, 0
	v_mov_b32_e32 v24, 0
	v_mov_b32_e32 v25, 0
	v_mov_b32_e32 v26, 0
	v_mov_b32_e32 v27, 0
	v_mov_b32_e32 v28, 0
	v_mov_b32_e32 v29, 0
	v_mov_b32_e32 v30, 0
	v_mov_b32_e32 v31, 0
	v_mov_b32_e32 v32, 0
	v_mov_b32_e32 v33, 0
	v_mov_b32_e32 v2, 0
	v_mov_b32_e32 v3, 0
	v_mov_b32_e32 v4, 0
	v_mov_b32_e32 v5, 0
	v_mov_b32_e32 v6, 0
	v_mov_b32_e32 v7, 0
	v_mov_b32_e32 v8, 0
	v_mov_b32_e32 v9, 0
	v_mov_b32_e32 v10, 0
	v_mov_b32_e32 v11, 0
	v_mov_b32_e32 v12, 0
	v_mov_b32_e32 v13, 0
	v_mov_b32_e32 v14, 0
	v_mov_b32_e32 v15, 0
	v_mov_b32_e32 v16, 0
	v_mov_b32_e32 v17, 0
	s_cmp_ge_i32 s9, s8
	s_cbranch_scc0 .LBB0_803

.LcL_815:
	s_waitcnt lgkmcnt(0)
	s_barrier
	s_setprio 2
	v_bfe_u32 v221, v222, 5, 1
	v_bfe_u32 v248, v222, 4, 1
	v_lshl_add_u32 v211, v221, 4, v178
	v_lshl_add_u32 v215, v221, 4, v179
	v_mul_u32_u24_e32 v221, 0x8f0, v248
	v_mul_u32_u24_e32 v248, 0x8f8, v248
	v_sub_u32_e32 v213, v211, v248
	v_sub_u32_e32 v220, v215, v248
	v_sub_u32_e32 v211, v211, v221
	v_sub_u32_e32 v215, v215, v221
	ds_read_b128 v[190:193], v215 offset:36864
	ds_read_b128 v[194:197], v211
	ds_read_b128 v[198:201], v215 offset:39168
	ds_read_b128 v[202:205], v215 offset:41472
	ds_read_b128 v[206:209], v215 offset:43776
	ds_read_b128 v[216:219], v211 offset:2304
	ds_read_b128 v[236:239], v211 offset:4608
	ds_read_b128 v[240:243], v211 offset:6912
	ds_read_b128 v[244:247], v211 offset:9216
	s_waitcnt lgkmcnt(7)
	v_mfma_f32_16x16x32_bf16 v[114:117], v[190:193], v[194:197], v[114:117]
	s_ashr_i32 s1, s0, 31
	s_lshl_b64 s[8:9], s[0:1], 7
	s_waitcnt lgkmcnt(6)
	v_mfma_f32_16x16x32_bf16 v[122:125], v[198:201], v[194:197], v[122:125]
	v_lshl_add_u64 v[154:155], v[180:181], 0, s[8:9]
	v_add_co_u32_e32 v130, vcc, 0x10000, v154
	s_waitcnt lgkmcnt(5)
	v_mfma_f32_16x16x32_bf16 v[98:101], v[202:205], v[194:197], v[98:101]
	v_lshl_add_u64 v[170:171], v[182:183], 0, s[8:9]
	s_nop 0
	s_waitcnt lgkmcnt(4)
	v_mfma_f32_16x16x32_bf16 v[106:109], v[206:209], v[194:197], v[106:109]
	ds_read_b128 v[194:197], v211 offset:11520
	v_addc_co_u32_e32 v131, vcc, 0, v155, vcc
	v_add_co_u32_e32 v134, vcc, 0x20000, v154
	s_waitcnt lgkmcnt(4)
	v_mfma_f32_16x16x32_bf16 v[118:121], v[190:193], v[216:219], v[118:121]
	global_load_dwordx4 v[142:145], v[154:155], off
	s_nop 0
	v_mfma_f32_16x16x32_bf16 v[126:129], v[198:201], v[216:219], v[126:129]
	global_load_dwordx4 v[130:133], v[130:131], off
	v_addc_co_u32_e32 v135, vcc, 0, v155, vcc
	v_mfma_f32_16x16x32_bf16 v[102:105], v[202:205], v[216:219], v[102:105]
	v_add_co_u32_e32 v138, vcc, 0x30000, v154
	s_add_i32 s0, s0, 1
	v_mfma_f32_16x16x32_bf16 v[110:113], v[206:209], v[216:219], v[110:113]
	ds_read_b128 v[216:219], v211 offset:13824
	s_nop 0
	v_addc_co_u32_e32 v139, vcc, 0, v155, vcc
	s_waitcnt lgkmcnt(4)
	v_mfma_f32_16x16x32_bf16 v[82:85], v[190:193], v[236:239], v[82:85]
	v_add_co_u32_e32 v146, vcc, 0x40000, v154
	global_load_dwordx4 v[134:137], v[134:135], off
	v_mfma_f32_16x16x32_bf16 v[90:93], v[198:201], v[236:239], v[90:93]
	s_nop 0
	global_load_dwordx4 v[138:141], v[138:139], off
	v_mfma_f32_16x16x32_bf16 v[66:69], v[202:205], v[236:239], v[66:69]
	v_addc_co_u32_e32 v147, vcc, 0, v155, vcc
	v_add_co_u32_e32 v150, vcc, 0x50000, v154
	v_mfma_f32_16x16x32_bf16 v[74:77], v[206:209], v[236:239], v[74:77]
	ds_read_b128 v[236:239], v211 offset:16128
	s_nop 0
	v_addc_co_u32_e32 v151, vcc, 0, v155, vcc
	s_waitcnt lgkmcnt(4)
	v_mfma_f32_16x16x32_bf16 v[86:89], v[190:193], v[240:243], v[86:89]
	v_add_co_u32_e32 v156, vcc, 0x60000, v154
	global_load_dwordx4 v[146:149], v[146:147], off
	v_mfma_f32_16x16x32_bf16 v[94:97], v[198:201], v[240:243], v[94:97]
	s_nop 0
	global_load_dwordx4 v[150:153], v[150:151], off
	v_mfma_f32_16x16x32_bf16 v[70:73], v[202:205], v[240:243], v[70:73]
	v_addc_co_u32_e32 v157, vcc, 0, v155, vcc
	v_add_co_u32_e32 v158, vcc, 0x70000, v154
	v_mfma_f32_16x16x32_bf16 v[78:81], v[206:209], v[240:243], v[78:81]
	ds_read_b128 v[240:243], v215 offset:36928
	s_nop 1
	v_addc_co_u32_e32 v159, vcc, 0, v155, vcc
	s_waitcnt lgkmcnt(4)
	v_mfma_f32_16x16x32_bf16 v[50:53], v[190:193], v[244:247], v[50:53]
	v_add_co_u32_e32 v166, vcc, 0x10000, v170
	global_load_dwordx4 v[154:157], v[156:157], off
	v_mfma_f32_16x16x32_bf16 v[58:61], v[198:201], v[244:247], v[58:61]
	s_nop 0
	global_load_dwordx4 v[158:161], v[158:159], off
	v_mfma_f32_16x16x32_bf16 v[34:37], v[202:205], v[244:247], v[34:37]
	v_addc_co_u32_e32 v167, vcc, 0, v171, vcc
	v_add_co_u32_e32 v172, vcc, 0x20000, v170
	v_mfma_f32_16x16x32_bf16 v[42:45], v[206:209], v[244:247], v[42:45]
	ds_read_b128 v[244:247], v211 offset:64
	global_load_dwordx4 v[162:165], v[170:171], off
	s_nop 0
	s_waitcnt lgkmcnt(4)
	v_mfma_f32_16x16x32_bf16 v[54:57], v[190:193], v[194:197], v[54:57]
	global_load_dwordx4 v[166:169], v[166:167], off
	v_addc_co_u32_e32 v173, vcc, 0, v171, vcc
	v_mfma_f32_16x16x32_bf16 v[62:65], v[198:201], v[194:197], v[62:65]
	v_add_co_u32_e32 v174, vcc, 0x30000, v170
	s_nop 1
	v_mfma_f32_16x16x32_bf16 v[38:41], v[202:205], v[194:197], v[38:41]
	v_addc_co_u32_e32 v175, vcc, 0, v171, vcc
	global_load_dwordx4 v[170:173], v[172:173], off
	v_mfma_f32_16x16x32_bf16 v[46:49], v[206:209], v[194:197], v[46:49]
	ds_read_b128 v[194:197], v211 offset:2368
	s_nop 0
	global_load_dwordx4 v[174:177], v[174:175], off
	s_waitcnt lgkmcnt(4)
	v_mfma_f32_16x16x32_bf16 v[18:21], v[190:193], v[216:219], v[18:21]
	s_cmp_lg_u32 s0, 16
	s_waitcnt lgkmcnt(3)
	v_mfma_f32_16x16x32_bf16 v[22:25], v[190:193], v[236:239], v[22:25]
	ds_read_b128 v[190:193], v215 offset:39232
	v_mfma_f32_16x16x32_bf16 v[26:29], v[198:201], v[216:219], v[26:29]
	v_mfma_f32_16x16x32_bf16 v[30:33], v[198:201], v[236:239], v[30:33]
	ds_read_b128 v[198:201], v215 offset:41536
	v_mfma_f32_16x16x32_bf16 v[2:5], v[202:205], v[216:219], v[2:5]
	v_mfma_f32_16x16x32_bf16 v[6:9], v[202:205], v[236:239], v[6:9]
	ds_read_b128 v[202:205], v215 offset:43840
	v_mfma_f32_16x16x32_bf16 v[10:13], v[206:209], v[216:219], v[10:13]
	ds_read_b128 v[216:219], v211 offset:4672
	v_mfma_f32_16x16x32_bf16 v[14:17], v[206:209], v[236:239], v[14:17]
	ds_read_b128 v[206:209], v211 offset:6976
	ds_read_b128 v[236:239], v211 offset:9280
	s_waitcnt lgkmcnt(7)
	v_mfma_f32_16x16x32_bf16 v[114:117], v[240:243], v[244:247], v[114:117]
	s_waitcnt lgkmcnt(6)
	v_mfma_f32_16x16x32_bf16 v[118:121], v[240:243], v[194:197], v[118:121]
	s_waitcnt lgkmcnt(5)
	v_mfma_f32_16x16x32_bf16 v[122:125], v[190:193], v[244:247], v[122:125]
	v_mfma_f32_16x16x32_bf16 v[126:129], v[190:193], v[194:197], v[126:129]
	s_waitcnt lgkmcnt(4)
	v_mfma_f32_16x16x32_bf16 v[98:101], v[198:201], v[244:247], v[98:101]
	v_mfma_f32_16x16x32_bf16 v[102:105], v[198:201], v[194:197], v[102:105]
	s_waitcnt lgkmcnt(3)
	v_mfma_f32_16x16x32_bf16 v[106:109], v[202:205], v[244:247], v[106:109]
	ds_read_b128 v[244:247], v211 offset:11584
	v_mfma_f32_16x16x32_bf16 v[110:113], v[202:205], v[194:197], v[110:113]
	ds_read_b128 v[194:197], v211 offset:13888
	s_waitcnt lgkmcnt(4)
	v_mfma_f32_16x16x32_bf16 v[82:85], v[240:243], v[216:219], v[82:85]
	v_mfma_f32_16x16x32_bf16 v[90:93], v[190:193], v[216:219], v[90:93]
	v_mfma_f32_16x16x32_bf16 v[66:69], v[198:201], v[216:219], v[66:69]
	v_mfma_f32_16x16x32_bf16 v[74:77], v[202:205], v[216:219], v[74:77]
	ds_read_b128 v[216:219], v211 offset:16192
	s_waitcnt lgkmcnt(4)
	v_mfma_f32_16x16x32_bf16 v[86:89], v[240:243], v[206:209], v[86:89]
	v_mfma_f32_16x16x32_bf16 v[94:97], v[190:193], v[206:209], v[94:97]
	v_mfma_f32_16x16x32_bf16 v[70:73], v[198:201], v[206:209], v[70:73]
	v_mfma_f32_16x16x32_bf16 v[78:81], v[202:205], v[206:209], v[78:81]
	s_waitcnt lgkmcnt(3)
	v_mfma_f32_16x16x32_bf16 v[50:53], v[240:243], v[236:239], v[50:53]
	v_mfma_f32_16x16x32_bf16 v[58:61], v[190:193], v[236:239], v[58:61]
	v_mfma_f32_16x16x32_bf16 v[34:37], v[198:201], v[236:239], v[34:37]
	v_mfma_f32_16x16x32_bf16 v[42:45], v[202:205], v[236:239], v[42:45]
	s_waitcnt lgkmcnt(2)
	v_mfma_f32_16x16x32_bf16 v[54:57], v[240:243], v[244:247], v[54:57]
	v_mfma_f32_16x16x32_bf16 v[62:65], v[190:193], v[244:247], v[62:65]
	v_mfma_f32_16x16x32_bf16 v[38:41], v[198:201], v[244:247], v[38:41]
	v_mfma_f32_16x16x32_bf16 v[46:49], v[202:205], v[244:247], v[46:49]
	s_waitcnt lgkmcnt(1)
	v_mfma_f32_16x16x32_bf16 v[18:21], v[240:243], v[194:197], v[18:21]
	v_mfma_f32_16x16x32_bf16 v[26:29], v[190:193], v[194:197], v[26:29]
	v_mfma_f32_16x16x32_bf16 v[2:5], v[198:201], v[194:197], v[2:5]
	v_mfma_f32_16x16x32_bf16 v[10:13], v[202:205], v[194:197], v[10:13]
	s_waitcnt lgkmcnt(0)
	v_mfma_f32_16x16x32_bf16 v[22:25], v[240:243], v[216:219], v[22:25]
	v_mfma_f32_16x16x32_bf16 v[30:33], v[190:193], v[216:219], v[30:33]
	v_mfma_f32_16x16x32_bf16 v[6:9], v[198:201], v[216:219], v[6:9]
	v_mfma_f32_16x16x32_bf16 v[14:17], v[202:205], v[216:219], v[14:17]
	s_setprio 0
	s_cbranch_scc1 .Ltail_815
	s_add_i32 s2, s2, 1
	s_cmp_ge_i32 s2, s4
	s_cbranch_scc1 .Lz_815
	s_mul_i32 s0, s2, s82
	s_add_i32 s0, s0, s63
	s_mul_hi_i32 s1, s0, 0x2e8ba2e9
	s_lshr_b32 s8, s1, 31
	s_ashr_i32 s1, s1, 4
	s_add_i32 s1, s1, s8
	s_mul_i32 s8, s1, 0x58
	s_sub_i32 s0, s0, s8
	s_lshl_b32 s1, s1, 1
	s_and_b32 s8, s0, 1
	s_or_b32 s1, s8, s1
	v_readlane_b32 s8, v252, 35
	s_ashr_i32 s0, s0, 1
	s_sub_i32 s10, 0x7f, s1
	v_readlane_b32 s9, v252, 36
	s_and_b64 s[8:9], s[8:9], exec
	s_cselect_b32 s8, s10, s1
	s_ashr_i32 s9, s8, 31
	s_ashr_i32 s1, s0, 31
	s_lshl_b64 s[8:9], s[8:9], 19
	s_lshl_b64 s[0:1], s[0:1], 18
	v_lshl_add_u64 v[180:181], v[186:187], 0, s[8:9]
	v_lshl_add_u64 v[182:183], v[188:189], 0, s[0:1]

.LBB0_821:
	s_nop 7
	v_permlane16_swap_b32_e32 v114, v118
	v_permlane16_swap_b32_e32 v115, v119
	v_permlane16_swap_b32_e32 v116, v120
	v_permlane16_swap_b32_e32 v117, v121
	v_permlane16_swap_b32_e32 v122, v126
	v_permlane16_swap_b32_e32 v123, v127
	v_permlane16_swap_b32_e32 v124, v128
	v_permlane16_swap_b32_e32 v125, v129
	v_permlane32_swap_b32_e32 v114, v118
	v_permlane32_swap_b32_e32 v115, v119
	v_permlane32_swap_b32_e32 v116, v120
	v_permlane32_swap_b32_e32 v117, v121
	v_permlane32_swap_b32_e32 v122, v126
	v_permlane32_swap_b32_e32 v123, v127
	v_permlane32_swap_b32_e32 v124, v128
	v_permlane32_swap_b32_e32 v125, v129
	v_permlane16_swap_b32_e32 v98, v102
	v_permlane16_swap_b32_e32 v99, v103
	v_permlane16_swap_b32_e32 v100, v104
	v_permlane16_swap_b32_e32 v101, v105
	v_permlane16_swap_b32_e32 v106, v110
	v_permlane16_swap_b32_e32 v107, v111
	v_permlane16_swap_b32_e32 v108, v112
	v_permlane16_swap_b32_e32 v109, v113
	v_permlane32_swap_b32_e32 v98, v102
	v_permlane32_swap_b32_e32 v99, v103
	v_permlane32_swap_b32_e32 v100, v104
	v_permlane32_swap_b32_e32 v101, v105
	v_permlane32_swap_b32_e32 v106, v110
	v_permlane32_swap_b32_e32 v107, v111
	v_permlane32_swap_b32_e32 v108, v112
	v_permlane32_swap_b32_e32 v109, v113
	v_permlane16_swap_b32_e32 v82, v86
	v_permlane16_swap_b32_e32 v83, v87
	v_permlane16_swap_b32_e32 v84, v88
	v_permlane16_swap_b32_e32 v85, v89
	v_permlane16_swap_b32_e32 v90, v94
	v_permlane16_swap_b32_e32 v91, v95
	v_permlane16_swap_b32_e32 v92, v96
	v_permlane16_swap_b32_e32 v93, v97
	v_permlane32_swap_b32_e32 v82, v86
	v_permlane32_swap_b32_e32 v83, v87
	v_permlane32_swap_b32_e32 v84, v88
	v_permlane32_swap_b32_e32 v85, v89
	v_permlane32_swap_b32_e32 v90, v94
	v_permlane32_swap_b32_e32 v91, v95
	v_permlane32_swap_b32_e32 v92, v96
	v_permlane32_swap_b32_e32 v93, v97
	v_permlane16_swap_b32_e32 v66, v70
	v_permlane16_swap_b32_e32 v67, v71
	v_permlane16_swap_b32_e32 v68, v72
	v_permlane16_swap_b32_e32 v69, v73
	v_permlane16_swap_b32_e32 v74, v78
	v_permlane16_swap_b32_e32 v75, v79
	v_permlane16_swap_b32_e32 v76, v80
	v_permlane16_swap_b32_e32 v77, v81
	v_permlane32_swap_b32_e32 v66, v70
	v_permlane32_swap_b32_e32 v67, v71
	v_permlane32_swap_b32_e32 v68, v72
	v_permlane32_swap_b32_e32 v69, v73
	v_permlane32_swap_b32_e32 v74, v78
	v_permlane32_swap_b32_e32 v75, v79
	v_permlane32_swap_b32_e32 v76, v80
	v_permlane32_swap_b32_e32 v77, v81
	v_permlane16_swap_b32_e32 v50, v54
	v_permlane16_swap_b32_e32 v51, v55
	v_permlane16_swap_b32_e32 v52, v56
	v_permlane16_swap_b32_e32 v53, v57
	v_permlane16_swap_b32_e32 v58, v62
	v_permlane16_swap_b32_e32 v59, v63
	v_permlane16_swap_b32_e32 v60, v64
	v_permlane16_swap_b32_e32 v61, v65
	v_permlane32_swap_b32_e32 v50, v54
	v_permlane32_swap_b32_e32 v51, v55
	v_permlane32_swap_b32_e32 v52, v56
	v_permlane32_swap_b32_e32 v53, v57
	v_permlane32_swap_b32_e32 v58, v62
	v_permlane32_swap_b32_e32 v59, v63
	v_permlane32_swap_b32_e32 v60, v64
	v_permlane32_swap_b32_e32 v61, v65
	v_permlane16_swap_b32_e32 v34, v38
	v_permlane16_swap_b32_e32 v35, v39
	v_permlane16_swap_b32_e32 v36, v40
	v_permlane16_swap_b32_e32 v37, v41
	v_permlane16_swap_b32_e32 v42, v46
	v_permlane16_swap_b32_e32 v43, v47
	v_permlane16_swap_b32_e32 v44, v48
	v_permlane16_swap_b32_e32 v45, v49
	v_permlane32_swap_b32_e32 v34, v38
	v_permlane32_swap_b32_e32 v35, v39
	v_permlane32_swap_b32_e32 v36, v40
	v_permlane32_swap_b32_e32 v37, v41
	v_permlane32_swap_b32_e32 v42, v46
	v_permlane32_swap_b32_e32 v43, v47
	v_permlane32_swap_b32_e32 v44, v48
	v_permlane32_swap_b32_e32 v45, v49
	v_permlane16_swap_b32_e32 v18, v22
	v_permlane16_swap_b32_e32 v19, v23
	v_permlane16_swap_b32_e32 v20, v24
	v_permlane16_swap_b32_e32 v21, v25
	v_permlane16_swap_b32_e32 v26, v30
	v_permlane16_swap_b32_e32 v27, v31
	v_permlane16_swap_b32_e32 v28, v32
	v_permlane16_swap_b32_e32 v29, v33
	v_permlane32_swap_b32_e32 v18, v22
	v_permlane32_swap_b32_e32 v19, v23
	v_permlane32_swap_b32_e32 v20, v24
	v_permlane32_swap_b32_e32 v21, v25
	v_permlane32_swap_b32_e32 v26, v30
	v_permlane32_swap_b32_e32 v27, v31
	v_permlane32_swap_b32_e32 v28, v32
	v_permlane32_swap_b32_e32 v29, v33
	v_permlane16_swap_b32_e32 v2, v6
	v_permlane16_swap_b32_e32 v3, v7
	v_permlane16_swap_b32_e32 v4, v8
	v_permlane16_swap_b32_e32 v5, v9
	v_permlane16_swap_b32_e32 v10, v14
	v_permlane16_swap_b32_e32 v11, v15
	v_permlane16_swap_b32_e32 v12, v16
	v_permlane16_swap_b32_e32 v13, v17
	v_permlane32_swap_b32_e32 v2, v6
	v_permlane32_swap_b32_e32 v3, v7
	v_permlane32_swap_b32_e32 v4, v8
	v_permlane32_swap_b32_e32 v5, v9
	v_permlane32_swap_b32_e32 v10, v14
	v_permlane32_swap_b32_e32 v11, v15
	v_permlane32_swap_b32_e32 v12, v16
	v_permlane32_swap_b32_e32 v13, v17
	s_mul_i32 s1, s5, s82
	s_add_i32 s1, s1, s63
	s_mul_hi_i32 s3, s1, 0x2e8ba2e9
	s_lshr_b32 s8, s3, 31
	s_ashr_i32 s3, s3, 4
	s_add_i32 s3, s3, s8
	s_mul_i32 s8, s3, 0x58
	s_sub_i32 s1, s1, s8
	s_lshl_b32 s3, s3, 1
	s_and_b32 s8, s1, 1
	s_or_b32 s3, s8, s3
	v_readlane_b32 s8, v252, 35
	s_sub_i32 s10, 0x7f, s3
	v_readlane_b32 s9, v252, 36
	s_and_b64 s[8:9], s[8:9], exec
	s_cselect_b32 s8, s10, s3
	v_mov_b32_e32 v0, v222
	s_ashr_i32 s9, s8, 31
	v_and_b32_e32 v192, 0xffffff80, v0
	s_lshl_b64 s[8:9], s[8:9], 8
	v_ashrrev_i32_e32 v193, 31, v192
	s_lshl_b32 s1, s1, 6
	v_lshl_add_u64 v[192:193], s[8:9], 0, v[192:193]
	v_readlane_b32 s8, v252, 45
	s_and_b32 s1, s1, 0xffffff80
	v_readlane_b32 s9, v252, 46
	v_and_or_b32 v185, v0, 64, s1
	v_lshrrev_b32_e32 v190, 3, v0
	v_and_or_b32 v0, v0, 31, v192
	v_mov_b64_e32 v[194:195], s[8:9]
	s_movk_i32 s1, 0x1600
	v_mad_u64_u32 v[194:195], s[8:9], v0, s1, v[194:195]
	v_mul_f32_e32 v0, 0xbfb8aa3b, v114
	v_exp_f32_e32 v0, v0
	v_mad_i32_i24 v195, v193, s1, v195
	v_ashrrev_i32_e32 v185, 1, v185
	v_and_or_b32 v190, v190, 4, v185
	v_add_f32_e32 v0, 1.0, v0
	v_rcp_f32_e32 v192, v0
	v_mul_f32_e32 v0, 0xbfb8aa3b, v115
	v_exp_f32_e32 v0, v0
	v_ashrrev_i32_e32 v191, 31, v190
	v_lshl_add_u64 v[190:191], v[190:191], 1, v[194:195]
	s_mov_b32 s1, 0x2c000
	v_add_f32_e32 v0, 1.0, v0
	v_rcp_f32_e32 v193, v0
	v_mul_f32_e32 v0, 0xbfb8aa3b, v116
	v_exp_f32_e32 v0, v0
	s_mov_b64 s[8:9], 0x2c000
	v_pk_mul_f32 v[114:115], v[114:115], v[192:193]
	s_mov_b32 s3, 0
	v_add_f32_e32 v0, 1.0, v0
	v_pk_mul_f32 v[98:99], v[98:99], v[114:115]
	v_rcp_f32_e32 v114, v0
	v_mul_f32_e32 v0, 0xbfb8aa3b, v117
	v_exp_f32_e32 v0, v0
	v_cvt_pk_bf16_f32 v98, v98, v99
	s_add_i32 s5, s5, 1
	v_add_f32_e32 v0, 1.0, v0
	v_rcp_f32_e32 v115, v0
	v_mul_f32_e32 v0, 0xbfb8aa3b, v118
	v_exp_f32_e32 v0, v0
	v_pk_mul_f32 v[114:115], v[116:117], v[114:115]
	s_nop 0
	v_pk_mul_f32 v[100:101], v[100:101], v[114:115]
	v_add_f32_e32 v0, 1.0, v0
	v_cvt_pk_bf16_f32 v99, v100, v101
	global_store_dwordx2 v[190:191], v[98:99], off
	v_rcp_f32_e32 v98, v0
	v_mul_f32_e32 v0, 0xbfb8aa3b, v119
	v_exp_f32_e32 v0, v0
	v_mov_b32_e32 v114, 0
	v_mov_b32_e32 v115, v114
	v_mov_b32_e32 v116, v114
	v_add_f32_e32 v0, 1.0, v0
	v_rcp_f32_e32 v99, v0
	v_mul_f32_e32 v0, 0xbfb8aa3b, v120
	v_exp_f32_e32 v0, v0
	v_mov_b32_e32 v117, v114
	v_pk_mul_f32 v[98:99], v[118:119], v[98:99]
	v_mov_b32_e32 v118, v114
	v_add_f32_e32 v0, 1.0, v0
	v_rcp_f32_e32 v100, v0
	v_mul_f32_e32 v0, 0xbfb8aa3b, v121
	v_exp_f32_e32 v0, v0
	v_pk_mul_f32 v[98:99], v[102:103], v[98:99]
	v_mov_b32_e32 v119, v114
	v_cvt_pk_bf16_f32 v98, v98, v99
	v_add_f32_e32 v0, 1.0, v0
	v_rcp_f32_e32 v101, v0
	v_mul_f32_e32 v0, 0xbfb8aa3b, v122
	v_exp_f32_e32 v0, v0
	v_mov_b32_e32 v102, v114
	v_pk_mul_f32 v[100:101], v[120:121], v[100:101]
	v_mov_b32_e32 v120, v114
	v_pk_mul_f32 v[100:101], v[104:105], v[100:101]
	v_add_f32_e32 v0, 1.0, v0
	v_cvt_pk_bf16_f32 v99, v100, v101
	global_store_dwordx2 v[190:191], v[98:99], off offset:16
	v_rcp_f32_e32 v98, v0
	v_mul_f32_e32 v0, 0xbfb8aa3b, v123
	v_exp_f32_e32 v0, v0
	v_mov_b32_e32 v121, v114
	v_mov_b32_e32 v103, v114
	v_mov_b32_e32 v104, v114
	v_add_f32_e32 v0, 1.0, v0
	v_rcp_f32_e32 v99, v0
	v_mul_f32_e32 v0, 0xbfb8aa3b, v124
	v_exp_f32_e32 v0, v0
	v_mov_b32_e32 v105, v114
	v_pk_mul_f32 v[98:99], v[122:123], v[98:99]
	v_mov_b32_e32 v122, v114
	v_add_f32_e32 v0, 1.0, v0
	v_rcp_f32_e32 v100, v0
	v_mul_f32_e32 v0, 0xbfb8aa3b, v125
	v_exp_f32_e32 v0, v0
	v_pk_mul_f32 v[98:99], v[106:107], v[98:99]
	v_mov_b32_e32 v123, v114
	v_cvt_pk_bf16_f32 v98, v98, v99
	v_add_f32_e32 v0, 1.0, v0
	v_rcp_f32_e32 v101, v0
	v_mul_f32_e32 v0, 0xbfb8aa3b, v126
	v_exp_f32_e32 v0, v0
	v_mov_b32_e32 v106, v114
	v_pk_mul_f32 v[100:101], v[124:125], v[100:101]
	v_mov_b32_e32 v124, v114
	v_pk_mul_f32 v[100:101], v[108:109], v[100:101]
	v_add_f32_e32 v0, 1.0, v0
	v_cvt_pk_bf16_f32 v99, v100, v101
	global_store_dwordx2 v[190:191], v[98:99], off offset:32
	v_rcp_f32_e32 v98, v0
	v_mul_f32_e32 v0, 0xbfb8aa3b, v127
	v_exp_f32_e32 v0, v0
	v_mov_b32_e32 v125, v114
	v_mov_b32_e32 v107, v114
	v_mov_b32_e32 v108, v114
	v_add_f32_e32 v0, 1.0, v0
	v_rcp_f32_e32 v99, v0
	v_mul_f32_e32 v0, 0xbfb8aa3b, v128
	v_exp_f32_e32 v0, v0
	v_mov_b32_e32 v109, v114
	v_pk_mul_f32 v[98:99], v[126:127], v[98:99]
	v_mov_b32_e32 v126, v114
	v_add_f32_e32 v0, 1.0, v0
	v_rcp_f32_e32 v100, v0
	v_mul_f32_e32 v0, 0xbfb8aa3b, v129
	v_exp_f32_e32 v0, v0
	v_pk_mul_f32 v[98:99], v[110:111], v[98:99]
	v_mov_b32_e32 v127, v114
	v_cvt_pk_bf16_f32 v98, v98, v99
	v_add_f32_e32 v0, 1.0, v0
	v_rcp_f32_e32 v101, v0
	v_mul_f32_e32 v0, 0xbfb8aa3b, v82
	v_exp_f32_e32 v0, v0
	v_mov_b32_e32 v110, v114
	v_pk_mul_f32 v[100:101], v[128:129], v[100:101]
	v_mov_b32_e32 v128, v114
	v_pk_mul_f32 v[100:101], v[112:113], v[100:101]
	v_add_f32_e32 v0, 1.0, v0
	v_cvt_pk_bf16_f32 v99, v100, v101
	v_rcp_f32_e32 v100, v0
	v_mul_f32_e32 v0, 0xbfb8aa3b, v83
	v_exp_f32_e32 v0, v0
	global_store_dwordx2 v[190:191], v[98:99], off offset:48
	v_lshl_add_u64 v[98:99], v[190:191], 0, s[8:9]
	s_mov_b64 s[8:9], 0x58000
	v_add_f32_e32 v0, 1.0, v0
	v_rcp_f32_e32 v101, v0
	v_mul_f32_e32 v0, 0xbfb8aa3b, v84
	v_exp_f32_e32 v0, v0
	v_mov_b32_e32 v129, v114
	v_pk_mul_f32 v[82:83], v[82:83], v[100:101]
	v_mov_b32_e32 v100, v114
	v_add_f32_e32 v0, 1.0, v0
	v_pk_mul_f32 v[66:67], v[66:67], v[82:83]
	v_rcp_f32_e32 v82, v0
	v_mul_f32_e32 v0, 0xbfb8aa3b, v85
	v_exp_f32_e32 v0, v0
	v_cvt_pk_bf16_f32 v66, v66, v67
	v_mov_b32_e32 v101, v114
	v_mov_b32_e32 v111, v114
	v_add_f32_e32 v0, 1.0, v0
	v_rcp_f32_e32 v83, v0
	v_mul_f32_e32 v0, 0xbfb8aa3b, v86
	v_exp_f32_e32 v0, v0
	v_mov_b32_e32 v112, v114
	v_pk_mul_f32 v[82:83], v[84:85], v[82:83]
	v_mov_b32_e32 v113, v114
	v_pk_mul_f32 v[68:69], v[68:69], v[82:83]
	v_add_f32_e32 v0, 1.0, v0
	v_cvt_pk_bf16_f32 v67, v68, v69
	v_add_co_u32_e32 v68, vcc, s1, v190
	s_mov_b32 s1, 0x58000
	s_nop 0
	v_addc_co_u32_e32 v69, vcc, 0, v191, vcc
	global_store_dwordx2 v[68:69], v[66:67], off
	v_rcp_f32_e32 v66, v0
	v_mul_f32_e32 v0, 0xbfb8aa3b, v87
	v_exp_f32_e32 v0, v0
	v_mov_b32_e32 v82, v114
	v_mov_b32_e32 v83, v114
	v_mov_b32_e32 v84, v114
	v_add_f32_e32 v0, 1.0, v0
	v_rcp_f32_e32 v67, v0
	v_mul_f32_e32 v0, 0xbfb8aa3b, v88
	v_exp_f32_e32 v0, v0
	v_mov_b32_e32 v85, v114
	v_pk_mul_f32 v[66:67], v[86:87], v[66:67]
	v_mov_b32_e32 v86, v114
	v_add_f32_e32 v0, 1.0, v0
	v_rcp_f32_e32 v68, v0
	v_mul_f32_e32 v0, 0xbfb8aa3b, v89
	v_exp_f32_e32 v0, v0
	v_pk_mul_f32 v[66:67], v[70:71], v[66:67]
	v_mov_b32_e32 v87, v114
	v_cvt_pk_bf16_f32 v66, v66, v67
	v_add_f32_e32 v0, 1.0, v0
	v_rcp_f32_e32 v69, v0
	v_mul_f32_e32 v0, 0xbfb8aa3b, v90
	v_exp_f32_e32 v0, v0
	v_mov_b32_e32 v70, v114
	v_pk_mul_f32 v[68:69], v[88:89], v[68:69]
	v_mov_b32_e32 v88, v114
	v_pk_mul_f32 v[68:69], v[72:73], v[68:69]
	v_add_f32_e32 v0, 1.0, v0
	v_cvt_pk_bf16_f32 v67, v68, v69
	global_store_dwordx2 v[98:99], v[66:67], off offset:16
	v_rcp_f32_e32 v66, v0
	v_mul_f32_e32 v0, 0xbfb8aa3b, v91
	v_exp_f32_e32 v0, v0
	v_mov_b32_e32 v89, v114
	v_mov_b32_e32 v71, v114
	v_mov_b32_e32 v72, v114
	v_add_f32_e32 v0, 1.0, v0
	v_rcp_f32_e32 v67, v0
	v_mul_f32_e32 v0, 0xbfb8aa3b, v92
	v_exp_f32_e32 v0, v0
	v_mov_b32_e32 v73, v114
	v_pk_mul_f32 v[66:67], v[90:91], v[66:67]
	v_mov_b32_e32 v90, v114
	v_add_f32_e32 v0, 1.0, v0
	v_rcp_f32_e32 v68, v0
	v_mul_f32_e32 v0, 0xbfb8aa3b, v93
	v_exp_f32_e32 v0, v0
	v_pk_mul_f32 v[66:67], v[74:75], v[66:67]
	v_mov_b32_e32 v91, v114
	v_cvt_pk_bf16_f32 v66, v66, v67
	v_add_f32_e32 v0, 1.0, v0
	v_rcp_f32_e32 v69, v0
	v_mul_f32_e32 v0, 0xbfb8aa3b, v94
	v_exp_f32_e32 v0, v0
	v_mov_b32_e32 v74, v114
	v_pk_mul_f32 v[68:69], v[92:93], v[68:69]
	v_mov_b32_e32 v92, v114
	v_pk_mul_f32 v[68:69], v[76:77], v[68:69]
	v_add_f32_e32 v0, 1.0, v0
	v_cvt_pk_bf16_f32 v67, v68, v69
	global_store_dwordx2 v[98:99], v[66:67], off offset:32
	v_rcp_f32_e32 v66, v0
	v_mul_f32_e32 v0, 0xbfb8aa3b, v95
	v_exp_f32_e32 v0, v0
	v_mov_b32_e32 v93, v114
	v_mov_b32_e32 v75, v114
	v_mov_b32_e32 v76, v114
	v_add_f32_e32 v0, 1.0, v0
	v_rcp_f32_e32 v67, v0
	v_mul_f32_e32 v0, 0xbfb8aa3b, v96
	v_exp_f32_e32 v0, v0
	v_mov_b32_e32 v77, v114
	v_pk_mul_f32 v[66:67], v[94:95], v[66:67]
	v_mov_b32_e32 v94, v114
	v_add_f32_e32 v0, 1.0, v0
	v_rcp_f32_e32 v68, v0
	v_mul_f32_e32 v0, 0xbfb8aa3b, v97
	v_exp_f32_e32 v0, v0
	v_pk_mul_f32 v[66:67], v[78:79], v[66:67]
	v_mov_b32_e32 v95, v114
	v_cvt_pk_bf16_f32 v66, v66, v67
	v_add_f32_e32 v0, 1.0, v0
	v_rcp_f32_e32 v69, v0
	v_mul_f32_e32 v0, 0xbfb8aa3b, v50
	v_exp_f32_e32 v0, v0
	v_mov_b32_e32 v78, v114
	v_pk_mul_f32 v[68:69], v[96:97], v[68:69]
	v_mov_b32_e32 v96, v114
	v_pk_mul_f32 v[68:69], v[80:81], v[68:69]
	v_add_f32_e32 v0, 1.0, v0
	v_cvt_pk_bf16_f32 v67, v68, v69
	v_rcp_f32_e32 v68, v0
	v_mul_f32_e32 v0, 0xbfb8aa3b, v51
	v_exp_f32_e32 v0, v0
	global_store_dwordx2 v[98:99], v[66:67], off offset:48
	v_lshl_add_u64 v[66:67], v[190:191], 0, s[8:9]
	s_mov_b64 s[8:9], 0x84000
	v_add_f32_e32 v0, 1.0, v0
	v_rcp_f32_e32 v69, v0
	v_mul_f32_e32 v0, 0xbfb8aa3b, v52
	v_exp_f32_e32 v0, v0
	v_mov_b32_e32 v98, v114
	v_pk_mul_f32 v[50:51], v[50:51], v[68:69]
	v_mov_b32_e32 v99, v114
	v_add_f32_e32 v0, 1.0, v0
	v_pk_mul_f32 v[34:35], v[34:35], v[50:51]
	v_rcp_f32_e32 v50, v0
	v_mul_f32_e32 v0, 0xbfb8aa3b, v53
	v_exp_f32_e32 v0, v0
	v_cvt_pk_bf16_f32 v34, v34, v35
	v_mov_b32_e32 v97, v114
	v_mov_b32_e32 v68, v114
	v_add_f32_e32 v0, 1.0, v0
	v_rcp_f32_e32 v51, v0
	v_mul_f32_e32 v0, 0xbfb8aa3b, v54
	v_exp_f32_e32 v0, v0
	v_mov_b32_e32 v69, v114
	v_pk_mul_f32 v[50:51], v[52:53], v[50:51]
	v_mov_b32_e32 v79, v114
	v_pk_mul_f32 v[36:37], v[36:37], v[50:51]
	v_add_f32_e32 v0, 1.0, v0
	v_cvt_pk_bf16_f32 v35, v36, v37
	v_add_co_u32_e32 v36, vcc, s1, v190
	s_mov_b32 s1, 0x84000
	s_nop 0
	v_addc_co_u32_e32 v37, vcc, 0, v191, vcc
	global_store_dwordx2 v[36:37], v[34:35], off
	v_rcp_f32_e32 v34, v0
	v_mul_f32_e32 v0, 0xbfb8aa3b, v55
	v_exp_f32_e32 v0, v0
	v_mov_b32_e32 v80, v114
	v_mov_b32_e32 v81, v114
	v_mov_b32_e32 v50, v114
	v_add_f32_e32 v0, 1.0, v0
	v_rcp_f32_e32 v35, v0
	v_mul_f32_e32 v0, 0xbfb8aa3b, v56
	v_exp_f32_e32 v0, v0
	v_mov_b32_e32 v51, v114
	v_pk_mul_f32 v[34:35], v[54:55], v[34:35]
	v_mov_b32_e32 v52, v114
	v_add_f32_e32 v0, 1.0, v0
	v_rcp_f32_e32 v36, v0
	v_mul_f32_e32 v0, 0xbfb8aa3b, v57
	v_exp_f32_e32 v0, v0
	v_pk_mul_f32 v[34:35], v[38:39], v[34:35]
	v_mov_b32_e32 v53, v114
	v_cvt_pk_bf16_f32 v34, v34, v35
	v_add_f32_e32 v0, 1.0, v0
	v_rcp_f32_e32 v37, v0
	v_mul_f32_e32 v0, 0xbfb8aa3b, v58
	v_exp_f32_e32 v0, v0
	v_mov_b32_e32 v54, v114
	v_pk_mul_f32 v[36:37], v[56:57], v[36:37]
	v_mov_b32_e32 v55, v114
	v_pk_mul_f32 v[36:37], v[40:41], v[36:37]
	v_add_f32_e32 v0, 1.0, v0
	v_cvt_pk_bf16_f32 v35, v36, v37
	global_store_dwordx2 v[66:67], v[34:35], off offset:16
	v_rcp_f32_e32 v34, v0
	v_mul_f32_e32 v0, 0xbfb8aa3b, v59
	v_exp_f32_e32 v0, v0
	v_mov_b32_e32 v56, v114
	v_mov_b32_e32 v57, v114
	v_mov_b32_e32 v38, v114
	v_add_f32_e32 v0, 1.0, v0
	v_rcp_f32_e32 v35, v0
	v_mul_f32_e32 v0, 0xbfb8aa3b, v60
	v_exp_f32_e32 v0, v0
	v_mov_b32_e32 v39, v114
	v_pk_mul_f32 v[34:35], v[58:59], v[34:35]
	v_mov_b32_e32 v58, v114
	v_add_f32_e32 v0, 1.0, v0
	v_rcp_f32_e32 v36, v0
	v_mul_f32_e32 v0, 0xbfb8aa3b, v61
	v_exp_f32_e32 v0, v0
	v_pk_mul_f32 v[34:35], v[42:43], v[34:35]
	v_mov_b32_e32 v59, v114
	v_cvt_pk_bf16_f32 v34, v34, v35
	v_add_f32_e32 v0, 1.0, v0
	v_rcp_f32_e32 v37, v0
	v_mul_f32_e32 v0, 0xbfb8aa3b, v62
	v_exp_f32_e32 v0, v0
	v_mov_b32_e32 v40, v114
	v_pk_mul_f32 v[36:37], v[60:61], v[36:37]
	v_mov_b32_e32 v60, v114
	v_pk_mul_f32 v[36:37], v[44:45], v[36:37]
	v_add_f32_e32 v0, 1.0, v0
	v_cvt_pk_bf16_f32 v35, v36, v37
	global_store_dwordx2 v[66:67], v[34:35], off offset:32
	v_rcp_f32_e32 v34, v0
	v_mul_f32_e32 v0, 0xbfb8aa3b, v63
	v_exp_f32_e32 v0, v0
	v_mov_b32_e32 v61, v114
	v_mov_b32_e32 v41, v114
	v_mov_b32_e32 v42, v114
	v_add_f32_e32 v0, 1.0, v0
	v_rcp_f32_e32 v35, v0
	v_mul_f32_e32 v0, 0xbfb8aa3b, v64
	v_exp_f32_e32 v0, v0
	v_mov_b32_e32 v43, v114
	v_pk_mul_f32 v[34:35], v[62:63], v[34:35]
	v_mov_b32_e32 v62, v114
	v_add_f32_e32 v0, 1.0, v0
	v_rcp_f32_e32 v36, v0
	v_mul_f32_e32 v0, 0xbfb8aa3b, v65
	v_exp_f32_e32 v0, v0
	v_pk_mul_f32 v[34:35], v[46:47], v[34:35]
	v_mov_b32_e32 v63, v114
	v_cvt_pk_bf16_f32 v34, v34, v35
	v_add_f32_e32 v0, 1.0, v0
	v_rcp_f32_e32 v37, v0
	v_mul_f32_e32 v0, 0xbfb8aa3b, v18
	v_exp_f32_e32 v0, v0
	v_mov_b32_e32 v44, v114
	v_pk_mul_f32 v[36:37], v[64:65], v[36:37]
	v_mov_b32_e32 v64, v114
	v_pk_mul_f32 v[36:37], v[48:49], v[36:37]
	v_add_f32_e32 v0, 1.0, v0
	v_cvt_pk_bf16_f32 v35, v36, v37
	v_rcp_f32_e32 v36, v0
	v_mul_f32_e32 v0, 0xbfb8aa3b, v19
	v_exp_f32_e32 v0, v0
	global_store_dwordx2 v[66:67], v[34:35], off offset:48
	v_lshl_add_u64 v[34:35], v[190:191], 0, s[8:9]
	v_mov_b32_e32 v66, v114
	v_add_f32_e32 v0, 1.0, v0
	v_rcp_f32_e32 v37, v0
	v_mul_f32_e32 v0, 0xbfb8aa3b, v20
	v_exp_f32_e32 v0, v0
	v_mov_b32_e32 v67, v114
	v_pk_mul_f32 v[18:19], v[18:19], v[36:37]
	v_mov_b32_e32 v65, v114
	v_add_f32_e32 v0, 1.0, v0
	v_pk_mul_f32 v[2:3], v[2:3], v[18:19]
	v_rcp_f32_e32 v18, v0
	v_mul_f32_e32 v0, 0xbfb8aa3b, v21
	v_exp_f32_e32 v0, v0
	v_cvt_pk_bf16_f32 v2, v2, v3
	v_mov_b32_e32 v36, v114
	v_mov_b32_e32 v37, v114
	v_add_f32_e32 v0, 1.0, v0
	v_rcp_f32_e32 v19, v0
	v_mul_f32_e32 v0, 0xbfb8aa3b, v22
	v_exp_f32_e32 v0, v0
	v_mov_b32_e32 v45, v114
	v_pk_mul_f32 v[18:19], v[20:21], v[18:19]
	v_mov_b32_e32 v46, v114
	v_pk_mul_f32 v[4:5], v[4:5], v[18:19]
	v_add_f32_e32 v0, 1.0, v0
	v_cvt_pk_bf16_f32 v3, v4, v5
	v_add_co_u32_e32 v4, vcc, s1, v190
	v_mov_b32_e32 v47, v114
	s_nop 0
	v_addc_co_u32_e32 v5, vcc, 0, v191, vcc
	global_store_dwordx2 v[4:5], v[2:3], off
	v_rcp_f32_e32 v2, v0
	v_mul_f32_e32 v0, 0xbfb8aa3b, v23
	v_exp_f32_e32 v0, v0
	v_mov_b32_e32 v48, v114
	v_mov_b32_e32 v49, v114
	v_mov_b32_e32 v18, v114
	v_add_f32_e32 v0, 1.0, v0
	v_rcp_f32_e32 v3, v0
	v_mul_f32_e32 v0, 0xbfb8aa3b, v24
	v_exp_f32_e32 v0, v0
	v_mov_b32_e32 v19, v114
	v_pk_mul_f32 v[2:3], v[22:23], v[2:3]
	v_mov_b32_e32 v20, v114
	v_add_f32_e32 v0, 1.0, v0
	v_rcp_f32_e32 v4, v0
	v_mul_f32_e32 v0, 0xbfb8aa3b, v25
	v_exp_f32_e32 v0, v0
	v_pk_mul_f32 v[2:3], v[6:7], v[2:3]
	v_mov_b32_e32 v21, v114
	v_cvt_pk_bf16_f32 v2, v2, v3
	v_add_f32_e32 v0, 1.0, v0
	v_rcp_f32_e32 v5, v0
	v_mul_f32_e32 v0, 0xbfb8aa3b, v26
	v_exp_f32_e32 v0, v0
	v_mov_b32_e32 v22, v114
	v_pk_mul_f32 v[4:5], v[24:25], v[4:5]
	v_mov_b32_e32 v23, v114
	v_pk_mul_f32 v[4:5], v[8:9], v[4:5]
	v_add_f32_e32 v0, 1.0, v0
	v_cvt_pk_bf16_f32 v3, v4, v5
	global_store_dwordx2 v[34:35], v[2:3], off offset:16
	v_rcp_f32_e32 v2, v0
	v_mul_f32_e32 v0, 0xbfb8aa3b, v27
	v_exp_f32_e32 v0, v0
	v_mov_b32_e32 v24, v114
	v_mov_b32_e32 v25, v114
	v_mov_b32_e32 v6, v114
	v_add_f32_e32 v0, 1.0, v0
	v_rcp_f32_e32 v3, v0
	v_mul_f32_e32 v0, 0xbfb8aa3b, v28
	v_exp_f32_e32 v0, v0
	v_mov_b32_e32 v7, v114
	v_pk_mul_f32 v[2:3], v[26:27], v[2:3]
	v_mov_b32_e32 v26, v114
	v_add_f32_e32 v0, 1.0, v0
	v_rcp_f32_e32 v4, v0
	v_mul_f32_e32 v0, 0xbfb8aa3b, v29
	v_exp_f32_e32 v0, v0
	v_pk_mul_f32 v[2:3], v[10:11], v[2:3]
	v_mov_b32_e32 v27, v114
	v_cvt_pk_bf16_f32 v2, v2, v3
	v_add_f32_e32 v0, 1.0, v0
	v_rcp_f32_e32 v5, v0
	v_mul_f32_e32 v0, 0xbfb8aa3b, v30
	v_exp_f32_e32 v0, v0
	v_mov_b32_e32 v8, v114
	v_pk_mul_f32 v[4:5], v[28:29], v[4:5]
	v_mov_b32_e32 v28, v114
	v_pk_mul_f32 v[4:5], v[12:13], v[4:5]
	v_add_f32_e32 v0, 1.0, v0
	v_cvt_pk_bf16_f32 v3, v4, v5
	global_store_dwordx2 v[34:35], v[2:3], off offset:32
	v_rcp_f32_e32 v2, v0
	v_mul_f32_e32 v0, 0xbfb8aa3b, v31
	v_exp_f32_e32 v0, v0
	v_mov_b32_e32 v29, v114
	v_mov_b32_e32 v9, v114
	v_mov_b32_e32 v10, v114
	v_add_f32_e32 v0, 1.0, v0
	v_rcp_f32_e32 v3, v0
	v_mul_f32_e32 v0, 0xbfb8aa3b, v32
	v_exp_f32_e32 v0, v0
	v_mov_b32_e32 v11, v114
	v_pk_mul_f32 v[2:3], v[30:31], v[2:3]
	v_mov_b32_e32 v30, v114
	v_add_f32_e32 v0, 1.0, v0
	v_rcp_f32_e32 v4, v0
	v_mul_f32_e32 v0, 0xbfb8aa3b, v33
	v_exp_f32_e32 v0, v0
	v_pk_mul_f32 v[2:3], v[14:15], v[2:3]
	v_mov_b32_e32 v31, v114
	v_cvt_pk_bf16_f32 v2, v2, v3
	v_add_f32_e32 v0, 1.0, v0
	v_rcp_f32_e32 v5, v0
	v_mov_b32_e32 v12, v114
	v_mov_b32_e32 v13, v114
	v_mov_b32_e32 v14, v114
	v_pk_mul_f32 v[4:5], v[32:33], v[4:5]
	v_mov_b32_e32 v32, v114
	v_pk_mul_f32 v[4:5], v[16:17], v[4:5]
	v_mov_b32_e32 v33, v114
	v_cvt_pk_bf16_f32 v3, v4, v5
	global_store_dwordx2 v[34:35], v[2:3], off offset:48
	v_mov_b32_e32 v34, v114
	v_mov_b32_e32 v35, v114
	v_mov_b32_e32 v2, v114
	v_mov_b32_e32 v3, v114
	v_mov_b32_e32 v4, v114
	v_mov_b32_e32 v5, v114
	v_mov_b32_e32 v15, v114
	v_mov_b32_e32 v16, v114
	v_mov_b32_e32 v17, v114
	s_cmp_ge_i32 s5, s4
	s_cbranch_scc0 .LBB0_817
